# K-loop: arrive at the closing barrier 1 MFMA early, priority 2 for the trailing MFMA
# speedup vs baseline: 1.0166x; 1.0081x over previous
; #define PG8_STAGE(bufoff, gbase, voff) do { _Pragma("unroll") for (int _i = 0; _i < 2; ++_i) \
;         __builtin_amdgcn_global_load_lds((const unsigned*)((const char*)(gbase) + (voff)[_i]), (PG8_LAS unsigned*)(lds + (bufoff) + ldsw + _i * 8192), 16, 0, 0); } while (0)
; #define PG8_LDA(dst, b, h) do { _Pragma("unroll") for (int m = 0; m < 4; ++m) _Pragma("unroll") for (int k = 0; k < 2; ++k) dst[m][k] = *(const PG8_LAS bf16x8*)(lds + PG8_SA(b, h) + aoff + m * 2048 + k * 1024); } while (0)
; #define PG8_LDB(dst, b, h) do { _Pragma("unroll") for (int n = 0; n < 2; ++n) _Pragma("unroll") for (int k = 0; k < 2; ++k) dst[n][k] = *(const PG8_LAS bf16x8*)(lds + PG8_SB(b, h) + boff + n * 2048 + k * 1024); } while (0)
; #define PG8_WAIT_V(n) asm volatile("s_waitcnt vmcnt(" #n ")" ::: "memory")
; #define PG8_WAIT_L(n) asm volatile("s_waitcnt lgkmcnt(" #n ")" ::: "memory")
; #define PG8_BAR __builtin_amdgcn_s_barrier()
; #define PG8_SCHED __builtin_amdgcn_sched_barrier(0)
; template <class Epi, class Sched, bool ALIGN_EPI = false, bool SP2 = false>
; __device__ __forceinline__ void gemm_phase(PG8_LAS unsigned char* lds, const Gemm g, const Sched& S, const Epi& E, const int wv  ) {
;     ...
;         for (int t = 0; t < nt; t += 2) {
;             const bool last = (t == nt - 2);
;             const char* a1 = cA + (size_t)(t + 1) * kstep;
;             const char* a2 = last ? nA : cA + (size_t)(t + 2) * kstep; const char* b2 = last ? nB : cB + (size_t)(t + 2) * kstep;
;             const char* a3 = a2 + kstep; const char* b3 = b2 + kstep;
;             if (last && has_next) S.a_ready(nxt);
;             if constexpr (SP2) {
;             PG8_LDB(B0, 0, 0); PG8_LDB(B1, 0, 1); PG8_SCHED; PG8_LDA(At, 0, 0); PG8_STAGE(PG8_SA(1, 1), a1 + hstepA, voffA);
;             PG8_WAIT_V(8); PG8_WAIT_L(0); PG8_BAR; PG8_MMA(0, 0, At, B0); PG8_MMA(0, 1, At, B1); PG8_BAR; PG8_SCHED;
;             PG8_LDA(At, 0, 1); PG8_STAGE(PG8_SB(0, 0), b2, voffB); PG8_STAGE(PG8_SB(0, 1), b2 + hstepB, voffB); PG8_STAGE(PG8_SA(0, 0), a2, voffA);
;             PG8_WAIT_V(8); PG8_WAIT_L(0); PG8_BAR; PG8_MMA(1, 0, At, B0); PG8_MMA(1, 1, At, B1); PG8_BAR; PG8_SCHED;
;             PG8_LDB(B0, 1, 0); PG8_LDB(B1, 1, 1); PG8_SCHED; PG8_LDA(At, 1, 0); PG8_STAGE(PG8_SA(0, 1), a2 + hstepA, voffA);
;             PG8_WAIT_V(8); PG8_WAIT_L(0); PG8_BAR; PG8_MMA(0, 0, At, B0); PG8_MMA(0, 1, At, B1); PG8_BAR; PG8_SCHED;
.LBB0_121:
	ds_read_b128 v[146:149], v152
	ds_read_b128 v[156:159], v152 offset:1024
	ds_read_b128 v[160:163], v152 offset:2048
	ds_read_b128 v[164:167], v152 offset:3072
	ds_read_b128 v[168:171], v153
	ds_read_b128 v[172:175], v153 offset:1024
	ds_read_b128 v[176:179], v153 offset:2048
	ds_read_b128 v[180:183], v153 offset:3072
	s_add_u32 s66, s64, 0xfff00080
	s_addc_u32 s67, s65, -1
	s_cmp_eq_u32 s96, 60
	s_cselect_b32 s69, s57, s67
	s_cselect_b32 s68, s92, s66
	s_cselect_b32 s67, s55, s95
	s_cselect_b32 s66, s93, s94
	v_lshl_add_u64 v[216:217], s[64:65], 0, v[138:139]
	s_add_i32 m0, s75, 0xc000
	ds_read_b128 v[184:187], v154
	ds_read_b128 v[188:191], v154 offset:1024
	ds_read_b128 v[192:195], v154 offset:2048
	ds_read_b128 v[196:199], v154 offset:3072
	ds_read_b128 v[200:203], v154 offset:4096
	ds_read_b128 v[204:207], v154 offset:5120
	ds_read_b128 v[208:211], v154 offset:6144
	ds_read_b128 v[212:215], v154 offset:7168
	global_load_lds_dwordx4 v[216:217], off
	v_lshl_add_u64 v[216:217], s[64:65], 0, v[140:141]
	s_add_i32 m0, s75, 0xe000
	s_nop 0
	global_load_lds_dwordx4 v[216:217], off
	s_waitcnt vmcnt(8)
	s_waitcnt lgkmcnt(0)
	s_barrier
	s_setprio 1
	s_waitcnt lgkmcnt(0)
	v_mfma_f32_16x16x32_bf16 v[76:79], v[146:149], v[184:187], v[76:79]
	v_mfma_f32_16x16x32_bf16 v[72:75], v[160:163], v[184:187], v[72:75]
	v_mfma_f32_16x16x32_bf16 v[68:71], v[146:149], v[192:195], v[68:71]
	v_mfma_f32_16x16x32_bf16 v[64:67], v[160:163], v[192:195], v[64:67]
	v_mfma_f32_16x16x32_bf16 v[56:59], v[146:149], v[200:203], v[56:59]
	v_mfma_f32_16x16x32_bf16 v[52:55], v[160:163], v[200:203], v[52:55]
	v_mfma_f32_16x16x32_bf16 v[44:47], v[146:149], v[208:211], v[44:47]
	v_mfma_f32_16x16x32_bf16 v[40:43], v[160:163], v[208:211], v[40:43]
	v_mfma_f32_16x16x32_bf16 v[76:79], v[156:159], v[188:191], v[76:79]
	v_mfma_f32_16x16x32_bf16 v[72:75], v[164:167], v[188:191], v[72:75]
	v_mfma_f32_16x16x32_bf16 v[68:71], v[156:159], v[196:199], v[68:71]
	v_mfma_f32_16x16x32_bf16 v[64:67], v[164:167], v[196:199], v[64:67]
	v_mfma_f32_16x16x32_bf16 v[56:59], v[156:159], v[204:207], v[56:59]
	v_mfma_f32_16x16x32_bf16 v[52:55], v[164:167], v[204:207], v[52:55]
	v_mfma_f32_16x16x32_bf16 v[44:47], v[156:159], v[212:215], v[44:47]
	v_mfma_f32_16x16x32_bf16 v[40:43], v[164:167], v[212:215], v[40:43]
	s_setprio 0
	s_setprio 1
	v_mfma_f32_16x16x32_bf16 v[124:127], v[168:171], v[184:187], v[124:127]
	v_mfma_f32_16x16x32_bf16 v[120:123], v[176:179], v[184:187], v[120:123]
	v_mfma_f32_16x16x32_bf16 v[116:119], v[168:171], v[192:195], v[116:119]
	v_mfma_f32_16x16x32_bf16 v[112:115], v[176:179], v[192:195], v[112:115]
	v_mfma_f32_16x16x32_bf16 v[108:111], v[168:171], v[200:203], v[108:111]
	v_mfma_f32_16x16x32_bf16 v[104:107], v[176:179], v[200:203], v[104:107]
	v_mfma_f32_16x16x32_bf16 v[100:103], v[168:171], v[208:211], v[100:103]
	v_mfma_f32_16x16x32_bf16 v[96:99], v[176:179], v[208:211], v[96:99]
	v_mfma_f32_16x16x32_bf16 v[124:127], v[172:175], v[188:191], v[124:127]
	v_mfma_f32_16x16x32_bf16 v[120:123], v[180:183], v[188:191], v[120:123]
	v_mfma_f32_16x16x32_bf16 v[116:119], v[172:175], v[196:199], v[116:119]
	v_mfma_f32_16x16x32_bf16 v[112:115], v[180:183], v[196:199], v[112:115]
	v_mfma_f32_16x16x32_bf16 v[108:111], v[172:175], v[204:207], v[108:111]
	v_mfma_f32_16x16x32_bf16 v[104:107], v[180:183], v[204:207], v[104:107]
	v_mfma_f32_16x16x32_bf16 v[100:103], v[172:175], v[212:215], v[100:103]
	s_setprio 2
	s_barrier
	v_mfma_f32_16x16x32_bf16 v[96:99], v[180:183], v[212:215], v[96:99]
	s_setprio 0
	s_add_i32 s97, s84, s74
	v_lshl_add_u64 v[216:217], s[66:67], 0, v[130:131]
	s_mov_b32 m0, s97
	ds_read_b128 v[184:187], v154 offset:16384
	ds_read_b128 v[188:191], v154 offset:17408
	ds_read_b128 v[192:195], v154 offset:18432
	ds_read_b128 v[196:199], v154 offset:19456
	ds_read_b128 v[200:203], v154 offset:20480
	ds_read_b128 v[204:207], v154 offset:21504
	ds_read_b128 v[208:211], v154 offset:22528
	ds_read_b128 v[212:215], v154 offset:23552
	global_load_lds_dwordx4 v[216:217], off
	s_add_i32 m0, s97, 0x2000
	s_add_u32 vcc_lo, s66, 0x100000
	v_lshl_add_u64 v[218:219], s[66:67], 0, v[134:135]
	s_addc_u32 vcc_hi, s67, 0
	s_add_i32 s97, s85, s74
	global_load_lds_dwordx4 v[218:219], off
	v_lshl_add_u64 v[220:221], vcc, 0, v[130:131]
	s_mov_b32 m0, s97
	v_lshl_add_u64 v[222:223], s[68:69], 0, v[132:133]
	global_load_lds_dwordx4 v[220:221], off
	v_lshl_add_u64 v[220:221], vcc, 0, v[134:135]
	s_add_i32 m0, s97, 0x2000
	s_nop 0
	global_load_lds_dwordx4 v[220:221], off
	v_lshl_add_u64 v[220:221], s[68:69], 0, v[128:129]
	s_mov_b32 m0, s75
	s_nop 0
	global_load_lds_dwordx4 v[220:221], off
	s_mov_b32 m0, s76
	s_nop 0
	global_load_lds_dwordx4 v[222:223], off
	s_waitcnt vmcnt(8)
	s_waitcnt lgkmcnt(0)
	s_barrier
; #define PG8_STAGE(bufoff, gbase, voff) do { _Pragma("unroll") for (int _i = 0; _i < 2; ++_i) \
;         __builtin_amdgcn_global_load_lds((const unsigned*)((const char*)(gbase) + (voff)[_i]), (PG8_LAS unsigned*)(lds + (bufoff) + ldsw + _i * 8192), 16, 0, 0); } while (0)
; #define PG8_LDA(dst, b, h) do { _Pragma("unroll") for (int m = 0; m < 4; ++m) _Pragma("unroll") for (int k = 0; k < 2; ++k) dst[m][k] = *(const PG8_LAS bf16x8*)(lds + PG8_SA(b, h) + aoff + m * 2048 + k * 1024); } while (0)
; #define PG8_LDB(dst, b, h) do { _Pragma("unroll") for (int n = 0; n < 2; ++n) _Pragma("unroll") for (int k = 0; k < 2; ++k) dst[n][k] = *(const PG8_LAS bf16x8*)(lds + PG8_SB(b, h) + boff + n * 2048 + k * 1024); } while (0)
; #define PG8_MMA(ai, bj, At, Bt) do { __builtin_amdgcn_s_setprio(1); _Pragma("unroll") for (int m = 0; m < 4; ++m) _Pragma("unroll") for (int n = 0; n < 2; ++n) _Pragma("unroll") for (int k = 0; k < 2; ++k) \
;         acc[ai][bj][m][n] = __builtin_amdgcn_mfma_f32_16x16x32_bf16(Bt[n][k], At[m][k], acc[ai][bj][m][n], 0, 0, 0); __builtin_amdgcn_s_setprio(0); } while (0)
; #define PG8_WAIT_V(n) asm volatile("s_waitcnt vmcnt(" #n ")" ::: "memory")
; #define PG8_WAIT_L(n) asm volatile("s_waitcnt lgkmcnt(" #n ")" ::: "memory")
; #define PG8_BAR __builtin_amdgcn_s_barrier()
; #define PG8_SCHED __builtin_amdgcn_sched_barrier(0)
; template <class Epi, class Sched, bool ALIGN_EPI = false, bool SP2 = false>
; __device__ __forceinline__ void gemm_phase(PG8_LAS unsigned char* lds, const Gemm g, const Sched& S, const Epi& E, const int wv  ) {
;     ...
;             PG8_WAIT_V(8); PG8_WAIT_L(0); PG8_BAR; PG8_MMA(1, 0, At, B0); PG8_MMA(1, 1, At, B1); PG8_BAR; PG8_SCHED;
;             PG8_LDB(B0, 1, 0); PG8_LDB(B1, 1, 1); PG8_SCHED; PG8_LDA(At, 1, 0); PG8_STAGE(PG8_SA(0, 1), a2 + hstepA, voffA);
;             PG8_WAIT_V(8); PG8_WAIT_L(0); PG8_BAR; PG8_MMA(0, 0, At, B0); PG8_MMA(0, 1, At, B1); PG8_BAR; PG8_SCHED;
	s_setprio 1
	s_waitcnt lgkmcnt(0)
	v_mfma_f32_16x16x32_bf16 v[28:31], v[146:149], v[184:187], v[28:31]
	v_mfma_f32_16x16x32_bf16 v[24:27], v[160:163], v[184:187], v[24:27]
	v_mfma_f32_16x16x32_bf16 v[20:23], v[146:149], v[192:195], v[20:23]
	v_mfma_f32_16x16x32_bf16 v[16:19], v[160:163], v[192:195], v[16:19]
	v_mfma_f32_16x16x32_bf16 v[12:15], v[146:149], v[200:203], v[12:15]
	v_mfma_f32_16x16x32_bf16 v[8:11], v[160:163], v[200:203], v[8:11]
	v_mfma_f32_16x16x32_bf16 v[4:7], v[146:149], v[208:211], v[4:7]
	v_mfma_f32_16x16x32_bf16 v[0:3], v[160:163], v[208:211], v[0:3]
	v_mfma_f32_16x16x32_bf16 v[28:31], v[156:159], v[188:191], v[28:31]
	v_mfma_f32_16x16x32_bf16 v[24:27], v[164:167], v[188:191], v[24:27]
	v_mfma_f32_16x16x32_bf16 v[20:23], v[156:159], v[196:199], v[20:23]
	v_mfma_f32_16x16x32_bf16 v[16:19], v[164:167], v[196:199], v[16:19]
	v_mfma_f32_16x16x32_bf16 v[12:15], v[156:159], v[204:207], v[12:15]
	v_mfma_f32_16x16x32_bf16 v[8:11], v[164:167], v[204:207], v[8:11]
	v_mfma_f32_16x16x32_bf16 v[4:7], v[156:159], v[212:215], v[4:7]
	v_mfma_f32_16x16x32_bf16 v[0:3], v[164:167], v[212:215], v[0:3]
	s_setprio 0
	s_setprio 1
	v_mfma_f32_16x16x32_bf16 v[92:95], v[168:171], v[184:187], v[92:95]
	v_mfma_f32_16x16x32_bf16 v[88:91], v[176:179], v[184:187], v[88:91]
	v_mfma_f32_16x16x32_bf16 v[84:87], v[168:171], v[192:195], v[84:87]
	v_mfma_f32_16x16x32_bf16 v[80:83], v[176:179], v[192:195], v[80:83]
	v_mfma_f32_16x16x32_bf16 v[60:63], v[168:171], v[200:203], v[60:63]
	v_mfma_f32_16x16x32_bf16 v[48:51], v[176:179], v[200:203], v[48:51]
	v_mfma_f32_16x16x32_bf16 v[36:39], v[168:171], v[208:211], v[36:39]
	v_mfma_f32_16x16x32_bf16 v[32:35], v[176:179], v[208:211], v[32:35]
	v_mfma_f32_16x16x32_bf16 v[92:95], v[172:175], v[188:191], v[92:95]
	v_mfma_f32_16x16x32_bf16 v[88:91], v[180:183], v[188:191], v[88:91]
	v_mfma_f32_16x16x32_bf16 v[84:87], v[172:175], v[196:199], v[84:87]
	v_mfma_f32_16x16x32_bf16 v[80:83], v[180:183], v[196:199], v[80:83]
	v_mfma_f32_16x16x32_bf16 v[60:63], v[172:175], v[204:207], v[60:63]
	v_mfma_f32_16x16x32_bf16 v[48:51], v[180:183], v[204:207], v[48:51]
	v_mfma_f32_16x16x32_bf16 v[36:39], v[172:175], v[212:215], v[36:39]
	s_setprio 2
	s_barrier
	v_mfma_f32_16x16x32_bf16 v[32:35], v[180:183], v[212:215], v[32:35]
	s_setprio 0
	s_add_i32 s97, 0, 0x18000
	v_add_u32_e32 v155, s97, v150
	s_add_i32 vcc_lo, 0, 0x1c000
	ds_read_b128 v[146:149], v155
	ds_read_b128 v[156:159], v155 offset:1024
	ds_read_b128 v[160:163], v155 offset:2048
	ds_read_b128 v[164:167], v155 offset:3072
	v_add_u32_e32 v155, vcc_lo, v150
	ds_read_b128 v[168:171], v155
	ds_read_b128 v[172:175], v155 offset:1024
	ds_read_b128 v[176:179], v155 offset:2048
	ds_read_b128 v[180:183], v155 offset:3072
	s_add_u32 s68, s68, 0x100000
	s_addc_u32 s69, s69, 0
	s_mov_b32 m0, s77
	v_lshl_add_u64 v[224:225], s[68:69], 0, v[128:129]
	ds_read_b128 v[184:187], v154 offset:32768
	ds_read_b128 v[188:191], v154 offset:33792
	ds_read_b128 v[192:195], v154 offset:34816
	ds_read_b128 v[196:199], v154 offset:35840
	ds_read_b128 v[200:203], v154 offset:36864
	ds_read_b128 v[204:207], v154 offset:37888
	ds_read_b128 v[208:211], v154 offset:38912
	ds_read_b128 v[212:215], v154 offset:39936
	global_load_lds_dwordx4 v[224:225], off
	v_lshl_add_u64 v[224:225], s[68:69], 0, v[132:133]
	s_mov_b32 m0, s78
	s_nop 0
	global_load_lds_dwordx4 v[224:225], off
	s_waitcnt vmcnt(8)
	s_waitcnt lgkmcnt(0)
	s_barrier
	s_setprio 1
	s_waitcnt lgkmcnt(0)
	v_mfma_f32_16x16x32_bf16 v[76:79], v[146:149], v[184:187], v[76:79]
	v_mfma_f32_16x16x32_bf16 v[72:75], v[160:163], v[184:187], v[72:75]
	v_mfma_f32_16x16x32_bf16 v[68:71], v[146:149], v[192:195], v[68:71]
	v_mfma_f32_16x16x32_bf16 v[64:67], v[160:163], v[192:195], v[64:67]
	v_mfma_f32_16x16x32_bf16 v[56:59], v[146:149], v[200:203], v[56:59]
	v_mfma_f32_16x16x32_bf16 v[52:55], v[160:163], v[200:203], v[52:55]
	v_mfma_f32_16x16x32_bf16 v[44:47], v[146:149], v[208:211], v[44:47]
	v_mfma_f32_16x16x32_bf16 v[40:43], v[160:163], v[208:211], v[40:43]
	v_mfma_f32_16x16x32_bf16 v[76:79], v[156:159], v[188:191], v[76:79]
	v_mfma_f32_16x16x32_bf16 v[72:75], v[164:167], v[188:191], v[72:75]
	v_mfma_f32_16x16x32_bf16 v[68:71], v[156:159], v[196:199], v[68:71]
	v_mfma_f32_16x16x32_bf16 v[64:67], v[164:167], v[196:199], v[64:67]
	v_mfma_f32_16x16x32_bf16 v[56:59], v[156:159], v[204:207], v[56:59]
	v_mfma_f32_16x16x32_bf16 v[52:55], v[164:167], v[204:207], v[52:55]
	v_mfma_f32_16x16x32_bf16 v[44:47], v[156:159], v[212:215], v[44:47]
	v_mfma_f32_16x16x32_bf16 v[40:43], v[164:167], v[212:215], v[40:43]
	s_setprio 0
	s_setprio 1
	v_mfma_f32_16x16x32_bf16 v[124:127], v[168:171], v[184:187], v[124:127]
	v_mfma_f32_16x16x32_bf16 v[120:123], v[176:179], v[184:187], v[120:123]
	v_mfma_f32_16x16x32_bf16 v[116:119], v[168:171], v[192:195], v[116:119]
	v_mfma_f32_16x16x32_bf16 v[112:115], v[176:179], v[192:195], v[112:115]
	v_mfma_f32_16x16x32_bf16 v[108:111], v[168:171], v[200:203], v[108:111]
	v_mfma_f32_16x16x32_bf16 v[104:107], v[176:179], v[200:203], v[104:107]
	v_mfma_f32_16x16x32_bf16 v[100:103], v[168:171], v[208:211], v[100:103]
	v_mfma_f32_16x16x32_bf16 v[96:99], v[176:179], v[208:211], v[96:99]
	v_mfma_f32_16x16x32_bf16 v[124:127], v[172:175], v[188:191], v[124:127]
	v_mfma_f32_16x16x32_bf16 v[120:123], v[180:183], v[188:191], v[120:123]
	v_mfma_f32_16x16x32_bf16 v[116:119], v[172:175], v[196:199], v[116:119]
	v_mfma_f32_16x16x32_bf16 v[112:115], v[180:183], v[196:199], v[112:115]
	v_mfma_f32_16x16x32_bf16 v[108:111], v[172:175], v[204:207], v[108:111]
	v_mfma_f32_16x16x32_bf16 v[104:107], v[180:183], v[204:207], v[104:107]
	v_mfma_f32_16x16x32_bf16 v[100:103], v[172:175], v[212:215], v[100:103]
	s_setprio 2
	s_barrier
; #define PG8_STAGE(bufoff, gbase, voff) do { _Pragma("unroll") for (int _i = 0; _i < 2; ++_i) \
;         __builtin_amdgcn_global_load_lds((const unsigned*)((const char*)(gbase) + (voff)[_i]), (PG8_LAS unsigned*)(lds + (bufoff) + ldsw + _i * 8192), 16, 0, 0); } while (0)
; #define PG8_LDA(dst, b, h) do { _Pragma("unroll") for (int m = 0; m < 4; ++m) _Pragma("unroll") for (int k = 0; k < 2; ++k) dst[m][k] = *(const PG8_LAS bf16x8*)(lds + PG8_SA(b, h) + aoff + m * 2048 + k * 1024); } while (0)
; #define PG8_MMA(ai, bj, At, Bt) do { __builtin_amdgcn_s_setprio(1); _Pragma("unroll") for (int m = 0; m < 4; ++m) _Pragma("unroll") for (int n = 0; n < 2; ++n) _Pragma("unroll") for (int k = 0; k < 2; ++k) \
;         acc[ai][bj][m][n] = __builtin_amdgcn_mfma_f32_16x16x32_bf16(Bt[n][k], At[m][k], acc[ai][bj][m][n], 0, 0, 0); __builtin_amdgcn_s_setprio(0); } while (0)
; #define PG8_WAIT_V(n) asm volatile("s_waitcnt vmcnt(" #n ")" ::: "memory")
; #define PG8_WAIT_L(n) asm volatile("s_waitcnt lgkmcnt(" #n ")" ::: "memory")
; #define PG8_BAR __builtin_amdgcn_s_barrier()
; #define PG8_SCHED __builtin_amdgcn_sched_barrier(0)
; template <class Epi, class Sched, bool ALIGN_EPI = false, bool SP2 = false>
; __device__ __forceinline__ void gemm_phase(PG8_LAS unsigned char* lds, const Gemm g, const Sched& S, const Epi& E, const int wv  ) {
;     ...
;             PG8_WAIT_V(8); PG8_WAIT_L(0); PG8_BAR; PG8_MMA(0, 0, At, B0); PG8_MMA(0, 1, At, B1); PG8_BAR; PG8_SCHED;
;             PG8_LDA(At, 1, 1); PG8_STAGE(PG8_SB(1, 0), b3, voffB); PG8_STAGE(PG8_SB(1, 1), b3 + hstepB, voffB); PG8_STAGE(PG8_SA(1, 0), a3, voffA);
;             PG8_WAIT_V(8); PG8_WAIT_L(0); PG8_BAR; PG8_MMA(1, 0, At, B0); PG8_MMA(1, 1, At, B1); PG8_BAR; PG8_SCHED;
;     ...
;         if constexpr (ALIGN_EPI) { if (wr == 0) PG8_BAR; }
	v_mfma_f32_16x16x32_bf16 v[96:99], v[180:183], v[212:215], v[96:99]
	s_setprio 0
	s_add_i32 s68, s97, s74
	v_lshl_add_u64 v[216:217], v[216:217], 0, s[18:19]
	s_mov_b32 m0, s68
	ds_read_b128 v[184:187], v154 offset:49152
	ds_read_b128 v[188:191], v154 offset:50176
	ds_read_b128 v[192:195], v154 offset:51200
	ds_read_b128 v[196:199], v154 offset:52224
	ds_read_b128 v[200:203], v154 offset:53248
	ds_read_b128 v[204:207], v154 offset:54272
	ds_read_b128 v[208:211], v154 offset:55296
	ds_read_b128 v[212:215], v154 offset:56320
	global_load_lds_dwordx4 v[216:217], off
	s_add_i32 m0, s68, 0x2000
	s_add_u32 s66, s66, 0x100080
	v_lshl_add_u64 v[216:217], v[218:219], 0, s[18:19]
	s_addc_u32 s67, s67, 0
	s_add_i32 s68, vcc_lo, s74
	global_load_lds_dwordx4 v[216:217], off
	v_lshl_add_u64 v[216:217], s[66:67], 0, v[130:131]
	s_mov_b32 m0, s68
	s_nop 0
	global_load_lds_dwordx4 v[216:217], off
	v_lshl_add_u64 v[216:217], s[66:67], 0, v[134:135]
	s_add_i32 m0, s68, 0x2000
	s_nop 0
	global_load_lds_dwordx4 v[216:217], off
	v_lshl_add_u64 v[216:217], v[220:221], 0, s[18:19]
	s_mov_b32 m0, s81
	s_nop 0
	global_load_lds_dwordx4 v[216:217], off
	v_lshl_add_u64 v[216:217], v[222:223], 0, s[18:19]
	s_mov_b32 m0, s82
	s_nop 0
	global_load_lds_dwordx4 v[216:217], off
	s_waitcnt vmcnt(8)
	s_waitcnt lgkmcnt(0)
	s_barrier
	s_setprio 1
	s_waitcnt lgkmcnt(0)
	v_mfma_f32_16x16x32_bf16 v[28:31], v[146:149], v[184:187], v[28:31]
	v_mfma_f32_16x16x32_bf16 v[24:27], v[160:163], v[184:187], v[24:27]
	v_mfma_f32_16x16x32_bf16 v[20:23], v[146:149], v[192:195], v[20:23]
	v_mfma_f32_16x16x32_bf16 v[16:19], v[160:163], v[192:195], v[16:19]
	v_mfma_f32_16x16x32_bf16 v[12:15], v[146:149], v[200:203], v[12:15]
	v_mfma_f32_16x16x32_bf16 v[8:11], v[160:163], v[200:203], v[8:11]
	v_mfma_f32_16x16x32_bf16 v[4:7], v[146:149], v[208:211], v[4:7]
	v_mfma_f32_16x16x32_bf16 v[0:3], v[160:163], v[208:211], v[0:3]
	v_mfma_f32_16x16x32_bf16 v[28:31], v[156:159], v[188:191], v[28:31]
	v_mfma_f32_16x16x32_bf16 v[24:27], v[164:167], v[188:191], v[24:27]
	v_mfma_f32_16x16x32_bf16 v[20:23], v[156:159], v[196:199], v[20:23]
	v_mfma_f32_16x16x32_bf16 v[16:19], v[164:167], v[196:199], v[16:19]
	v_mfma_f32_16x16x32_bf16 v[12:15], v[156:159], v[204:207], v[12:15]
	v_mfma_f32_16x16x32_bf16 v[8:11], v[164:167], v[204:207], v[8:11]
	v_mfma_f32_16x16x32_bf16 v[4:7], v[156:159], v[212:215], v[4:7]
	v_mfma_f32_16x16x32_bf16 v[0:3], v[164:167], v[212:215], v[0:3]
	s_setprio 0
	s_setprio 1
	v_mfma_f32_16x16x32_bf16 v[92:95], v[168:171], v[184:187], v[92:95]
	v_mfma_f32_16x16x32_bf16 v[88:91], v[176:179], v[184:187], v[88:91]
	v_mfma_f32_16x16x32_bf16 v[84:87], v[168:171], v[192:195], v[84:87]
	v_mfma_f32_16x16x32_bf16 v[80:83], v[176:179], v[192:195], v[80:83]
	v_mfma_f32_16x16x32_bf16 v[60:63], v[168:171], v[200:203], v[60:63]
	v_mfma_f32_16x16x32_bf16 v[48:51], v[176:179], v[200:203], v[48:51]
	v_mfma_f32_16x16x32_bf16 v[36:39], v[168:171], v[208:211], v[36:39]
	v_mfma_f32_16x16x32_bf16 v[32:35], v[176:179], v[208:211], v[32:35]
	v_mfma_f32_16x16x32_bf16 v[92:95], v[172:175], v[188:191], v[92:95]
	v_mfma_f32_16x16x32_bf16 v[88:91], v[180:183], v[188:191], v[88:91]
	v_mfma_f32_16x16x32_bf16 v[84:87], v[172:175], v[196:199], v[84:87]
	v_mfma_f32_16x16x32_bf16 v[80:83], v[180:183], v[196:199], v[80:83]
	v_mfma_f32_16x16x32_bf16 v[60:63], v[172:175], v[204:207], v[60:63]
	v_mfma_f32_16x16x32_bf16 v[48:51], v[180:183], v[204:207], v[48:51]
	v_mfma_f32_16x16x32_bf16 v[36:39], v[172:175], v[212:215], v[36:39]
	s_setprio 2
	s_barrier
	v_mfma_f32_16x16x32_bf16 v[32:35], v[180:183], v[212:215], v[32:35]
	s_setprio 0
	s_add_i32 s96, s96, 2
	s_add_u32 s64, s64, 0x100
	s_addc_u32 s65, s65, 0
	s_add_u32 s94, s94, 0x100
	s_addc_u32 s95, s95, 0
	s_cmp_gt_u32 s96, 61
	s_cbranch_scc0 .LBB0_121
	s_and_b64 vcc, exec, s[20:21]
	s_cbranch_vccz .LBB0_124
	s_barrier

; #define PG8_STAGE(bufoff, gbase, voff) do { _Pragma("unroll") for (int _i = 0; _i < 2; ++_i) \
;         __builtin_amdgcn_global_load_lds((const unsigned*)((const char*)(gbase) + (voff)[_i]), (PG8_LAS unsigned*)(lds + (bufoff) + ldsw + _i * 8192), 16, 0, 0); } while (0)
; #define PG8_LDA(dst, b, h) do { _Pragma("unroll") for (int m = 0; m < 4; ++m) _Pragma("unroll") for (int k = 0; k < 2; ++k) dst[m][k] = *(const PG8_LAS bf16x8*)(lds + PG8_SA(b, h) + aoff + m * 2048 + k * 1024); } while (0)
; #define PG8_LDB(dst, b, h) do { _Pragma("unroll") for (int n = 0; n < 2; ++n) _Pragma("unroll") for (int k = 0; k < 2; ++k) dst[n][k] = *(const PG8_LAS bf16x8*)(lds + PG8_SB(b, h) + boff + n * 2048 + k * 1024); } while (0)
; #define PG8_MMA(ai, bj, At, Bt) do { __builtin_amdgcn_s_setprio(1); _Pragma("unroll") for (int m = 0; m < 4; ++m) _Pragma("unroll") for (int n = 0; n < 2; ++n) _Pragma("unroll") for (int k = 0; k < 2; ++k) \
;         acc[ai][bj][m][n] = __builtin_amdgcn_mfma_f32_16x16x32_bf16(Bt[n][k], At[m][k], acc[ai][bj][m][n], 0, 0, 0); __builtin_amdgcn_s_setprio(0); } while (0)
; #define PG8_WAIT_V(n) asm volatile("s_waitcnt vmcnt(" #n ")" ::: "memory")
; #define PG8_WAIT_L(n) asm volatile("s_waitcnt lgkmcnt(" #n ")" ::: "memory")
; #define PG8_BAR __builtin_amdgcn_s_barrier()
; template <class Epi, class Sched, bool ALIGN_EPI = false, bool SP2 = false>
; __device__ __forceinline__ void gemm_phase(PG8_LAS unsigned char* lds, const Gemm g, const Sched& S, const Epi& E, const int wv  ) {
;     ...
;         for (int t = 0; t < nt; t += 2) {
;             const bool last = (t == nt - 2);
;             const char* a1 = cA + (size_t)(t + 1) * kstep;
;             const char* a2 = last ? nA : cA + (size_t)(t + 2) * kstep; const char* b2 = last ? nB : cB + (size_t)(t + 2) * kstep;
;             const char* a3 = a2 + kstep; const char* b3 = b2 + kstep;
;             if (last && has_next) S.a_ready(nxt);
;             if constexpr (SP2) {
;             PG8_LDB(B0, 0, 0); PG8_LDB(B1, 0, 1); PG8_SCHED; PG8_LDA(At, 0, 0); PG8_STAGE(PG8_SA(1, 1), a1 + hstepA, voffA);
;             PG8_WAIT_V(8); PG8_WAIT_L(0); PG8_BAR; PG8_MMA(0, 0, At, B0); PG8_MMA(0, 1, At, B1); PG8_BAR; PG8_SCHED;
;             PG8_LDA(At, 0, 1); PG8_STAGE(PG8_SB(0, 0), b2, voffB); PG8_STAGE(PG8_SB(0, 1), b2 + hstepB, voffB); PG8_STAGE(PG8_SA(0, 0), a2, voffA);
.LBB0_706:
	ds_read_b128 v[146:149], v152
	ds_read_b128 v[156:159], v152 offset:1024
	ds_read_b128 v[160:163], v152 offset:2048
	ds_read_b128 v[164:167], v152 offset:3072
	ds_read_b128 v[168:171], v153
	ds_read_b128 v[172:175], v153 offset:1024
	ds_read_b128 v[176:179], v153 offset:2048
	ds_read_b128 v[180:183], v153 offset:3072
	s_add_u32 s60, s58, 0xfff00080
	s_addc_u32 s61, s59, -1
	s_cmp_eq_u32 s87, 60
	s_cselect_b32 s63, s51, s61
	s_cselect_b32 s62, s83, s60
	s_cselect_b32 s61, s49, s86
	s_cselect_b32 s60, s84, s85
	v_lshl_add_u64 v[216:217], s[58:59], 0, v[138:139]
	s_add_i32 m0, s68, 0xc000
	ds_read_b128 v[184:187], v154
	ds_read_b128 v[188:191], v154 offset:1024
	ds_read_b128 v[192:195], v154 offset:2048
	ds_read_b128 v[196:199], v154 offset:3072
	ds_read_b128 v[200:203], v154 offset:4096
	ds_read_b128 v[204:207], v154 offset:5120
	ds_read_b128 v[208:211], v154 offset:6144
	ds_read_b128 v[212:215], v154 offset:7168
	global_load_lds_dwordx4 v[216:217], off
	v_lshl_add_u64 v[216:217], s[58:59], 0, v[140:141]
	s_add_i32 m0, s68, 0xe000
	s_nop 0
	global_load_lds_dwordx4 v[216:217], off
	s_waitcnt vmcnt(8)
	s_waitcnt lgkmcnt(0)
	s_barrier
	s_setprio 1
	s_waitcnt lgkmcnt(0)
	v_mfma_f32_16x16x32_bf16 v[76:79], v[146:149], v[184:187], v[76:79]
	v_mfma_f32_16x16x32_bf16 v[72:75], v[160:163], v[184:187], v[72:75]
	v_mfma_f32_16x16x32_bf16 v[68:71], v[146:149], v[192:195], v[68:71]
	v_mfma_f32_16x16x32_bf16 v[64:67], v[160:163], v[192:195], v[64:67]
	v_mfma_f32_16x16x32_bf16 v[56:59], v[146:149], v[200:203], v[56:59]
	v_mfma_f32_16x16x32_bf16 v[52:55], v[160:163], v[200:203], v[52:55]
	v_mfma_f32_16x16x32_bf16 v[44:47], v[146:149], v[208:211], v[44:47]
	v_mfma_f32_16x16x32_bf16 v[40:43], v[160:163], v[208:211], v[40:43]
	v_mfma_f32_16x16x32_bf16 v[76:79], v[156:159], v[188:191], v[76:79]
	v_mfma_f32_16x16x32_bf16 v[72:75], v[164:167], v[188:191], v[72:75]
	v_mfma_f32_16x16x32_bf16 v[68:71], v[156:159], v[196:199], v[68:71]
	v_mfma_f32_16x16x32_bf16 v[64:67], v[164:167], v[196:199], v[64:67]
	v_mfma_f32_16x16x32_bf16 v[56:59], v[156:159], v[204:207], v[56:59]
	v_mfma_f32_16x16x32_bf16 v[52:55], v[164:167], v[204:207], v[52:55]
	v_mfma_f32_16x16x32_bf16 v[44:47], v[156:159], v[212:215], v[44:47]
	v_mfma_f32_16x16x32_bf16 v[40:43], v[164:167], v[212:215], v[40:43]
	s_setprio 0
	s_setprio 1
	v_mfma_f32_16x16x32_bf16 v[124:127], v[168:171], v[184:187], v[124:127]
	v_mfma_f32_16x16x32_bf16 v[120:123], v[176:179], v[184:187], v[120:123]
	v_mfma_f32_16x16x32_bf16 v[116:119], v[168:171], v[192:195], v[116:119]
	v_mfma_f32_16x16x32_bf16 v[112:115], v[176:179], v[192:195], v[112:115]
	v_mfma_f32_16x16x32_bf16 v[108:111], v[168:171], v[200:203], v[108:111]
	v_mfma_f32_16x16x32_bf16 v[104:107], v[176:179], v[200:203], v[104:107]
	v_mfma_f32_16x16x32_bf16 v[100:103], v[168:171], v[208:211], v[100:103]
	v_mfma_f32_16x16x32_bf16 v[96:99], v[176:179], v[208:211], v[96:99]
	v_mfma_f32_16x16x32_bf16 v[124:127], v[172:175], v[188:191], v[124:127]
	v_mfma_f32_16x16x32_bf16 v[120:123], v[180:183], v[188:191], v[120:123]
	v_mfma_f32_16x16x32_bf16 v[116:119], v[172:175], v[196:199], v[116:119]
	v_mfma_f32_16x16x32_bf16 v[112:115], v[180:183], v[196:199], v[112:115]
	v_mfma_f32_16x16x32_bf16 v[108:111], v[172:175], v[204:207], v[108:111]
	v_mfma_f32_16x16x32_bf16 v[104:107], v[180:183], v[204:207], v[104:107]
	v_mfma_f32_16x16x32_bf16 v[100:103], v[172:175], v[212:215], v[100:103]
	s_setprio 2
	s_barrier
	v_mfma_f32_16x16x32_bf16 v[96:99], v[180:183], v[212:215], v[96:99]
	s_setprio 0
	s_add_i32 s90, s77, s67
	v_lshl_add_u64 v[216:217], s[60:61], 0, v[130:131]
	s_mov_b32 m0, s90
	ds_read_b128 v[184:187], v154 offset:16384
	ds_read_b128 v[188:191], v154 offset:17408
	ds_read_b128 v[192:195], v154 offset:18432
	ds_read_b128 v[196:199], v154 offset:19456
	ds_read_b128 v[200:203], v154 offset:20480
	ds_read_b128 v[204:207], v154 offset:21504
	ds_read_b128 v[208:211], v154 offset:22528
	ds_read_b128 v[212:215], v154 offset:23552
	global_load_lds_dwordx4 v[216:217], off
	s_add_i32 m0, s90, 0x2000
	s_add_u32 s90, s60, 0x100000
	v_lshl_add_u64 v[218:219], s[60:61], 0, v[134:135]
	s_addc_u32 s91, s61, 0
	s_add_i32 s92, s78, s67
	global_load_lds_dwordx4 v[218:219], off
	v_lshl_add_u64 v[220:221], s[90:91], 0, v[130:131]
	s_mov_b32 m0, s92
	v_lshl_add_u64 v[222:223], s[62:63], 0, v[132:133]
	global_load_lds_dwordx4 v[220:221], off
	v_lshl_add_u64 v[220:221], s[90:91], 0, v[134:135]
	s_add_i32 m0, s92, 0x2000
	s_nop 0
	global_load_lds_dwordx4 v[220:221], off
	v_lshl_add_u64 v[220:221], s[62:63], 0, v[128:129]
	s_mov_b32 m0, s68
	s_nop 0
	global_load_lds_dwordx4 v[220:221], off
	s_mov_b32 m0, s69
	s_nop 0
	global_load_lds_dwordx4 v[222:223], off
	s_waitcnt vmcnt(8)
	s_waitcnt lgkmcnt(0)
	s_barrier
; #define PG8_STAGE(bufoff, gbase, voff) do { _Pragma("unroll") for (int _i = 0; _i < 2; ++_i) \
;         __builtin_amdgcn_global_load_lds((const unsigned*)((const char*)(gbase) + (voff)[_i]), (PG8_LAS unsigned*)(lds + (bufoff) + ldsw + _i * 8192), 16, 0, 0); } while (0)
; #define PG8_LDA(dst, b, h) do { _Pragma("unroll") for (int m = 0; m < 4; ++m) _Pragma("unroll") for (int k = 0; k < 2; ++k) dst[m][k] = *(const PG8_LAS bf16x8*)(lds + PG8_SA(b, h) + aoff + m * 2048 + k * 1024); } while (0)
; #define PG8_LDB(dst, b, h) do { _Pragma("unroll") for (int n = 0; n < 2; ++n) _Pragma("unroll") for (int k = 0; k < 2; ++k) dst[n][k] = *(const PG8_LAS bf16x8*)(lds + PG8_SB(b, h) + boff + n * 2048 + k * 1024); } while (0)
; #define PG8_MMA(ai, bj, At, Bt) do { __builtin_amdgcn_s_setprio(1); _Pragma("unroll") for (int m = 0; m < 4; ++m) _Pragma("unroll") for (int n = 0; n < 2; ++n) _Pragma("unroll") for (int k = 0; k < 2; ++k) \
;         acc[ai][bj][m][n] = __builtin_amdgcn_mfma_f32_16x16x32_bf16(Bt[n][k], At[m][k], acc[ai][bj][m][n], 0, 0, 0); __builtin_amdgcn_s_setprio(0); } while (0)
; #define PG8_WAIT_V(n) asm volatile("s_waitcnt vmcnt(" #n ")" ::: "memory")
; #define PG8_WAIT_L(n) asm volatile("s_waitcnt lgkmcnt(" #n ")" ::: "memory")
; #define PG8_BAR __builtin_amdgcn_s_barrier()
; #define PG8_SCHED __builtin_amdgcn_sched_barrier(0)
; template <class Epi, class Sched, bool ALIGN_EPI = false, bool SP2 = false>
; __device__ __forceinline__ void gemm_phase(PG8_LAS unsigned char* lds, const Gemm g, const Sched& S, const Epi& E, const int wv  ) {
;     ...
;             PG8_WAIT_V(8); PG8_WAIT_L(0); PG8_BAR; PG8_MMA(1, 0, At, B0); PG8_MMA(1, 1, At, B1); PG8_BAR; PG8_SCHED;
;             PG8_LDB(B0, 1, 0); PG8_LDB(B1, 1, 1); PG8_SCHED; PG8_LDA(At, 1, 0); PG8_STAGE(PG8_SA(0, 1), a2 + hstepA, voffA);
;             PG8_WAIT_V(8); PG8_WAIT_L(0); PG8_BAR; PG8_MMA(0, 0, At, B0); PG8_MMA(0, 1, At, B1); PG8_BAR; PG8_SCHED;
	s_setprio 1
	s_waitcnt lgkmcnt(0)
	v_mfma_f32_16x16x32_bf16 v[28:31], v[146:149], v[184:187], v[28:31]
	v_mfma_f32_16x16x32_bf16 v[24:27], v[160:163], v[184:187], v[24:27]
	v_mfma_f32_16x16x32_bf16 v[20:23], v[146:149], v[192:195], v[20:23]
	v_mfma_f32_16x16x32_bf16 v[16:19], v[160:163], v[192:195], v[16:19]
	v_mfma_f32_16x16x32_bf16 v[12:15], v[146:149], v[200:203], v[12:15]
	v_mfma_f32_16x16x32_bf16 v[8:11], v[160:163], v[200:203], v[8:11]
	v_mfma_f32_16x16x32_bf16 v[4:7], v[146:149], v[208:211], v[4:7]
	v_mfma_f32_16x16x32_bf16 v[0:3], v[160:163], v[208:211], v[0:3]
	v_mfma_f32_16x16x32_bf16 v[28:31], v[156:159], v[188:191], v[28:31]
	v_mfma_f32_16x16x32_bf16 v[24:27], v[164:167], v[188:191], v[24:27]
	v_mfma_f32_16x16x32_bf16 v[20:23], v[156:159], v[196:199], v[20:23]
	v_mfma_f32_16x16x32_bf16 v[16:19], v[164:167], v[196:199], v[16:19]
	v_mfma_f32_16x16x32_bf16 v[12:15], v[156:159], v[204:207], v[12:15]
	v_mfma_f32_16x16x32_bf16 v[8:11], v[164:167], v[204:207], v[8:11]
	v_mfma_f32_16x16x32_bf16 v[4:7], v[156:159], v[212:215], v[4:7]
	v_mfma_f32_16x16x32_bf16 v[0:3], v[164:167], v[212:215], v[0:3]
	s_setprio 0
	s_setprio 1
	v_mfma_f32_16x16x32_bf16 v[92:95], v[168:171], v[184:187], v[92:95]
	v_mfma_f32_16x16x32_bf16 v[88:91], v[176:179], v[184:187], v[88:91]
	v_mfma_f32_16x16x32_bf16 v[84:87], v[168:171], v[192:195], v[84:87]
	v_mfma_f32_16x16x32_bf16 v[80:83], v[176:179], v[192:195], v[80:83]
	v_mfma_f32_16x16x32_bf16 v[60:63], v[168:171], v[200:203], v[60:63]
	v_mfma_f32_16x16x32_bf16 v[48:51], v[176:179], v[200:203], v[48:51]
	v_mfma_f32_16x16x32_bf16 v[36:39], v[168:171], v[208:211], v[36:39]
	v_mfma_f32_16x16x32_bf16 v[32:35], v[176:179], v[208:211], v[32:35]
	v_mfma_f32_16x16x32_bf16 v[92:95], v[172:175], v[188:191], v[92:95]
	v_mfma_f32_16x16x32_bf16 v[88:91], v[180:183], v[188:191], v[88:91]
	v_mfma_f32_16x16x32_bf16 v[84:87], v[172:175], v[196:199], v[84:87]
	v_mfma_f32_16x16x32_bf16 v[80:83], v[180:183], v[196:199], v[80:83]
	v_mfma_f32_16x16x32_bf16 v[60:63], v[172:175], v[204:207], v[60:63]
	v_mfma_f32_16x16x32_bf16 v[48:51], v[180:183], v[204:207], v[48:51]
	v_mfma_f32_16x16x32_bf16 v[36:39], v[172:175], v[212:215], v[36:39]
	s_setprio 2
	s_barrier
	v_mfma_f32_16x16x32_bf16 v[32:35], v[180:183], v[212:215], v[32:35]
	s_setprio 0
	s_add_i32 s90, 0, 0x18000
	v_add_u32_e32 v155, s90, v150
	s_add_i32 s91, 0, 0x1c000
	ds_read_b128 v[146:149], v155
	ds_read_b128 v[156:159], v155 offset:1024
	ds_read_b128 v[160:163], v155 offset:2048
	ds_read_b128 v[164:167], v155 offset:3072
	v_add_u32_e32 v155, s91, v150
	ds_read_b128 v[168:171], v155
	ds_read_b128 v[172:175], v155 offset:1024
	ds_read_b128 v[176:179], v155 offset:2048
	ds_read_b128 v[180:183], v155 offset:3072
	s_add_u32 s62, s62, 0x100000
	s_addc_u32 s63, s63, 0
	s_mov_b32 m0, s70
	v_lshl_add_u64 v[224:225], s[62:63], 0, v[128:129]
	ds_read_b128 v[184:187], v154 offset:32768
	ds_read_b128 v[188:191], v154 offset:33792
	ds_read_b128 v[192:195], v154 offset:34816
	ds_read_b128 v[196:199], v154 offset:35840
	ds_read_b128 v[200:203], v154 offset:36864
	ds_read_b128 v[204:207], v154 offset:37888
	ds_read_b128 v[208:211], v154 offset:38912
	ds_read_b128 v[212:215], v154 offset:39936
	global_load_lds_dwordx4 v[224:225], off
	v_lshl_add_u64 v[224:225], s[62:63], 0, v[132:133]
	s_mov_b32 m0, s71
	s_nop 0
	global_load_lds_dwordx4 v[224:225], off
	s_waitcnt vmcnt(8)
	s_waitcnt lgkmcnt(0)
	s_barrier
	s_setprio 1
	s_waitcnt lgkmcnt(0)
	v_mfma_f32_16x16x32_bf16 v[76:79], v[146:149], v[184:187], v[76:79]
	v_mfma_f32_16x16x32_bf16 v[72:75], v[160:163], v[184:187], v[72:75]
	v_mfma_f32_16x16x32_bf16 v[68:71], v[146:149], v[192:195], v[68:71]
	v_mfma_f32_16x16x32_bf16 v[64:67], v[160:163], v[192:195], v[64:67]
	v_mfma_f32_16x16x32_bf16 v[56:59], v[146:149], v[200:203], v[56:59]
	v_mfma_f32_16x16x32_bf16 v[52:55], v[160:163], v[200:203], v[52:55]
	v_mfma_f32_16x16x32_bf16 v[44:47], v[146:149], v[208:211], v[44:47]
	v_mfma_f32_16x16x32_bf16 v[40:43], v[160:163], v[208:211], v[40:43]
	v_mfma_f32_16x16x32_bf16 v[76:79], v[156:159], v[188:191], v[76:79]
	v_mfma_f32_16x16x32_bf16 v[72:75], v[164:167], v[188:191], v[72:75]
	v_mfma_f32_16x16x32_bf16 v[68:71], v[156:159], v[196:199], v[68:71]
	v_mfma_f32_16x16x32_bf16 v[64:67], v[164:167], v[196:199], v[64:67]
	v_mfma_f32_16x16x32_bf16 v[56:59], v[156:159], v[204:207], v[56:59]
	v_mfma_f32_16x16x32_bf16 v[52:55], v[164:167], v[204:207], v[52:55]
	v_mfma_f32_16x16x32_bf16 v[44:47], v[156:159], v[212:215], v[44:47]
	v_mfma_f32_16x16x32_bf16 v[40:43], v[164:167], v[212:215], v[40:43]
	s_setprio 0
	s_setprio 1
	v_mfma_f32_16x16x32_bf16 v[124:127], v[168:171], v[184:187], v[124:127]
	v_mfma_f32_16x16x32_bf16 v[120:123], v[176:179], v[184:187], v[120:123]
	v_mfma_f32_16x16x32_bf16 v[116:119], v[168:171], v[192:195], v[116:119]
	v_mfma_f32_16x16x32_bf16 v[112:115], v[176:179], v[192:195], v[112:115]
	v_mfma_f32_16x16x32_bf16 v[108:111], v[168:171], v[200:203], v[108:111]
	v_mfma_f32_16x16x32_bf16 v[104:107], v[176:179], v[200:203], v[104:107]
	v_mfma_f32_16x16x32_bf16 v[100:103], v[168:171], v[208:211], v[100:103]
	v_mfma_f32_16x16x32_bf16 v[96:99], v[176:179], v[208:211], v[96:99]
	v_mfma_f32_16x16x32_bf16 v[124:127], v[172:175], v[188:191], v[124:127]
	v_mfma_f32_16x16x32_bf16 v[120:123], v[180:183], v[188:191], v[120:123]
	v_mfma_f32_16x16x32_bf16 v[116:119], v[172:175], v[196:199], v[116:119]
	v_mfma_f32_16x16x32_bf16 v[112:115], v[180:183], v[196:199], v[112:115]
	v_mfma_f32_16x16x32_bf16 v[108:111], v[172:175], v[204:207], v[108:111]
	v_mfma_f32_16x16x32_bf16 v[104:107], v[180:183], v[204:207], v[104:107]
	v_mfma_f32_16x16x32_bf16 v[100:103], v[172:175], v[212:215], v[100:103]
	s_setprio 2
	s_barrier
; #define PG8_STAGE(bufoff, gbase, voff) do { _Pragma("unroll") for (int _i = 0; _i < 2; ++_i) \
;         __builtin_amdgcn_global_load_lds((const unsigned*)((const char*)(gbase) + (voff)[_i]), (PG8_LAS unsigned*)(lds + (bufoff) + ldsw + _i * 8192), 16, 0, 0); } while (0)
; #define PG8_LDA(dst, b, h) do { _Pragma("unroll") for (int m = 0; m < 4; ++m) _Pragma("unroll") for (int k = 0; k < 2; ++k) dst[m][k] = *(const PG8_LAS bf16x8*)(lds + PG8_SA(b, h) + aoff + m * 2048 + k * 1024); } while (0)
; #define PG8_MMA(ai, bj, At, Bt) do { __builtin_amdgcn_s_setprio(1); _Pragma("unroll") for (int m = 0; m < 4; ++m) _Pragma("unroll") for (int n = 0; n < 2; ++n) _Pragma("unroll") for (int k = 0; k < 2; ++k) \
;         acc[ai][bj][m][n] = __builtin_amdgcn_mfma_f32_16x16x32_bf16(Bt[n][k], At[m][k], acc[ai][bj][m][n], 0, 0, 0); __builtin_amdgcn_s_setprio(0); } while (0)
; #define PG8_WAIT_V(n) asm volatile("s_waitcnt vmcnt(" #n ")" ::: "memory")
; #define PG8_WAIT_L(n) asm volatile("s_waitcnt lgkmcnt(" #n ")" ::: "memory")
; #define PG8_BAR __builtin_amdgcn_s_barrier()
; #define PG8_SCHED __builtin_amdgcn_sched_barrier(0)
; template <class Epi, class Sched, bool ALIGN_EPI = false, bool SP2 = false>
; __device__ __forceinline__ void gemm_phase(PG8_LAS unsigned char* lds, const Gemm g, const Sched& S, const Epi& E, const int wv  ) {
;     ...
;             PG8_WAIT_V(8); PG8_WAIT_L(0); PG8_BAR; PG8_MMA(0, 0, At, B0); PG8_MMA(0, 1, At, B1); PG8_BAR; PG8_SCHED;
;             PG8_LDA(At, 1, 1); PG8_STAGE(PG8_SB(1, 0), b3, voffB); PG8_STAGE(PG8_SB(1, 1), b3 + hstepB, voffB); PG8_STAGE(PG8_SA(1, 0), a3, voffA);
;             PG8_WAIT_V(8); PG8_WAIT_L(0); PG8_BAR; PG8_MMA(1, 0, At, B0); PG8_MMA(1, 1, At, B1); PG8_BAR; PG8_SCHED;
;     ...
;         if constexpr (ALIGN_EPI) { if (wr == 0) PG8_BAR; }
	v_mfma_f32_16x16x32_bf16 v[96:99], v[180:183], v[212:215], v[96:99]
	s_setprio 0
	s_add_i32 s62, s90, s67
	v_lshl_add_u64 v[216:217], v[216:217], 0, s[12:13]
	s_mov_b32 m0, s62
	ds_read_b128 v[184:187], v154 offset:49152
	ds_read_b128 v[188:191], v154 offset:50176
	ds_read_b128 v[192:195], v154 offset:51200
	ds_read_b128 v[196:199], v154 offset:52224
	ds_read_b128 v[200:203], v154 offset:53248
	ds_read_b128 v[204:207], v154 offset:54272
	ds_read_b128 v[208:211], v154 offset:55296
	ds_read_b128 v[212:215], v154 offset:56320
	global_load_lds_dwordx4 v[216:217], off
	s_add_i32 m0, s62, 0x2000
	s_add_u32 s60, s60, 0x100080
	v_lshl_add_u64 v[216:217], v[218:219], 0, s[12:13]
	s_addc_u32 s61, s61, 0
	s_add_i32 s62, s91, s67
	global_load_lds_dwordx4 v[216:217], off
	v_lshl_add_u64 v[216:217], s[60:61], 0, v[130:131]
	s_mov_b32 m0, s62
	s_nop 0
	global_load_lds_dwordx4 v[216:217], off
	v_lshl_add_u64 v[216:217], s[60:61], 0, v[134:135]
	s_add_i32 m0, s62, 0x2000
	s_nop 0
	global_load_lds_dwordx4 v[216:217], off
	v_lshl_add_u64 v[216:217], v[220:221], 0, s[12:13]
	s_mov_b32 m0, s74
	s_nop 0
	global_load_lds_dwordx4 v[216:217], off
	v_lshl_add_u64 v[216:217], v[222:223], 0, s[12:13]
	s_mov_b32 m0, s75
	s_nop 0
	global_load_lds_dwordx4 v[216:217], off
	s_waitcnt vmcnt(8)
	s_waitcnt lgkmcnt(0)
	s_barrier
	s_setprio 1
	s_waitcnt lgkmcnt(0)
	v_mfma_f32_16x16x32_bf16 v[28:31], v[146:149], v[184:187], v[28:31]
	v_mfma_f32_16x16x32_bf16 v[24:27], v[160:163], v[184:187], v[24:27]
	v_mfma_f32_16x16x32_bf16 v[20:23], v[146:149], v[192:195], v[20:23]
	v_mfma_f32_16x16x32_bf16 v[16:19], v[160:163], v[192:195], v[16:19]
	v_mfma_f32_16x16x32_bf16 v[12:15], v[146:149], v[200:203], v[12:15]
	v_mfma_f32_16x16x32_bf16 v[8:11], v[160:163], v[200:203], v[8:11]
	v_mfma_f32_16x16x32_bf16 v[4:7], v[146:149], v[208:211], v[4:7]
	v_mfma_f32_16x16x32_bf16 v[0:3], v[160:163], v[208:211], v[0:3]
	v_mfma_f32_16x16x32_bf16 v[28:31], v[156:159], v[188:191], v[28:31]
	v_mfma_f32_16x16x32_bf16 v[24:27], v[164:167], v[188:191], v[24:27]
	v_mfma_f32_16x16x32_bf16 v[20:23], v[156:159], v[196:199], v[20:23]
	v_mfma_f32_16x16x32_bf16 v[16:19], v[164:167], v[196:199], v[16:19]
	v_mfma_f32_16x16x32_bf16 v[12:15], v[156:159], v[204:207], v[12:15]
	v_mfma_f32_16x16x32_bf16 v[8:11], v[164:167], v[204:207], v[8:11]
	v_mfma_f32_16x16x32_bf16 v[4:7], v[156:159], v[212:215], v[4:7]
	v_mfma_f32_16x16x32_bf16 v[0:3], v[164:167], v[212:215], v[0:3]
	s_setprio 0
	s_setprio 1
	v_mfma_f32_16x16x32_bf16 v[92:95], v[168:171], v[184:187], v[92:95]
	v_mfma_f32_16x16x32_bf16 v[88:91], v[176:179], v[184:187], v[88:91]
	v_mfma_f32_16x16x32_bf16 v[84:87], v[168:171], v[192:195], v[84:87]
	v_mfma_f32_16x16x32_bf16 v[80:83], v[176:179], v[192:195], v[80:83]
	v_mfma_f32_16x16x32_bf16 v[60:63], v[168:171], v[200:203], v[60:63]
	v_mfma_f32_16x16x32_bf16 v[48:51], v[176:179], v[200:203], v[48:51]
	v_mfma_f32_16x16x32_bf16 v[36:39], v[168:171], v[208:211], v[36:39]
	v_mfma_f32_16x16x32_bf16 v[32:35], v[176:179], v[208:211], v[32:35]
	v_mfma_f32_16x16x32_bf16 v[92:95], v[172:175], v[188:191], v[92:95]
	v_mfma_f32_16x16x32_bf16 v[88:91], v[180:183], v[188:191], v[88:91]
	v_mfma_f32_16x16x32_bf16 v[84:87], v[172:175], v[196:199], v[84:87]
	v_mfma_f32_16x16x32_bf16 v[80:83], v[180:183], v[196:199], v[80:83]
	v_mfma_f32_16x16x32_bf16 v[60:63], v[172:175], v[204:207], v[60:63]
	v_mfma_f32_16x16x32_bf16 v[48:51], v[180:183], v[204:207], v[48:51]
	v_mfma_f32_16x16x32_bf16 v[36:39], v[172:175], v[212:215], v[36:39]
	s_setprio 2
	s_barrier
	v_mfma_f32_16x16x32_bf16 v[32:35], v[180:183], v[212:215], v[32:35]
	s_setprio 0
	s_add_i32 s87, s87, 2
	s_add_u32 s58, s58, 0x100
	s_addc_u32 s59, s59, 0
	s_add_u32 s85, s85, 0x100
	s_addc_u32 s86, s86, 0
	s_cmp_gt_u32 s87, 61
	s_cbranch_scc0 .LBB0_706
	s_and_b64 vcc, exec, s[14:15]
	s_cbranch_vccz .LBB0_709
	s_barrier

; #define PG8_STAGE(bufoff, gbase, voff) do { _Pragma("unroll") for (int _i = 0; _i < 2; ++_i) \
;         __builtin_amdgcn_global_load_lds((const unsigned*)((const char*)(gbase) + (voff)[_i]), (PG8_LAS unsigned*)(lds + (bufoff) + ldsw + _i * 8192), 16, 0, 0); } while (0)
; #define PG8_LDA(dst, b, h) do { _Pragma("unroll") for (int m = 0; m < 4; ++m) _Pragma("unroll") for (int k = 0; k < 2; ++k) dst[m][k] = *(const PG8_LAS bf16x8*)(lds + PG8_SA(b, h) + aoff + m * 2048 + k * 1024); } while (0)
; #define PG8_LDB(dst, b, h) do { _Pragma("unroll") for (int n = 0; n < 2; ++n) _Pragma("unroll") for (int k = 0; k < 2; ++k) dst[n][k] = *(const PG8_LAS bf16x8*)(lds + PG8_SB(b, h) + boff + n * 2048 + k * 1024); } while (0)
; #define PG8_MMA(ai, bj, At, Bt) do { __builtin_amdgcn_s_setprio(1); _Pragma("unroll") for (int m = 0; m < 4; ++m) _Pragma("unroll") for (int n = 0; n < 2; ++n) _Pragma("unroll") for (int k = 0; k < 2; ++k) \
;         acc[ai][bj][m][n] = __builtin_amdgcn_mfma_f32_16x16x32_bf16(Bt[n][k], At[m][k], acc[ai][bj][m][n], 0, 0, 0); __builtin_amdgcn_s_setprio(0); } while (0)
; #define PG8_WAIT_V(n) asm volatile("s_waitcnt vmcnt(" #n ")" ::: "memory")
; #define PG8_WAIT_L(n) asm volatile("s_waitcnt lgkmcnt(" #n ")" ::: "memory")
; #define PG8_BAR __builtin_amdgcn_s_barrier()
; template <class Epi, class Sched, bool ALIGN_EPI = false, bool SP2 = false>
; __device__ __forceinline__ void gemm_phase(PG8_LAS unsigned char* lds, const Gemm g, const Sched& S, const Epi& E, const int wv  ) {
;     ...
;         for (int t = 0; t < nt; t += 2) {
;             const bool last = (t == nt - 2);
;             const char* a1 = cA + (size_t)(t + 1) * kstep;
;             const char* a2 = last ? nA : cA + (size_t)(t + 2) * kstep; const char* b2 = last ? nB : cB + (size_t)(t + 2) * kstep;
;             const char* a3 = a2 + kstep; const char* b3 = b2 + kstep;
;             if (last && has_next) S.a_ready(nxt);
;             if constexpr (SP2) {
;             PG8_LDB(B0, 0, 0); PG8_LDB(B1, 0, 1); PG8_SCHED; PG8_LDA(At, 0, 0); PG8_STAGE(PG8_SA(1, 1), a1 + hstepA, voffA);
;             PG8_WAIT_V(8); PG8_WAIT_L(0); PG8_BAR; PG8_MMA(0, 0, At, B0); PG8_MMA(0, 1, At, B1); PG8_BAR; PG8_SCHED;
;             PG8_LDA(At, 0, 1); PG8_STAGE(PG8_SB(0, 0), b2, voffB); PG8_STAGE(PG8_SB(0, 1), b2 + hstepB, voffB); PG8_STAGE(PG8_SA(0, 0), a2, voffA);
.LBB0_850:
	ds_read_b128 v[146:149], v152
	ds_read_b128 v[156:159], v152 offset:1024
	ds_read_b128 v[160:163], v152 offset:2048
	ds_read_b128 v[164:167], v152 offset:3072
	ds_read_b128 v[168:171], v153
	ds_read_b128 v[172:175], v153 offset:1024
	ds_read_b128 v[176:179], v153 offset:2048
	ds_read_b128 v[180:183], v153 offset:3072
	s_add_u32 s60, s58, 0xfff00080
	s_addc_u32 s61, s59, -1
	s_cmp_eq_u32 s92, 60
	s_cselect_b32 s63, s51, s61
	s_cselect_b32 s62, s86, s60
	s_cselect_b32 s61, s49, s91
	s_cselect_b32 s60, s87, s90
	v_lshl_add_u64 v[216:217], s[58:59], 0, v[138:139]
	s_add_i32 m0, s71, 0xc000
	ds_read_b128 v[184:187], v154
	ds_read_b128 v[188:191], v154 offset:1024
	ds_read_b128 v[192:195], v154 offset:2048
	ds_read_b128 v[196:199], v154 offset:3072
	ds_read_b128 v[200:203], v154 offset:4096
	ds_read_b128 v[204:207], v154 offset:5120
	ds_read_b128 v[208:211], v154 offset:6144
	ds_read_b128 v[212:215], v154 offset:7168
	global_load_lds_dwordx4 v[216:217], off
	v_lshl_add_u64 v[216:217], s[58:59], 0, v[140:141]
	s_add_i32 m0, s71, 0xe000
	s_nop 0
	global_load_lds_dwordx4 v[216:217], off
	s_waitcnt vmcnt(8)
	s_waitcnt lgkmcnt(0)
	s_barrier
	s_setprio 1
	s_waitcnt lgkmcnt(0)
	v_mfma_f32_16x16x32_bf16 v[76:79], v[146:149], v[184:187], v[76:79]
	v_mfma_f32_16x16x32_bf16 v[72:75], v[160:163], v[184:187], v[72:75]
	v_mfma_f32_16x16x32_bf16 v[68:71], v[146:149], v[192:195], v[68:71]
	v_mfma_f32_16x16x32_bf16 v[64:67], v[160:163], v[192:195], v[64:67]
	v_mfma_f32_16x16x32_bf16 v[56:59], v[146:149], v[200:203], v[56:59]
	v_mfma_f32_16x16x32_bf16 v[52:55], v[160:163], v[200:203], v[52:55]
	v_mfma_f32_16x16x32_bf16 v[44:47], v[146:149], v[208:211], v[44:47]
	v_mfma_f32_16x16x32_bf16 v[40:43], v[160:163], v[208:211], v[40:43]
	v_mfma_f32_16x16x32_bf16 v[76:79], v[156:159], v[188:191], v[76:79]
	v_mfma_f32_16x16x32_bf16 v[72:75], v[164:167], v[188:191], v[72:75]
	v_mfma_f32_16x16x32_bf16 v[68:71], v[156:159], v[196:199], v[68:71]
	v_mfma_f32_16x16x32_bf16 v[64:67], v[164:167], v[196:199], v[64:67]
	v_mfma_f32_16x16x32_bf16 v[56:59], v[156:159], v[204:207], v[56:59]
	v_mfma_f32_16x16x32_bf16 v[52:55], v[164:167], v[204:207], v[52:55]
	v_mfma_f32_16x16x32_bf16 v[44:47], v[156:159], v[212:215], v[44:47]
	v_mfma_f32_16x16x32_bf16 v[40:43], v[164:167], v[212:215], v[40:43]
	s_setprio 0
	s_setprio 1
	v_mfma_f32_16x16x32_bf16 v[124:127], v[168:171], v[184:187], v[124:127]
	v_mfma_f32_16x16x32_bf16 v[120:123], v[176:179], v[184:187], v[120:123]
	v_mfma_f32_16x16x32_bf16 v[116:119], v[168:171], v[192:195], v[116:119]
	v_mfma_f32_16x16x32_bf16 v[112:115], v[176:179], v[192:195], v[112:115]
	v_mfma_f32_16x16x32_bf16 v[108:111], v[168:171], v[200:203], v[108:111]
	v_mfma_f32_16x16x32_bf16 v[104:107], v[176:179], v[200:203], v[104:107]
	v_mfma_f32_16x16x32_bf16 v[100:103], v[168:171], v[208:211], v[100:103]
	v_mfma_f32_16x16x32_bf16 v[96:99], v[176:179], v[208:211], v[96:99]
	v_mfma_f32_16x16x32_bf16 v[124:127], v[172:175], v[188:191], v[124:127]
	v_mfma_f32_16x16x32_bf16 v[120:123], v[180:183], v[188:191], v[120:123]
	v_mfma_f32_16x16x32_bf16 v[116:119], v[172:175], v[196:199], v[116:119]
	v_mfma_f32_16x16x32_bf16 v[112:115], v[180:183], v[196:199], v[112:115]
	v_mfma_f32_16x16x32_bf16 v[108:111], v[172:175], v[204:207], v[108:111]
	v_mfma_f32_16x16x32_bf16 v[104:107], v[180:183], v[204:207], v[104:107]
	v_mfma_f32_16x16x32_bf16 v[100:103], v[172:175], v[212:215], v[100:103]
	s_setprio 2
	s_barrier
	v_mfma_f32_16x16x32_bf16 v[96:99], v[180:183], v[212:215], v[96:99]
	s_setprio 0
	s_add_i32 s93, s80, s70
	v_lshl_add_u64 v[216:217], s[60:61], 0, v[130:131]
	s_mov_b32 m0, s93
	ds_read_b128 v[184:187], v154 offset:16384
	ds_read_b128 v[188:191], v154 offset:17408
	ds_read_b128 v[192:195], v154 offset:18432
	ds_read_b128 v[196:199], v154 offset:19456
	ds_read_b128 v[200:203], v154 offset:20480
	ds_read_b128 v[204:207], v154 offset:21504
	ds_read_b128 v[208:211], v154 offset:22528
	ds_read_b128 v[212:215], v154 offset:23552
	global_load_lds_dwordx4 v[216:217], off
	s_add_i32 m0, s93, 0x2000
	s_add_u32 s94, s60, 0x100000
	v_lshl_add_u64 v[218:219], s[60:61], 0, v[134:135]
	s_addc_u32 s95, s61, 0
	s_add_i32 s93, s81, s70
	global_load_lds_dwordx4 v[218:219], off
	v_lshl_add_u64 v[220:221], s[94:95], 0, v[130:131]
	s_mov_b32 m0, s93
	v_lshl_add_u64 v[222:223], s[62:63], 0, v[132:133]
	global_load_lds_dwordx4 v[220:221], off
	v_lshl_add_u64 v[220:221], s[94:95], 0, v[134:135]
	s_add_i32 m0, s93, 0x2000
	s_nop 0
	global_load_lds_dwordx4 v[220:221], off
	v_lshl_add_u64 v[220:221], s[62:63], 0, v[128:129]
	s_mov_b32 m0, s71
	s_nop 0
	global_load_lds_dwordx4 v[220:221], off
	s_mov_b32 m0, s72
	s_nop 0
	global_load_lds_dwordx4 v[222:223], off
	s_waitcnt vmcnt(8)
	s_waitcnt lgkmcnt(0)
	s_barrier
; #define PG8_STAGE(bufoff, gbase, voff) do { _Pragma("unroll") for (int _i = 0; _i < 2; ++_i) \
;         __builtin_amdgcn_global_load_lds((const unsigned*)((const char*)(gbase) + (voff)[_i]), (PG8_LAS unsigned*)(lds + (bufoff) + ldsw + _i * 8192), 16, 0, 0); } while (0)
; #define PG8_LDA(dst, b, h) do { _Pragma("unroll") for (int m = 0; m < 4; ++m) _Pragma("unroll") for (int k = 0; k < 2; ++k) dst[m][k] = *(const PG8_LAS bf16x8*)(lds + PG8_SA(b, h) + aoff + m * 2048 + k * 1024); } while (0)
; #define PG8_LDB(dst, b, h) do { _Pragma("unroll") for (int n = 0; n < 2; ++n) _Pragma("unroll") for (int k = 0; k < 2; ++k) dst[n][k] = *(const PG8_LAS bf16x8*)(lds + PG8_SB(b, h) + boff + n * 2048 + k * 1024); } while (0)
; #define PG8_MMA(ai, bj, At, Bt) do { __builtin_amdgcn_s_setprio(1); _Pragma("unroll") for (int m = 0; m < 4; ++m) _Pragma("unroll") for (int n = 0; n < 2; ++n) _Pragma("unroll") for (int k = 0; k < 2; ++k) \
;         acc[ai][bj][m][n] = __builtin_amdgcn_mfma_f32_16x16x32_bf16(Bt[n][k], At[m][k], acc[ai][bj][m][n], 0, 0, 0); __builtin_amdgcn_s_setprio(0); } while (0)
; #define PG8_WAIT_V(n) asm volatile("s_waitcnt vmcnt(" #n ")" ::: "memory")
; #define PG8_WAIT_L(n) asm volatile("s_waitcnt lgkmcnt(" #n ")" ::: "memory")
; #define PG8_BAR __builtin_amdgcn_s_barrier()
; #define PG8_SCHED __builtin_amdgcn_sched_barrier(0)
; template <class Epi, class Sched, bool ALIGN_EPI = false, bool SP2 = false>
; __device__ __forceinline__ void gemm_phase(PG8_LAS unsigned char* lds, const Gemm g, const Sched& S, const Epi& E, const int wv  ) {
;     ...
;             PG8_WAIT_V(8); PG8_WAIT_L(0); PG8_BAR; PG8_MMA(1, 0, At, B0); PG8_MMA(1, 1, At, B1); PG8_BAR; PG8_SCHED;
;             PG8_LDB(B0, 1, 0); PG8_LDB(B1, 1, 1); PG8_SCHED; PG8_LDA(At, 1, 0); PG8_STAGE(PG8_SA(0, 1), a2 + hstepA, voffA);
;             PG8_WAIT_V(8); PG8_WAIT_L(0); PG8_BAR; PG8_MMA(0, 0, At, B0); PG8_MMA(0, 1, At, B1); PG8_BAR; PG8_SCHED;
	s_setprio 1
	s_waitcnt lgkmcnt(0)
	v_mfma_f32_16x16x32_bf16 v[28:31], v[146:149], v[184:187], v[28:31]
	v_mfma_f32_16x16x32_bf16 v[24:27], v[160:163], v[184:187], v[24:27]
	v_mfma_f32_16x16x32_bf16 v[20:23], v[146:149], v[192:195], v[20:23]
	v_mfma_f32_16x16x32_bf16 v[16:19], v[160:163], v[192:195], v[16:19]
	v_mfma_f32_16x16x32_bf16 v[12:15], v[146:149], v[200:203], v[12:15]
	v_mfma_f32_16x16x32_bf16 v[8:11], v[160:163], v[200:203], v[8:11]
	v_mfma_f32_16x16x32_bf16 v[4:7], v[146:149], v[208:211], v[4:7]
	v_mfma_f32_16x16x32_bf16 v[0:3], v[160:163], v[208:211], v[0:3]
	v_mfma_f32_16x16x32_bf16 v[28:31], v[156:159], v[188:191], v[28:31]
	v_mfma_f32_16x16x32_bf16 v[24:27], v[164:167], v[188:191], v[24:27]
	v_mfma_f32_16x16x32_bf16 v[20:23], v[156:159], v[196:199], v[20:23]
	v_mfma_f32_16x16x32_bf16 v[16:19], v[164:167], v[196:199], v[16:19]
	v_mfma_f32_16x16x32_bf16 v[12:15], v[156:159], v[204:207], v[12:15]
	v_mfma_f32_16x16x32_bf16 v[8:11], v[164:167], v[204:207], v[8:11]
	v_mfma_f32_16x16x32_bf16 v[4:7], v[156:159], v[212:215], v[4:7]
	v_mfma_f32_16x16x32_bf16 v[0:3], v[164:167], v[212:215], v[0:3]
	s_setprio 0
	s_setprio 1
	v_mfma_f32_16x16x32_bf16 v[92:95], v[168:171], v[184:187], v[92:95]
	v_mfma_f32_16x16x32_bf16 v[88:91], v[176:179], v[184:187], v[88:91]
	v_mfma_f32_16x16x32_bf16 v[84:87], v[168:171], v[192:195], v[84:87]
	v_mfma_f32_16x16x32_bf16 v[80:83], v[176:179], v[192:195], v[80:83]
	v_mfma_f32_16x16x32_bf16 v[60:63], v[168:171], v[200:203], v[60:63]
	v_mfma_f32_16x16x32_bf16 v[48:51], v[176:179], v[200:203], v[48:51]
	v_mfma_f32_16x16x32_bf16 v[36:39], v[168:171], v[208:211], v[36:39]
	v_mfma_f32_16x16x32_bf16 v[32:35], v[176:179], v[208:211], v[32:35]
	v_mfma_f32_16x16x32_bf16 v[92:95], v[172:175], v[188:191], v[92:95]
	v_mfma_f32_16x16x32_bf16 v[88:91], v[180:183], v[188:191], v[88:91]
	v_mfma_f32_16x16x32_bf16 v[84:87], v[172:175], v[196:199], v[84:87]
	v_mfma_f32_16x16x32_bf16 v[80:83], v[180:183], v[196:199], v[80:83]
	v_mfma_f32_16x16x32_bf16 v[60:63], v[172:175], v[204:207], v[60:63]
	v_mfma_f32_16x16x32_bf16 v[48:51], v[180:183], v[204:207], v[48:51]
	v_mfma_f32_16x16x32_bf16 v[36:39], v[172:175], v[212:215], v[36:39]
	s_setprio 2
	s_barrier
	v_mfma_f32_16x16x32_bf16 v[32:35], v[180:183], v[212:215], v[32:35]
	s_setprio 0
	s_add_i32 s93, 0, 0x18000
	v_add_u32_e32 v155, s93, v150
	s_add_i32 s94, 0, 0x1c000
	ds_read_b128 v[146:149], v155
	ds_read_b128 v[156:159], v155 offset:1024
	ds_read_b128 v[160:163], v155 offset:2048
	ds_read_b128 v[164:167], v155 offset:3072
	v_add_u32_e32 v155, s94, v150
	ds_read_b128 v[168:171], v155
	ds_read_b128 v[172:175], v155 offset:1024
	ds_read_b128 v[176:179], v155 offset:2048
	ds_read_b128 v[180:183], v155 offset:3072
	s_add_u32 s62, s62, 0x100000
	s_addc_u32 s63, s63, 0
	s_mov_b32 m0, s73
	v_lshl_add_u64 v[224:225], s[62:63], 0, v[128:129]
	ds_read_b128 v[184:187], v154 offset:32768
	ds_read_b128 v[188:191], v154 offset:33792
	ds_read_b128 v[192:195], v154 offset:34816
	ds_read_b128 v[196:199], v154 offset:35840
	ds_read_b128 v[200:203], v154 offset:36864
	ds_read_b128 v[204:207], v154 offset:37888
	ds_read_b128 v[208:211], v154 offset:38912
	ds_read_b128 v[212:215], v154 offset:39936
	global_load_lds_dwordx4 v[224:225], off
	v_lshl_add_u64 v[224:225], s[62:63], 0, v[132:133]
	s_mov_b32 m0, s74
	s_nop 0
	global_load_lds_dwordx4 v[224:225], off
	s_waitcnt vmcnt(8)
	s_waitcnt lgkmcnt(0)
	s_barrier
	s_setprio 1
	s_waitcnt lgkmcnt(0)
	v_mfma_f32_16x16x32_bf16 v[76:79], v[146:149], v[184:187], v[76:79]
	v_mfma_f32_16x16x32_bf16 v[72:75], v[160:163], v[184:187], v[72:75]
	v_mfma_f32_16x16x32_bf16 v[68:71], v[146:149], v[192:195], v[68:71]
	v_mfma_f32_16x16x32_bf16 v[64:67], v[160:163], v[192:195], v[64:67]
	v_mfma_f32_16x16x32_bf16 v[56:59], v[146:149], v[200:203], v[56:59]
	v_mfma_f32_16x16x32_bf16 v[52:55], v[160:163], v[200:203], v[52:55]
	v_mfma_f32_16x16x32_bf16 v[44:47], v[146:149], v[208:211], v[44:47]
	v_mfma_f32_16x16x32_bf16 v[40:43], v[160:163], v[208:211], v[40:43]
	v_mfma_f32_16x16x32_bf16 v[76:79], v[156:159], v[188:191], v[76:79]
	v_mfma_f32_16x16x32_bf16 v[72:75], v[164:167], v[188:191], v[72:75]
	v_mfma_f32_16x16x32_bf16 v[68:71], v[156:159], v[196:199], v[68:71]
	v_mfma_f32_16x16x32_bf16 v[64:67], v[164:167], v[196:199], v[64:67]
	v_mfma_f32_16x16x32_bf16 v[56:59], v[156:159], v[204:207], v[56:59]
	v_mfma_f32_16x16x32_bf16 v[52:55], v[164:167], v[204:207], v[52:55]
	v_mfma_f32_16x16x32_bf16 v[44:47], v[156:159], v[212:215], v[44:47]
	v_mfma_f32_16x16x32_bf16 v[40:43], v[164:167], v[212:215], v[40:43]
	s_setprio 0
	s_setprio 1
	v_mfma_f32_16x16x32_bf16 v[124:127], v[168:171], v[184:187], v[124:127]
	v_mfma_f32_16x16x32_bf16 v[120:123], v[176:179], v[184:187], v[120:123]
	v_mfma_f32_16x16x32_bf16 v[116:119], v[168:171], v[192:195], v[116:119]
	v_mfma_f32_16x16x32_bf16 v[112:115], v[176:179], v[192:195], v[112:115]
	v_mfma_f32_16x16x32_bf16 v[108:111], v[168:171], v[200:203], v[108:111]
	v_mfma_f32_16x16x32_bf16 v[104:107], v[176:179], v[200:203], v[104:107]
	v_mfma_f32_16x16x32_bf16 v[100:103], v[168:171], v[208:211], v[100:103]
	v_mfma_f32_16x16x32_bf16 v[96:99], v[176:179], v[208:211], v[96:99]
	v_mfma_f32_16x16x32_bf16 v[124:127], v[172:175], v[188:191], v[124:127]
	v_mfma_f32_16x16x32_bf16 v[120:123], v[180:183], v[188:191], v[120:123]
	v_mfma_f32_16x16x32_bf16 v[116:119], v[172:175], v[196:199], v[116:119]
	v_mfma_f32_16x16x32_bf16 v[112:115], v[180:183], v[196:199], v[112:115]
	v_mfma_f32_16x16x32_bf16 v[108:111], v[172:175], v[204:207], v[108:111]
	v_mfma_f32_16x16x32_bf16 v[104:107], v[180:183], v[204:207], v[104:107]
	v_mfma_f32_16x16x32_bf16 v[100:103], v[172:175], v[212:215], v[100:103]
	s_setprio 2
	s_barrier
; #define PG8_STAGE(bufoff, gbase, voff) do { _Pragma("unroll") for (int _i = 0; _i < 2; ++_i) \
;         __builtin_amdgcn_global_load_lds((const unsigned*)((const char*)(gbase) + (voff)[_i]), (PG8_LAS unsigned*)(lds + (bufoff) + ldsw + _i * 8192), 16, 0, 0); } while (0)
; #define PG8_LDA(dst, b, h) do { _Pragma("unroll") for (int m = 0; m < 4; ++m) _Pragma("unroll") for (int k = 0; k < 2; ++k) dst[m][k] = *(const PG8_LAS bf16x8*)(lds + PG8_SA(b, h) + aoff + m * 2048 + k * 1024); } while (0)
; #define PG8_MMA(ai, bj, At, Bt) do { __builtin_amdgcn_s_setprio(1); _Pragma("unroll") for (int m = 0; m < 4; ++m) _Pragma("unroll") for (int n = 0; n < 2; ++n) _Pragma("unroll") for (int k = 0; k < 2; ++k) \
;         acc[ai][bj][m][n] = __builtin_amdgcn_mfma_f32_16x16x32_bf16(Bt[n][k], At[m][k], acc[ai][bj][m][n], 0, 0, 0); __builtin_amdgcn_s_setprio(0); } while (0)
; #define PG8_WAIT_V(n) asm volatile("s_waitcnt vmcnt(" #n ")" ::: "memory")
; #define PG8_WAIT_L(n) asm volatile("s_waitcnt lgkmcnt(" #n ")" ::: "memory")
; #define PG8_BAR __builtin_amdgcn_s_barrier()
; #define PG8_SCHED __builtin_amdgcn_sched_barrier(0)
; template <class Epi, class Sched, bool ALIGN_EPI = false, bool SP2 = false>
; __device__ __forceinline__ void gemm_phase(PG8_LAS unsigned char* lds, const Gemm g, const Sched& S, const Epi& E, const int wv  ) {
;     ...
;             PG8_WAIT_V(8); PG8_WAIT_L(0); PG8_BAR; PG8_MMA(0, 0, At, B0); PG8_MMA(0, 1, At, B1); PG8_BAR; PG8_SCHED;
;             PG8_LDA(At, 1, 1); PG8_STAGE(PG8_SB(1, 0), b3, voffB); PG8_STAGE(PG8_SB(1, 1), b3 + hstepB, voffB); PG8_STAGE(PG8_SA(1, 0), a3, voffA);
;             PG8_WAIT_V(8); PG8_WAIT_L(0); PG8_BAR; PG8_MMA(1, 0, At, B0); PG8_MMA(1, 1, At, B1); PG8_BAR; PG8_SCHED;
;     ...
;         if constexpr (ALIGN_EPI) { if (wr == 0) PG8_BAR; }
	v_mfma_f32_16x16x32_bf16 v[96:99], v[180:183], v[212:215], v[96:99]
	s_setprio 0
	s_add_i32 s62, s93, s70
	v_lshl_add_u64 v[216:217], v[216:217], 0, s[10:11]
	s_mov_b32 m0, s62
	ds_read_b128 v[184:187], v154 offset:49152
	ds_read_b128 v[188:191], v154 offset:50176
	ds_read_b128 v[192:195], v154 offset:51200
	ds_read_b128 v[196:199], v154 offset:52224
	ds_read_b128 v[200:203], v154 offset:53248
	ds_read_b128 v[204:207], v154 offset:54272
	ds_read_b128 v[208:211], v154 offset:55296
	ds_read_b128 v[212:215], v154 offset:56320
	global_load_lds_dwordx4 v[216:217], off
	s_add_i32 m0, s62, 0x2000
	s_add_u32 s60, s60, 0x100080
	v_lshl_add_u64 v[216:217], v[218:219], 0, s[10:11]
	s_addc_u32 s61, s61, 0
	s_add_i32 s62, s94, s70
	global_load_lds_dwordx4 v[216:217], off
	v_lshl_add_u64 v[216:217], s[60:61], 0, v[130:131]
	s_mov_b32 m0, s62
	s_nop 0
	global_load_lds_dwordx4 v[216:217], off
	v_lshl_add_u64 v[216:217], s[60:61], 0, v[134:135]
	s_add_i32 m0, s62, 0x2000
	s_nop 0
	global_load_lds_dwordx4 v[216:217], off
	v_lshl_add_u64 v[216:217], v[220:221], 0, s[10:11]
	s_mov_b32 m0, s77
	s_nop 0
	global_load_lds_dwordx4 v[216:217], off
	v_lshl_add_u64 v[216:217], v[222:223], 0, s[10:11]
	s_mov_b32 m0, s78
	s_nop 0
	global_load_lds_dwordx4 v[216:217], off
	s_waitcnt vmcnt(8)
	s_waitcnt lgkmcnt(0)
	s_barrier
	s_setprio 1
	s_waitcnt lgkmcnt(0)
	v_mfma_f32_16x16x32_bf16 v[28:31], v[146:149], v[184:187], v[28:31]
	v_mfma_f32_16x16x32_bf16 v[24:27], v[160:163], v[184:187], v[24:27]
	v_mfma_f32_16x16x32_bf16 v[20:23], v[146:149], v[192:195], v[20:23]
	v_mfma_f32_16x16x32_bf16 v[16:19], v[160:163], v[192:195], v[16:19]
	v_mfma_f32_16x16x32_bf16 v[12:15], v[146:149], v[200:203], v[12:15]
	v_mfma_f32_16x16x32_bf16 v[8:11], v[160:163], v[200:203], v[8:11]
	v_mfma_f32_16x16x32_bf16 v[4:7], v[146:149], v[208:211], v[4:7]
	v_mfma_f32_16x16x32_bf16 v[0:3], v[160:163], v[208:211], v[0:3]
	v_mfma_f32_16x16x32_bf16 v[28:31], v[156:159], v[188:191], v[28:31]
	v_mfma_f32_16x16x32_bf16 v[24:27], v[164:167], v[188:191], v[24:27]
	v_mfma_f32_16x16x32_bf16 v[20:23], v[156:159], v[196:199], v[20:23]
	v_mfma_f32_16x16x32_bf16 v[16:19], v[164:167], v[196:199], v[16:19]
	v_mfma_f32_16x16x32_bf16 v[12:15], v[156:159], v[204:207], v[12:15]
	v_mfma_f32_16x16x32_bf16 v[8:11], v[164:167], v[204:207], v[8:11]
	v_mfma_f32_16x16x32_bf16 v[4:7], v[156:159], v[212:215], v[4:7]
	v_mfma_f32_16x16x32_bf16 v[0:3], v[164:167], v[212:215], v[0:3]
	s_setprio 0
	s_setprio 1
	v_mfma_f32_16x16x32_bf16 v[92:95], v[168:171], v[184:187], v[92:95]
	v_mfma_f32_16x16x32_bf16 v[88:91], v[176:179], v[184:187], v[88:91]
	v_mfma_f32_16x16x32_bf16 v[84:87], v[168:171], v[192:195], v[84:87]
	v_mfma_f32_16x16x32_bf16 v[80:83], v[176:179], v[192:195], v[80:83]
	v_mfma_f32_16x16x32_bf16 v[60:63], v[168:171], v[200:203], v[60:63]
	v_mfma_f32_16x16x32_bf16 v[48:51], v[176:179], v[200:203], v[48:51]
	v_mfma_f32_16x16x32_bf16 v[36:39], v[168:171], v[208:211], v[36:39]
	v_mfma_f32_16x16x32_bf16 v[32:35], v[176:179], v[208:211], v[32:35]
	v_mfma_f32_16x16x32_bf16 v[92:95], v[172:175], v[188:191], v[92:95]
	v_mfma_f32_16x16x32_bf16 v[88:91], v[180:183], v[188:191], v[88:91]
	v_mfma_f32_16x16x32_bf16 v[84:87], v[172:175], v[196:199], v[84:87]
	v_mfma_f32_16x16x32_bf16 v[80:83], v[180:183], v[196:199], v[80:83]
	v_mfma_f32_16x16x32_bf16 v[60:63], v[172:175], v[204:207], v[60:63]
	v_mfma_f32_16x16x32_bf16 v[48:51], v[180:183], v[204:207], v[48:51]
	v_mfma_f32_16x16x32_bf16 v[36:39], v[172:175], v[212:215], v[36:39]
	s_setprio 2
	s_barrier
	v_mfma_f32_16x16x32_bf16 v[32:35], v[180:183], v[212:215], v[32:35]
	s_setprio 0
	s_add_i32 s92, s92, 2
	s_add_u32 s58, s58, 0x100
	s_addc_u32 s59, s59, 0
	s_add_u32 s90, s90, 0x100
	s_addc_u32 s91, s91, 0
	s_cmp_gt_u32 s92, 61
	s_cbranch_scc0 .LBB0_850
	s_and_b64 vcc, exec, s[12:13]
	s_cbranch_vccz .LBB0_853
	s_barrier

; #define PG8_STAGE(bufoff, gbase, voff) do { _Pragma("unroll") for (int _i = 0; _i < 2; ++_i) \
;         __builtin_amdgcn_global_load_lds((const unsigned*)((const char*)(gbase) + (voff)[_i]), (PG8_LAS unsigned*)(lds + (bufoff) + ldsw + _i * 8192), 16, 0, 0); } while (0)
; #define PG8_LDA(dst, b, h) do { _Pragma("unroll") for (int m = 0; m < 4; ++m) _Pragma("unroll") for (int k = 0; k < 2; ++k) dst[m][k] = *(const PG8_LAS bf16x8*)(lds + PG8_SA(b, h) + aoff + m * 2048 + k * 1024); } while (0)
; #define PG8_LDB(dst, b, h) do { _Pragma("unroll") for (int n = 0; n < 2; ++n) _Pragma("unroll") for (int k = 0; k < 2; ++k) dst[n][k] = *(const PG8_LAS bf16x8*)(lds + PG8_SB(b, h) + boff + n * 2048 + k * 1024); } while (0)
; #define PG8_MMA(ai, bj, At, Bt) do { __builtin_amdgcn_s_setprio(1); _Pragma("unroll") for (int m = 0; m < 4; ++m) _Pragma("unroll") for (int n = 0; n < 2; ++n) _Pragma("unroll") for (int k = 0; k < 2; ++k) \
;         acc[ai][bj][m][n] = __builtin_amdgcn_mfma_f32_16x16x32_bf16(Bt[n][k], At[m][k], acc[ai][bj][m][n], 0, 0, 0); __builtin_amdgcn_s_setprio(0); } while (0)
; #define PG8_WAIT_V(n) asm volatile("s_waitcnt vmcnt(" #n ")" ::: "memory")
; #define PG8_WAIT_L(n) asm volatile("s_waitcnt lgkmcnt(" #n ")" ::: "memory")
; #define PG8_BAR __builtin_amdgcn_s_barrier()
; template <class Epi, class Sched, bool ALIGN_EPI = false, bool SP2 = false>
; __device__ __forceinline__ void gemm_phase(PG8_LAS unsigned char* lds, const Gemm g, const Sched& S, const Epi& E, const int wv  ) {
;     ...
;         for (int t = 0; t < nt; t += 2) {
;             const bool last = (t == nt - 2);
;             const char* a1 = cA + (size_t)(t + 1) * kstep;
;             const char* a2 = last ? nA : cA + (size_t)(t + 2) * kstep; const char* b2 = last ? nB : cB + (size_t)(t + 2) * kstep;
;             const char* a3 = a2 + kstep; const char* b3 = b2 + kstep;
;             if (last && has_next) S.a_ready(nxt);
;             if constexpr (SP2) {
;             PG8_LDB(B0, 0, 0); PG8_LDB(B1, 0, 1); PG8_SCHED; PG8_LDA(At, 0, 0); PG8_STAGE(PG8_SA(1, 1), a1 + hstepA, voffA);
;             PG8_WAIT_V(8); PG8_WAIT_L(0); PG8_BAR; PG8_MMA(0, 0, At, B0); PG8_MMA(0, 1, At, B1); PG8_BAR; PG8_SCHED;
;             PG8_LDA(At, 0, 1); PG8_STAGE(PG8_SB(0, 0), b2, voffB); PG8_STAGE(PG8_SB(0, 1), b2 + hstepB, voffB); PG8_STAGE(PG8_SA(0, 0), a2, voffA);
.LBB0_871:
	ds_read_b128 v[142:145], v148
	ds_read_b128 v[152:155], v148 offset:1024
	ds_read_b128 v[156:159], v148 offset:2048
	ds_read_b128 v[160:163], v148 offset:3072
	ds_read_b128 v[164:167], v149
	ds_read_b128 v[168:171], v149 offset:1024
	ds_read_b128 v[172:175], v149 offset:2048
	ds_read_b128 v[176:179], v149 offset:3072
	s_add_u32 s60, s58, 0xfff00080
	s_addc_u32 s61, s59, -1
	s_cmp_eq_u32 s96, 60
	s_cselect_b32 s63, s49, s61
	s_cselect_b32 s62, s92, s60
	s_cselect_b32 s61, s47, s95
	s_cselect_b32 s60, s93, s94
	v_lshl_add_u64 v[212:213], s[58:59], 0, v[138:139]
	s_add_i32 m0, s75, 0xc000
	ds_read_b128 v[180:183], v150
	ds_read_b128 v[184:187], v150 offset:1024
	ds_read_b128 v[188:191], v150 offset:2048
	ds_read_b128 v[192:195], v150 offset:3072
	ds_read_b128 v[196:199], v150 offset:4096
	ds_read_b128 v[200:203], v150 offset:5120
	ds_read_b128 v[204:207], v150 offset:6144
	ds_read_b128 v[208:211], v150 offset:7168
	global_load_lds_dwordx4 v[212:213], off
	v_lshl_add_u64 v[212:213], s[58:59], 0, v[140:141]
	s_add_i32 m0, s75, 0xe000
	s_nop 0
	global_load_lds_dwordx4 v[212:213], off
	s_waitcnt vmcnt(8)
	s_waitcnt lgkmcnt(0)
	s_barrier
	s_setprio 1
	s_waitcnt lgkmcnt(0)
	v_mfma_f32_16x16x32_bf16 v[76:79], v[142:145], v[180:183], v[76:79]
	v_mfma_f32_16x16x32_bf16 v[72:75], v[156:159], v[180:183], v[72:75]
	v_mfma_f32_16x16x32_bf16 v[68:71], v[142:145], v[188:191], v[68:71]
	v_mfma_f32_16x16x32_bf16 v[64:67], v[156:159], v[188:191], v[64:67]
	v_mfma_f32_16x16x32_bf16 v[56:59], v[142:145], v[196:199], v[56:59]
	v_mfma_f32_16x16x32_bf16 v[52:55], v[156:159], v[196:199], v[52:55]
	v_mfma_f32_16x16x32_bf16 v[44:47], v[142:145], v[204:207], v[44:47]
	v_mfma_f32_16x16x32_bf16 v[40:43], v[156:159], v[204:207], v[40:43]
	v_mfma_f32_16x16x32_bf16 v[76:79], v[152:155], v[184:187], v[76:79]
	v_mfma_f32_16x16x32_bf16 v[72:75], v[160:163], v[184:187], v[72:75]
	v_mfma_f32_16x16x32_bf16 v[68:71], v[152:155], v[192:195], v[68:71]
	v_mfma_f32_16x16x32_bf16 v[64:67], v[160:163], v[192:195], v[64:67]
	v_mfma_f32_16x16x32_bf16 v[56:59], v[152:155], v[200:203], v[56:59]
	v_mfma_f32_16x16x32_bf16 v[52:55], v[160:163], v[200:203], v[52:55]
	v_mfma_f32_16x16x32_bf16 v[44:47], v[152:155], v[208:211], v[44:47]
	v_mfma_f32_16x16x32_bf16 v[40:43], v[160:163], v[208:211], v[40:43]
	s_setprio 0
	s_setprio 1
	v_mfma_f32_16x16x32_bf16 v[124:127], v[164:167], v[180:183], v[124:127]
	v_mfma_f32_16x16x32_bf16 v[120:123], v[172:175], v[180:183], v[120:123]
	v_mfma_f32_16x16x32_bf16 v[116:119], v[164:167], v[188:191], v[116:119]
	v_mfma_f32_16x16x32_bf16 v[112:115], v[172:175], v[188:191], v[112:115]
	v_mfma_f32_16x16x32_bf16 v[108:111], v[164:167], v[196:199], v[108:111]
	v_mfma_f32_16x16x32_bf16 v[104:107], v[172:175], v[196:199], v[104:107]
	v_mfma_f32_16x16x32_bf16 v[100:103], v[164:167], v[204:207], v[100:103]
	v_mfma_f32_16x16x32_bf16 v[96:99], v[172:175], v[204:207], v[96:99]
	v_mfma_f32_16x16x32_bf16 v[124:127], v[168:171], v[184:187], v[124:127]
	v_mfma_f32_16x16x32_bf16 v[120:123], v[176:179], v[184:187], v[120:123]
	v_mfma_f32_16x16x32_bf16 v[116:119], v[168:171], v[192:195], v[116:119]
	v_mfma_f32_16x16x32_bf16 v[112:115], v[176:179], v[192:195], v[112:115]
	v_mfma_f32_16x16x32_bf16 v[108:111], v[168:171], v[200:203], v[108:111]
	v_mfma_f32_16x16x32_bf16 v[104:107], v[176:179], v[200:203], v[104:107]
	v_mfma_f32_16x16x32_bf16 v[100:103], v[168:171], v[208:211], v[100:103]
	s_setprio 2
	s_barrier
	v_mfma_f32_16x16x32_bf16 v[96:99], v[176:179], v[208:211], v[96:99]
	s_setprio 0
	s_add_i32 s97, s84, s73
	v_lshl_add_u64 v[212:213], s[60:61], 0, v[132:133]
	s_mov_b32 m0, s97
	ds_read_b128 v[180:183], v150 offset:16384
	ds_read_b128 v[184:187], v150 offset:17408
	ds_read_b128 v[188:191], v150 offset:18432
	ds_read_b128 v[192:195], v150 offset:19456
	ds_read_b128 v[196:199], v150 offset:20480
	ds_read_b128 v[200:203], v150 offset:21504
	ds_read_b128 v[204:207], v150 offset:22528
	ds_read_b128 v[208:211], v150 offset:23552
	global_load_lds_dwordx4 v[212:213], off
	s_add_i32 m0, s97, 0x2000
	s_add_u32 vcc_lo, s60, 0x100000
	v_lshl_add_u64 v[214:215], s[60:61], 0, v[128:129]
	s_addc_u32 vcc_hi, s61, 0
	s_add_i32 s97, s85, s73
	global_load_lds_dwordx4 v[214:215], off
	v_lshl_add_u64 v[216:217], vcc, 0, v[132:133]
	s_mov_b32 m0, s97
	v_lshl_add_u64 v[218:219], s[62:63], 0, v[130:131]
	global_load_lds_dwordx4 v[216:217], off
	v_lshl_add_u64 v[216:217], vcc, 0, v[128:129]
	s_add_i32 m0, s97, 0x2000
	s_nop 0
	global_load_lds_dwordx4 v[216:217], off
	v_lshl_add_u64 v[216:217], s[62:63], 0, v[134:135]
	s_mov_b32 m0, s75
	s_nop 0
	global_load_lds_dwordx4 v[216:217], off
	s_mov_b32 m0, s76
	s_nop 0
	global_load_lds_dwordx4 v[218:219], off
	s_waitcnt vmcnt(8)
	s_waitcnt lgkmcnt(0)
	s_barrier
; #define PG8_STAGE(bufoff, gbase, voff) do { _Pragma("unroll") for (int _i = 0; _i < 2; ++_i) \
;         __builtin_amdgcn_global_load_lds((const unsigned*)((const char*)(gbase) + (voff)[_i]), (PG8_LAS unsigned*)(lds + (bufoff) + ldsw + _i * 8192), 16, 0, 0); } while (0)
; #define PG8_LDA(dst, b, h) do { _Pragma("unroll") for (int m = 0; m < 4; ++m) _Pragma("unroll") for (int k = 0; k < 2; ++k) dst[m][k] = *(const PG8_LAS bf16x8*)(lds + PG8_SA(b, h) + aoff + m * 2048 + k * 1024); } while (0)
; #define PG8_LDB(dst, b, h) do { _Pragma("unroll") for (int n = 0; n < 2; ++n) _Pragma("unroll") for (int k = 0; k < 2; ++k) dst[n][k] = *(const PG8_LAS bf16x8*)(lds + PG8_SB(b, h) + boff + n * 2048 + k * 1024); } while (0)
; #define PG8_MMA(ai, bj, At, Bt) do { __builtin_amdgcn_s_setprio(1); _Pragma("unroll") for (int m = 0; m < 4; ++m) _Pragma("unroll") for (int n = 0; n < 2; ++n) _Pragma("unroll") for (int k = 0; k < 2; ++k) \
;         acc[ai][bj][m][n] = __builtin_amdgcn_mfma_f32_16x16x32_bf16(Bt[n][k], At[m][k], acc[ai][bj][m][n], 0, 0, 0); __builtin_amdgcn_s_setprio(0); } while (0)
; #define PG8_WAIT_V(n) asm volatile("s_waitcnt vmcnt(" #n ")" ::: "memory")
; #define PG8_WAIT_L(n) asm volatile("s_waitcnt lgkmcnt(" #n ")" ::: "memory")
; #define PG8_BAR __builtin_amdgcn_s_barrier()
; #define PG8_SCHED __builtin_amdgcn_sched_barrier(0)
; template <class Epi, class Sched, bool ALIGN_EPI = false, bool SP2 = false>
; __device__ __forceinline__ void gemm_phase(PG8_LAS unsigned char* lds, const Gemm g, const Sched& S, const Epi& E, const int wv  ) {
;     ...
;             PG8_WAIT_V(8); PG8_WAIT_L(0); PG8_BAR; PG8_MMA(1, 0, At, B0); PG8_MMA(1, 1, At, B1); PG8_BAR; PG8_SCHED;
;             PG8_LDB(B0, 1, 0); PG8_LDB(B1, 1, 1); PG8_SCHED; PG8_LDA(At, 1, 0); PG8_STAGE(PG8_SA(0, 1), a2 + hstepA, voffA);
;             PG8_WAIT_V(8); PG8_WAIT_L(0); PG8_BAR; PG8_MMA(0, 0, At, B0); PG8_MMA(0, 1, At, B1); PG8_BAR; PG8_SCHED;
	s_setprio 1
	s_waitcnt lgkmcnt(0)
	v_mfma_f32_16x16x32_bf16 v[28:31], v[142:145], v[180:183], v[28:31]
	v_mfma_f32_16x16x32_bf16 v[24:27], v[156:159], v[180:183], v[24:27]
	v_mfma_f32_16x16x32_bf16 v[20:23], v[142:145], v[188:191], v[20:23]
	v_mfma_f32_16x16x32_bf16 v[16:19], v[156:159], v[188:191], v[16:19]
	v_mfma_f32_16x16x32_bf16 v[12:15], v[142:145], v[196:199], v[12:15]
	v_mfma_f32_16x16x32_bf16 v[8:11], v[156:159], v[196:199], v[8:11]
	v_mfma_f32_16x16x32_bf16 v[4:7], v[142:145], v[204:207], v[4:7]
	v_mfma_f32_16x16x32_bf16 v[0:3], v[156:159], v[204:207], v[0:3]
	v_mfma_f32_16x16x32_bf16 v[28:31], v[152:155], v[184:187], v[28:31]
	v_mfma_f32_16x16x32_bf16 v[24:27], v[160:163], v[184:187], v[24:27]
	v_mfma_f32_16x16x32_bf16 v[20:23], v[152:155], v[192:195], v[20:23]
	v_mfma_f32_16x16x32_bf16 v[16:19], v[160:163], v[192:195], v[16:19]
	v_mfma_f32_16x16x32_bf16 v[12:15], v[152:155], v[200:203], v[12:15]
	v_mfma_f32_16x16x32_bf16 v[8:11], v[160:163], v[200:203], v[8:11]
	v_mfma_f32_16x16x32_bf16 v[4:7], v[152:155], v[208:211], v[4:7]
	v_mfma_f32_16x16x32_bf16 v[0:3], v[160:163], v[208:211], v[0:3]
	s_setprio 0
	s_setprio 1
	v_mfma_f32_16x16x32_bf16 v[92:95], v[164:167], v[180:183], v[92:95]
	v_mfma_f32_16x16x32_bf16 v[88:91], v[172:175], v[180:183], v[88:91]
	v_mfma_f32_16x16x32_bf16 v[84:87], v[164:167], v[188:191], v[84:87]
	v_mfma_f32_16x16x32_bf16 v[80:83], v[172:175], v[188:191], v[80:83]
	v_mfma_f32_16x16x32_bf16 v[60:63], v[164:167], v[196:199], v[60:63]
	v_mfma_f32_16x16x32_bf16 v[48:51], v[172:175], v[196:199], v[48:51]
	v_mfma_f32_16x16x32_bf16 v[36:39], v[164:167], v[204:207], v[36:39]
	v_mfma_f32_16x16x32_bf16 v[32:35], v[172:175], v[204:207], v[32:35]
	v_mfma_f32_16x16x32_bf16 v[92:95], v[168:171], v[184:187], v[92:95]
	v_mfma_f32_16x16x32_bf16 v[88:91], v[176:179], v[184:187], v[88:91]
	v_mfma_f32_16x16x32_bf16 v[84:87], v[168:171], v[192:195], v[84:87]
	v_mfma_f32_16x16x32_bf16 v[80:83], v[176:179], v[192:195], v[80:83]
	v_mfma_f32_16x16x32_bf16 v[60:63], v[168:171], v[200:203], v[60:63]
	v_mfma_f32_16x16x32_bf16 v[48:51], v[176:179], v[200:203], v[48:51]
	v_mfma_f32_16x16x32_bf16 v[36:39], v[168:171], v[208:211], v[36:39]
	s_setprio 2
	s_barrier
	v_mfma_f32_16x16x32_bf16 v[32:35], v[176:179], v[208:211], v[32:35]
	s_setprio 0
	s_add_i32 s97, 0, 0x18000
	v_add_u32_e32 v151, s97, v146
	s_add_i32 vcc_lo, 0, 0x1c000
	ds_read_b128 v[142:145], v151
	ds_read_b128 v[152:155], v151 offset:1024
	ds_read_b128 v[156:159], v151 offset:2048
	ds_read_b128 v[160:163], v151 offset:3072
	v_add_u32_e32 v151, vcc_lo, v146
	ds_read_b128 v[164:167], v151
	ds_read_b128 v[168:171], v151 offset:1024
	ds_read_b128 v[172:175], v151 offset:2048
	ds_read_b128 v[176:179], v151 offset:3072
	s_add_u32 s62, s62, 0x100000
	s_addc_u32 s63, s63, 0
	s_mov_b32 m0, s77
	v_lshl_add_u64 v[220:221], s[62:63], 0, v[134:135]
	ds_read_b128 v[180:183], v150 offset:32768
	ds_read_b128 v[184:187], v150 offset:33792
	ds_read_b128 v[188:191], v150 offset:34816
	ds_read_b128 v[192:195], v150 offset:35840
	ds_read_b128 v[196:199], v150 offset:36864
	ds_read_b128 v[200:203], v150 offset:37888
	ds_read_b128 v[204:207], v150 offset:38912
	ds_read_b128 v[208:211], v150 offset:39936
	global_load_lds_dwordx4 v[220:221], off
	v_lshl_add_u64 v[220:221], s[62:63], 0, v[130:131]
	s_mov_b32 m0, s78
	s_nop 0
	global_load_lds_dwordx4 v[220:221], off
	s_waitcnt vmcnt(8)
	s_waitcnt lgkmcnt(0)
	s_barrier
	s_setprio 1
	s_waitcnt lgkmcnt(0)
	v_mfma_f32_16x16x32_bf16 v[76:79], v[142:145], v[180:183], v[76:79]
	v_mfma_f32_16x16x32_bf16 v[72:75], v[156:159], v[180:183], v[72:75]
	v_mfma_f32_16x16x32_bf16 v[68:71], v[142:145], v[188:191], v[68:71]
	v_mfma_f32_16x16x32_bf16 v[64:67], v[156:159], v[188:191], v[64:67]
	v_mfma_f32_16x16x32_bf16 v[56:59], v[142:145], v[196:199], v[56:59]
	v_mfma_f32_16x16x32_bf16 v[52:55], v[156:159], v[196:199], v[52:55]
	v_mfma_f32_16x16x32_bf16 v[44:47], v[142:145], v[204:207], v[44:47]
	v_mfma_f32_16x16x32_bf16 v[40:43], v[156:159], v[204:207], v[40:43]
	v_mfma_f32_16x16x32_bf16 v[76:79], v[152:155], v[184:187], v[76:79]
	v_mfma_f32_16x16x32_bf16 v[72:75], v[160:163], v[184:187], v[72:75]
	v_mfma_f32_16x16x32_bf16 v[68:71], v[152:155], v[192:195], v[68:71]
	v_mfma_f32_16x16x32_bf16 v[64:67], v[160:163], v[192:195], v[64:67]
	v_mfma_f32_16x16x32_bf16 v[56:59], v[152:155], v[200:203], v[56:59]
	v_mfma_f32_16x16x32_bf16 v[52:55], v[160:163], v[200:203], v[52:55]
	v_mfma_f32_16x16x32_bf16 v[44:47], v[152:155], v[208:211], v[44:47]
	v_mfma_f32_16x16x32_bf16 v[40:43], v[160:163], v[208:211], v[40:43]
	s_setprio 0
	s_setprio 1
	v_mfma_f32_16x16x32_bf16 v[124:127], v[164:167], v[180:183], v[124:127]
	v_mfma_f32_16x16x32_bf16 v[120:123], v[172:175], v[180:183], v[120:123]
	v_mfma_f32_16x16x32_bf16 v[116:119], v[164:167], v[188:191], v[116:119]
	v_mfma_f32_16x16x32_bf16 v[112:115], v[172:175], v[188:191], v[112:115]
	v_mfma_f32_16x16x32_bf16 v[108:111], v[164:167], v[196:199], v[108:111]
	v_mfma_f32_16x16x32_bf16 v[104:107], v[172:175], v[196:199], v[104:107]
	v_mfma_f32_16x16x32_bf16 v[100:103], v[164:167], v[204:207], v[100:103]
	v_mfma_f32_16x16x32_bf16 v[96:99], v[172:175], v[204:207], v[96:99]
	v_mfma_f32_16x16x32_bf16 v[124:127], v[168:171], v[184:187], v[124:127]
	v_mfma_f32_16x16x32_bf16 v[120:123], v[176:179], v[184:187], v[120:123]
	v_mfma_f32_16x16x32_bf16 v[116:119], v[168:171], v[192:195], v[116:119]
	v_mfma_f32_16x16x32_bf16 v[112:115], v[176:179], v[192:195], v[112:115]
	v_mfma_f32_16x16x32_bf16 v[108:111], v[168:171], v[200:203], v[108:111]
	v_mfma_f32_16x16x32_bf16 v[104:107], v[176:179], v[200:203], v[104:107]
	v_mfma_f32_16x16x32_bf16 v[100:103], v[168:171], v[208:211], v[100:103]
	s_setprio 2
	s_barrier
; #define PG8_STAGE(bufoff, gbase, voff) do { _Pragma("unroll") for (int _i = 0; _i < 2; ++_i) \
;         __builtin_amdgcn_global_load_lds((const unsigned*)((const char*)(gbase) + (voff)[_i]), (PG8_LAS unsigned*)(lds + (bufoff) + ldsw + _i * 8192), 16, 0, 0); } while (0)
; #define PG8_LDA(dst, b, h) do { _Pragma("unroll") for (int m = 0; m < 4; ++m) _Pragma("unroll") for (int k = 0; k < 2; ++k) dst[m][k] = *(const PG8_LAS bf16x8*)(lds + PG8_SA(b, h) + aoff + m * 2048 + k * 1024); } while (0)
; #define PG8_MMA(ai, bj, At, Bt) do { __builtin_amdgcn_s_setprio(1); _Pragma("unroll") for (int m = 0; m < 4; ++m) _Pragma("unroll") for (int n = 0; n < 2; ++n) _Pragma("unroll") for (int k = 0; k < 2; ++k) \
;         acc[ai][bj][m][n] = __builtin_amdgcn_mfma_f32_16x16x32_bf16(Bt[n][k], At[m][k], acc[ai][bj][m][n], 0, 0, 0); __builtin_amdgcn_s_setprio(0); } while (0)
; #define PG8_WAIT_V(n) asm volatile("s_waitcnt vmcnt(" #n ")" ::: "memory")
; #define PG8_WAIT_L(n) asm volatile("s_waitcnt lgkmcnt(" #n ")" ::: "memory")
; #define PG8_BAR __builtin_amdgcn_s_barrier()
; #define PG8_SCHED __builtin_amdgcn_sched_barrier(0)
; template <class Epi, class Sched, bool ALIGN_EPI = false, bool SP2 = false>
; __device__ __forceinline__ void gemm_phase(PG8_LAS unsigned char* lds, const Gemm g, const Sched& S, const Epi& E, const int wv  ) {
;     ...
;             PG8_WAIT_V(8); PG8_WAIT_L(0); PG8_BAR; PG8_MMA(0, 0, At, B0); PG8_MMA(0, 1, At, B1); PG8_BAR; PG8_SCHED;
;             PG8_LDA(At, 1, 1); PG8_STAGE(PG8_SB(1, 0), b3, voffB); PG8_STAGE(PG8_SB(1, 1), b3 + hstepB, voffB); PG8_STAGE(PG8_SA(1, 0), a3, voffA);
;             PG8_WAIT_V(8); PG8_WAIT_L(0); PG8_BAR; PG8_MMA(1, 0, At, B0); PG8_MMA(1, 1, At, B1); PG8_BAR; PG8_SCHED;
;     ...
;         if constexpr (ALIGN_EPI) { if (wr == 0) PG8_BAR; }
	v_mfma_f32_16x16x32_bf16 v[96:99], v[176:179], v[208:211], v[96:99]
	s_setprio 0
	s_add_i32 s62, s97, s73
	v_lshl_add_u64 v[212:213], v[212:213], 0, s[8:9]
	s_mov_b32 m0, s62
	ds_read_b128 v[180:183], v150 offset:49152
	ds_read_b128 v[184:187], v150 offset:50176
	ds_read_b128 v[188:191], v150 offset:51200
	ds_read_b128 v[192:195], v150 offset:52224
	ds_read_b128 v[196:199], v150 offset:53248
	ds_read_b128 v[200:203], v150 offset:54272
	ds_read_b128 v[204:207], v150 offset:55296
	ds_read_b128 v[208:211], v150 offset:56320
	global_load_lds_dwordx4 v[212:213], off
	s_add_i32 m0, s62, 0x2000
	s_add_u32 s60, s60, 0x100080
	v_lshl_add_u64 v[212:213], v[214:215], 0, s[8:9]
	s_addc_u32 s61, s61, 0
	s_add_i32 s62, vcc_lo, s73
	global_load_lds_dwordx4 v[212:213], off
	v_lshl_add_u64 v[212:213], s[60:61], 0, v[132:133]
	s_mov_b32 m0, s62
	s_nop 0
	global_load_lds_dwordx4 v[212:213], off
	v_lshl_add_u64 v[212:213], s[60:61], 0, v[128:129]
	s_add_i32 m0, s62, 0x2000
	s_nop 0
	global_load_lds_dwordx4 v[212:213], off
	v_lshl_add_u64 v[212:213], v[216:217], 0, s[8:9]
	s_mov_b32 m0, s80
	s_nop 0
	global_load_lds_dwordx4 v[212:213], off
	v_lshl_add_u64 v[212:213], v[218:219], 0, s[8:9]
	s_mov_b32 m0, s81
	s_nop 0
	global_load_lds_dwordx4 v[212:213], off
	s_waitcnt vmcnt(8)
	s_waitcnt lgkmcnt(0)
	s_barrier
	s_setprio 1
	s_waitcnt lgkmcnt(0)
	v_mfma_f32_16x16x32_bf16 v[28:31], v[142:145], v[180:183], v[28:31]
	v_mfma_f32_16x16x32_bf16 v[24:27], v[156:159], v[180:183], v[24:27]
	v_mfma_f32_16x16x32_bf16 v[20:23], v[142:145], v[188:191], v[20:23]
	v_mfma_f32_16x16x32_bf16 v[16:19], v[156:159], v[188:191], v[16:19]
	v_mfma_f32_16x16x32_bf16 v[12:15], v[142:145], v[196:199], v[12:15]
	v_mfma_f32_16x16x32_bf16 v[8:11], v[156:159], v[196:199], v[8:11]
	v_mfma_f32_16x16x32_bf16 v[4:7], v[142:145], v[204:207], v[4:7]
	v_mfma_f32_16x16x32_bf16 v[0:3], v[156:159], v[204:207], v[0:3]
	v_mfma_f32_16x16x32_bf16 v[28:31], v[152:155], v[184:187], v[28:31]
	v_mfma_f32_16x16x32_bf16 v[24:27], v[160:163], v[184:187], v[24:27]
	v_mfma_f32_16x16x32_bf16 v[20:23], v[152:155], v[192:195], v[20:23]
	v_mfma_f32_16x16x32_bf16 v[16:19], v[160:163], v[192:195], v[16:19]
	v_mfma_f32_16x16x32_bf16 v[12:15], v[152:155], v[200:203], v[12:15]
	v_mfma_f32_16x16x32_bf16 v[8:11], v[160:163], v[200:203], v[8:11]
	v_mfma_f32_16x16x32_bf16 v[4:7], v[152:155], v[208:211], v[4:7]
	v_mfma_f32_16x16x32_bf16 v[0:3], v[160:163], v[208:211], v[0:3]
	s_setprio 0
	s_setprio 1
	v_mfma_f32_16x16x32_bf16 v[92:95], v[164:167], v[180:183], v[92:95]
	v_mfma_f32_16x16x32_bf16 v[88:91], v[172:175], v[180:183], v[88:91]
	v_mfma_f32_16x16x32_bf16 v[84:87], v[164:167], v[188:191], v[84:87]
	v_mfma_f32_16x16x32_bf16 v[80:83], v[172:175], v[188:191], v[80:83]
	v_mfma_f32_16x16x32_bf16 v[60:63], v[164:167], v[196:199], v[60:63]
	v_mfma_f32_16x16x32_bf16 v[48:51], v[172:175], v[196:199], v[48:51]
	v_mfma_f32_16x16x32_bf16 v[36:39], v[164:167], v[204:207], v[36:39]
	v_mfma_f32_16x16x32_bf16 v[32:35], v[172:175], v[204:207], v[32:35]
	v_mfma_f32_16x16x32_bf16 v[92:95], v[168:171], v[184:187], v[92:95]
	v_mfma_f32_16x16x32_bf16 v[88:91], v[176:179], v[184:187], v[88:91]
	v_mfma_f32_16x16x32_bf16 v[84:87], v[168:171], v[192:195], v[84:87]
	v_mfma_f32_16x16x32_bf16 v[80:83], v[176:179], v[192:195], v[80:83]
	v_mfma_f32_16x16x32_bf16 v[60:63], v[168:171], v[200:203], v[60:63]
	v_mfma_f32_16x16x32_bf16 v[48:51], v[176:179], v[200:203], v[48:51]
	v_mfma_f32_16x16x32_bf16 v[36:39], v[168:171], v[208:211], v[36:39]
	s_setprio 2
	s_barrier
	v_mfma_f32_16x16x32_bf16 v[32:35], v[176:179], v[208:211], v[32:35]
	s_setprio 0
	s_add_i32 s96, s96, 2
	s_add_u32 s58, s58, 0x100
	s_addc_u32 s59, s59, 0
	s_add_u32 s94, s94, 0x100
	s_addc_u32 s95, s95, 0
	s_cmp_gt_u32 s96, 61
	s_cbranch_scc0 .LBB0_871
	s_and_b64 vcc, exec, s[10:11]
	s_cbranch_vccz .LBB0_874
	s_barrier

; #define PG8_STAGE(bufoff, gbase, voff) do { _Pragma("unroll") for (int _i = 0; _i < 2; ++_i) \
;         __builtin_amdgcn_global_load_lds((const unsigned*)((const char*)(gbase) + (voff)[_i]), (PG8_LAS unsigned*)(lds + (bufoff) + ldsw + _i * 8192), 16, 0, 0); } while (0)
; #define PG8_LDA(dst, b, h) do { _Pragma("unroll") for (int m = 0; m < 4; ++m) _Pragma("unroll") for (int k = 0; k < 2; ++k) dst[m][k] = *(const PG8_LAS bf16x8*)(lds + PG8_SA(b, h) + aoff + m * 2048 + k * 1024); } while (0)
; #define PG8_LDB(dst, b, h) do { _Pragma("unroll") for (int n = 0; n < 2; ++n) _Pragma("unroll") for (int k = 0; k < 2; ++k) dst[n][k] = *(const PG8_LAS bf16x8*)(lds + PG8_SB(b, h) + boff + n * 2048 + k * 1024); } while (0)
; #define PG8_MMA(ai, bj, At, Bt) do { __builtin_amdgcn_s_setprio(1); _Pragma("unroll") for (int m = 0; m < 4; ++m) _Pragma("unroll") for (int n = 0; n < 2; ++n) _Pragma("unroll") for (int k = 0; k < 2; ++k) \
;         acc[ai][bj][m][n] = __builtin_amdgcn_mfma_f32_16x16x32_bf16(Bt[n][k], At[m][k], acc[ai][bj][m][n], 0, 0, 0); __builtin_amdgcn_s_setprio(0); } while (0)
; #define PG8_WAIT_V(n) asm volatile("s_waitcnt vmcnt(" #n ")" ::: "memory")
; #define PG8_WAIT_L(n) asm volatile("s_waitcnt lgkmcnt(" #n ")" ::: "memory")
; #define PG8_BAR __builtin_amdgcn_s_barrier()
; template <class Epi, class Sched, bool ALIGN_EPI = false, bool SP2 = false>
; __device__ __forceinline__ void gemm_phase(PG8_LAS unsigned char* lds, const Gemm g, const Sched& S, const Epi& E, const int wv  ) {
;     ...
;         for (int t = 0; t < nt; t += 2) {
;             const bool last = (t == nt - 2);
;             const char* a1 = cA + (size_t)(t + 1) * kstep;
;             const char* a2 = last ? nA : cA + (size_t)(t + 2) * kstep; const char* b2 = last ? nB : cB + (size_t)(t + 2) * kstep;
;             const char* a3 = a2 + kstep; const char* b3 = b2 + kstep;
;             if (last && has_next) S.a_ready(nxt);
;             if constexpr (SP2) {
;             PG8_LDB(B0, 0, 0); PG8_LDB(B1, 0, 1); PG8_SCHED; PG8_LDA(At, 0, 0); PG8_STAGE(PG8_SA(1, 1), a1 + hstepA, voffA);
;             PG8_WAIT_V(8); PG8_WAIT_L(0); PG8_BAR; PG8_MMA(0, 0, At, B0); PG8_MMA(0, 1, At, B1); PG8_BAR; PG8_SCHED;
;             PG8_LDA(At, 0, 1); PG8_STAGE(PG8_SB(0, 0), b2, voffB); PG8_STAGE(PG8_SB(0, 1), b2 + hstepB, voffB); PG8_STAGE(PG8_SA(0, 0), a2, voffA);
.LBB0_892:
	ds_read_b128 v[142:145], v148
	ds_read_b128 v[152:155], v148 offset:1024
	ds_read_b128 v[156:159], v148 offset:2048
	ds_read_b128 v[160:163], v148 offset:3072
	ds_read_b128 v[164:167], v149
	ds_read_b128 v[168:171], v149 offset:1024
	ds_read_b128 v[172:175], v149 offset:2048
	ds_read_b128 v[176:179], v149 offset:3072
	s_add_u32 s60, s58, 0xfff00080
	s_addc_u32 s61, s59, -1
	s_cmp_eq_u32 s92, 60
	s_cselect_b32 s63, s49, s61
	s_cselect_b32 s62, s86, s60
	s_cselect_b32 s61, s47, s91
	s_cselect_b32 s60, s87, s90
	v_lshl_add_u64 v[212:213], s[58:59], 0, v[138:139]
	s_add_i32 m0, s71, 0xc000
	ds_read_b128 v[180:183], v150
	ds_read_b128 v[184:187], v150 offset:1024
	ds_read_b128 v[188:191], v150 offset:2048
	ds_read_b128 v[192:195], v150 offset:3072
	ds_read_b128 v[196:199], v150 offset:4096
	ds_read_b128 v[200:203], v150 offset:5120
	ds_read_b128 v[204:207], v150 offset:6144
	ds_read_b128 v[208:211], v150 offset:7168
	global_load_lds_dwordx4 v[212:213], off
	v_lshl_add_u64 v[212:213], s[58:59], 0, v[140:141]
	s_add_i32 m0, s71, 0xe000
	s_nop 0
	global_load_lds_dwordx4 v[212:213], off
	s_waitcnt vmcnt(8)
	s_waitcnt lgkmcnt(0)
	s_barrier
	s_setprio 1
	s_waitcnt lgkmcnt(0)
	v_mfma_f32_16x16x32_bf16 v[76:79], v[142:145], v[180:183], v[76:79]
	v_mfma_f32_16x16x32_bf16 v[72:75], v[156:159], v[180:183], v[72:75]
	v_mfma_f32_16x16x32_bf16 v[68:71], v[142:145], v[188:191], v[68:71]
	v_mfma_f32_16x16x32_bf16 v[64:67], v[156:159], v[188:191], v[64:67]
	v_mfma_f32_16x16x32_bf16 v[56:59], v[142:145], v[196:199], v[56:59]
	v_mfma_f32_16x16x32_bf16 v[52:55], v[156:159], v[196:199], v[52:55]
	v_mfma_f32_16x16x32_bf16 v[44:47], v[142:145], v[204:207], v[44:47]
	v_mfma_f32_16x16x32_bf16 v[40:43], v[156:159], v[204:207], v[40:43]
	v_mfma_f32_16x16x32_bf16 v[76:79], v[152:155], v[184:187], v[76:79]
	v_mfma_f32_16x16x32_bf16 v[72:75], v[160:163], v[184:187], v[72:75]
	v_mfma_f32_16x16x32_bf16 v[68:71], v[152:155], v[192:195], v[68:71]
	v_mfma_f32_16x16x32_bf16 v[64:67], v[160:163], v[192:195], v[64:67]
	v_mfma_f32_16x16x32_bf16 v[56:59], v[152:155], v[200:203], v[56:59]
	v_mfma_f32_16x16x32_bf16 v[52:55], v[160:163], v[200:203], v[52:55]
	v_mfma_f32_16x16x32_bf16 v[44:47], v[152:155], v[208:211], v[44:47]
	v_mfma_f32_16x16x32_bf16 v[40:43], v[160:163], v[208:211], v[40:43]
	s_setprio 0
	s_setprio 1
	v_mfma_f32_16x16x32_bf16 v[124:127], v[164:167], v[180:183], v[124:127]
	v_mfma_f32_16x16x32_bf16 v[120:123], v[172:175], v[180:183], v[120:123]
	v_mfma_f32_16x16x32_bf16 v[116:119], v[164:167], v[188:191], v[116:119]
	v_mfma_f32_16x16x32_bf16 v[112:115], v[172:175], v[188:191], v[112:115]
	v_mfma_f32_16x16x32_bf16 v[108:111], v[164:167], v[196:199], v[108:111]
	v_mfma_f32_16x16x32_bf16 v[104:107], v[172:175], v[196:199], v[104:107]
	v_mfma_f32_16x16x32_bf16 v[100:103], v[164:167], v[204:207], v[100:103]
	v_mfma_f32_16x16x32_bf16 v[96:99], v[172:175], v[204:207], v[96:99]
	v_mfma_f32_16x16x32_bf16 v[124:127], v[168:171], v[184:187], v[124:127]
	v_mfma_f32_16x16x32_bf16 v[120:123], v[176:179], v[184:187], v[120:123]
	v_mfma_f32_16x16x32_bf16 v[116:119], v[168:171], v[192:195], v[116:119]
	v_mfma_f32_16x16x32_bf16 v[112:115], v[176:179], v[192:195], v[112:115]
	v_mfma_f32_16x16x32_bf16 v[108:111], v[168:171], v[200:203], v[108:111]
	v_mfma_f32_16x16x32_bf16 v[104:107], v[176:179], v[200:203], v[104:107]
	v_mfma_f32_16x16x32_bf16 v[100:103], v[168:171], v[208:211], v[100:103]
	s_setprio 2
	s_barrier
	v_mfma_f32_16x16x32_bf16 v[96:99], v[176:179], v[208:211], v[96:99]
	s_setprio 0
	s_add_i32 s93, s84, s69
	v_lshl_add_u64 v[212:213], s[60:61], 0, v[132:133]
	s_mov_b32 m0, s93
	ds_read_b128 v[180:183], v150 offset:16384
	ds_read_b128 v[184:187], v150 offset:17408
	ds_read_b128 v[188:191], v150 offset:18432
	ds_read_b128 v[192:195], v150 offset:19456
	ds_read_b128 v[196:199], v150 offset:20480
	ds_read_b128 v[200:203], v150 offset:21504
	ds_read_b128 v[204:207], v150 offset:22528
	ds_read_b128 v[208:211], v150 offset:23552
	global_load_lds_dwordx4 v[212:213], off
	s_add_i32 m0, s93, 0x2000
	s_add_u32 s94, s60, 0x100000
	v_lshl_add_u64 v[214:215], s[60:61], 0, v[128:129]
	s_addc_u32 s95, s61, 0
	s_add_i32 s93, s85, s69
	global_load_lds_dwordx4 v[214:215], off
	v_lshl_add_u64 v[216:217], s[94:95], 0, v[132:133]
	s_mov_b32 m0, s93
	v_lshl_add_u64 v[218:219], s[62:63], 0, v[130:131]
	global_load_lds_dwordx4 v[216:217], off
	v_lshl_add_u64 v[216:217], s[94:95], 0, v[128:129]
	s_add_i32 m0, s93, 0x2000
	s_nop 0
	global_load_lds_dwordx4 v[216:217], off
	v_lshl_add_u64 v[216:217], s[62:63], 0, v[134:135]
	s_mov_b32 m0, s71
	s_nop 0
	global_load_lds_dwordx4 v[216:217], off
	s_mov_b32 m0, s72
	s_nop 0
	global_load_lds_dwordx4 v[218:219], off
	s_waitcnt vmcnt(8)
	s_waitcnt lgkmcnt(0)
	s_barrier
; #define PG8_STAGE(bufoff, gbase, voff) do { _Pragma("unroll") for (int _i = 0; _i < 2; ++_i) \
;         __builtin_amdgcn_global_load_lds((const unsigned*)((const char*)(gbase) + (voff)[_i]), (PG8_LAS unsigned*)(lds + (bufoff) + ldsw + _i * 8192), 16, 0, 0); } while (0)
; #define PG8_LDA(dst, b, h) do { _Pragma("unroll") for (int m = 0; m < 4; ++m) _Pragma("unroll") for (int k = 0; k < 2; ++k) dst[m][k] = *(const PG8_LAS bf16x8*)(lds + PG8_SA(b, h) + aoff + m * 2048 + k * 1024); } while (0)
; #define PG8_LDB(dst, b, h) do { _Pragma("unroll") for (int n = 0; n < 2; ++n) _Pragma("unroll") for (int k = 0; k < 2; ++k) dst[n][k] = *(const PG8_LAS bf16x8*)(lds + PG8_SB(b, h) + boff + n * 2048 + k * 1024); } while (0)
; #define PG8_MMA(ai, bj, At, Bt) do { __builtin_amdgcn_s_setprio(1); _Pragma("unroll") for (int m = 0; m < 4; ++m) _Pragma("unroll") for (int n = 0; n < 2; ++n) _Pragma("unroll") for (int k = 0; k < 2; ++k) \
;         acc[ai][bj][m][n] = __builtin_amdgcn_mfma_f32_16x16x32_bf16(Bt[n][k], At[m][k], acc[ai][bj][m][n], 0, 0, 0); __builtin_amdgcn_s_setprio(0); } while (0)
; #define PG8_WAIT_V(n) asm volatile("s_waitcnt vmcnt(" #n ")" ::: "memory")
; #define PG8_WAIT_L(n) asm volatile("s_waitcnt lgkmcnt(" #n ")" ::: "memory")
; #define PG8_BAR __builtin_amdgcn_s_barrier()
; #define PG8_SCHED __builtin_amdgcn_sched_barrier(0)
; template <class Epi, class Sched, bool ALIGN_EPI = false, bool SP2 = false>
; __device__ __forceinline__ void gemm_phase(PG8_LAS unsigned char* lds, const Gemm g, const Sched& S, const Epi& E, const int wv  ) {
;     ...
;             PG8_WAIT_V(8); PG8_WAIT_L(0); PG8_BAR; PG8_MMA(1, 0, At, B0); PG8_MMA(1, 1, At, B1); PG8_BAR; PG8_SCHED;
;             PG8_LDB(B0, 1, 0); PG8_LDB(B1, 1, 1); PG8_SCHED; PG8_LDA(At, 1, 0); PG8_STAGE(PG8_SA(0, 1), a2 + hstepA, voffA);
;             PG8_WAIT_V(8); PG8_WAIT_L(0); PG8_BAR; PG8_MMA(0, 0, At, B0); PG8_MMA(0, 1, At, B1); PG8_BAR; PG8_SCHED;
	s_setprio 1
	s_waitcnt lgkmcnt(0)
	v_mfma_f32_16x16x32_bf16 v[28:31], v[142:145], v[180:183], v[28:31]
	v_mfma_f32_16x16x32_bf16 v[24:27], v[156:159], v[180:183], v[24:27]
	v_mfma_f32_16x16x32_bf16 v[20:23], v[142:145], v[188:191], v[20:23]
	v_mfma_f32_16x16x32_bf16 v[16:19], v[156:159], v[188:191], v[16:19]
	v_mfma_f32_16x16x32_bf16 v[12:15], v[142:145], v[196:199], v[12:15]
	v_mfma_f32_16x16x32_bf16 v[8:11], v[156:159], v[196:199], v[8:11]
	v_mfma_f32_16x16x32_bf16 v[4:7], v[142:145], v[204:207], v[4:7]
	v_mfma_f32_16x16x32_bf16 v[0:3], v[156:159], v[204:207], v[0:3]
	v_mfma_f32_16x16x32_bf16 v[28:31], v[152:155], v[184:187], v[28:31]
	v_mfma_f32_16x16x32_bf16 v[24:27], v[160:163], v[184:187], v[24:27]
	v_mfma_f32_16x16x32_bf16 v[20:23], v[152:155], v[192:195], v[20:23]
	v_mfma_f32_16x16x32_bf16 v[16:19], v[160:163], v[192:195], v[16:19]
	v_mfma_f32_16x16x32_bf16 v[12:15], v[152:155], v[200:203], v[12:15]
	v_mfma_f32_16x16x32_bf16 v[8:11], v[160:163], v[200:203], v[8:11]
	v_mfma_f32_16x16x32_bf16 v[4:7], v[152:155], v[208:211], v[4:7]
	v_mfma_f32_16x16x32_bf16 v[0:3], v[160:163], v[208:211], v[0:3]
	s_setprio 0
	s_setprio 1
	v_mfma_f32_16x16x32_bf16 v[92:95], v[164:167], v[180:183], v[92:95]
	v_mfma_f32_16x16x32_bf16 v[88:91], v[172:175], v[180:183], v[88:91]
	v_mfma_f32_16x16x32_bf16 v[84:87], v[164:167], v[188:191], v[84:87]
	v_mfma_f32_16x16x32_bf16 v[80:83], v[172:175], v[188:191], v[80:83]
	v_mfma_f32_16x16x32_bf16 v[60:63], v[164:167], v[196:199], v[60:63]
	v_mfma_f32_16x16x32_bf16 v[48:51], v[172:175], v[196:199], v[48:51]
	v_mfma_f32_16x16x32_bf16 v[36:39], v[164:167], v[204:207], v[36:39]
	v_mfma_f32_16x16x32_bf16 v[32:35], v[172:175], v[204:207], v[32:35]
	v_mfma_f32_16x16x32_bf16 v[92:95], v[168:171], v[184:187], v[92:95]
	v_mfma_f32_16x16x32_bf16 v[88:91], v[176:179], v[184:187], v[88:91]
	v_mfma_f32_16x16x32_bf16 v[84:87], v[168:171], v[192:195], v[84:87]
	v_mfma_f32_16x16x32_bf16 v[80:83], v[176:179], v[192:195], v[80:83]
	v_mfma_f32_16x16x32_bf16 v[60:63], v[168:171], v[200:203], v[60:63]
	v_mfma_f32_16x16x32_bf16 v[48:51], v[176:179], v[200:203], v[48:51]
	v_mfma_f32_16x16x32_bf16 v[36:39], v[168:171], v[208:211], v[36:39]
	s_setprio 2
	s_barrier
	v_mfma_f32_16x16x32_bf16 v[32:35], v[176:179], v[208:211], v[32:35]
	s_setprio 0
	s_add_i32 s93, 0, 0x18000
	v_add_u32_e32 v151, s93, v146
	s_add_i32 s94, 0, 0x1c000
	ds_read_b128 v[142:145], v151
	ds_read_b128 v[152:155], v151 offset:1024
	ds_read_b128 v[156:159], v151 offset:2048
	ds_read_b128 v[160:163], v151 offset:3072
	v_add_u32_e32 v151, s94, v146
	ds_read_b128 v[164:167], v151
	ds_read_b128 v[168:171], v151 offset:1024
	ds_read_b128 v[172:175], v151 offset:2048
	ds_read_b128 v[176:179], v151 offset:3072
	s_add_u32 s62, s62, 0x100000
	s_addc_u32 s63, s63, 0
	s_mov_b32 m0, s73
	v_lshl_add_u64 v[220:221], s[62:63], 0, v[134:135]
	ds_read_b128 v[180:183], v150 offset:32768
	ds_read_b128 v[184:187], v150 offset:33792
	ds_read_b128 v[188:191], v150 offset:34816
	ds_read_b128 v[192:195], v150 offset:35840
	ds_read_b128 v[196:199], v150 offset:36864
	ds_read_b128 v[200:203], v150 offset:37888
	ds_read_b128 v[204:207], v150 offset:38912
	ds_read_b128 v[208:211], v150 offset:39936
	global_load_lds_dwordx4 v[220:221], off
	v_lshl_add_u64 v[220:221], s[62:63], 0, v[130:131]
	s_mov_b32 m0, s74
	s_nop 0
	global_load_lds_dwordx4 v[220:221], off
	s_waitcnt vmcnt(8)
	s_waitcnt lgkmcnt(0)
	s_barrier
	s_setprio 1
	s_waitcnt lgkmcnt(0)
	v_mfma_f32_16x16x32_bf16 v[76:79], v[142:145], v[180:183], v[76:79]
	v_mfma_f32_16x16x32_bf16 v[72:75], v[156:159], v[180:183], v[72:75]
	v_mfma_f32_16x16x32_bf16 v[68:71], v[142:145], v[188:191], v[68:71]
	v_mfma_f32_16x16x32_bf16 v[64:67], v[156:159], v[188:191], v[64:67]
	v_mfma_f32_16x16x32_bf16 v[56:59], v[142:145], v[196:199], v[56:59]
	v_mfma_f32_16x16x32_bf16 v[52:55], v[156:159], v[196:199], v[52:55]
	v_mfma_f32_16x16x32_bf16 v[44:47], v[142:145], v[204:207], v[44:47]
	v_mfma_f32_16x16x32_bf16 v[40:43], v[156:159], v[204:207], v[40:43]
	v_mfma_f32_16x16x32_bf16 v[76:79], v[152:155], v[184:187], v[76:79]
	v_mfma_f32_16x16x32_bf16 v[72:75], v[160:163], v[184:187], v[72:75]
	v_mfma_f32_16x16x32_bf16 v[68:71], v[152:155], v[192:195], v[68:71]
	v_mfma_f32_16x16x32_bf16 v[64:67], v[160:163], v[192:195], v[64:67]
	v_mfma_f32_16x16x32_bf16 v[56:59], v[152:155], v[200:203], v[56:59]
	v_mfma_f32_16x16x32_bf16 v[52:55], v[160:163], v[200:203], v[52:55]
	v_mfma_f32_16x16x32_bf16 v[44:47], v[152:155], v[208:211], v[44:47]
	v_mfma_f32_16x16x32_bf16 v[40:43], v[160:163], v[208:211], v[40:43]
	s_setprio 0
	s_setprio 1
	v_mfma_f32_16x16x32_bf16 v[124:127], v[164:167], v[180:183], v[124:127]
	v_mfma_f32_16x16x32_bf16 v[120:123], v[172:175], v[180:183], v[120:123]
	v_mfma_f32_16x16x32_bf16 v[116:119], v[164:167], v[188:191], v[116:119]
	v_mfma_f32_16x16x32_bf16 v[112:115], v[172:175], v[188:191], v[112:115]
	v_mfma_f32_16x16x32_bf16 v[108:111], v[164:167], v[196:199], v[108:111]
	v_mfma_f32_16x16x32_bf16 v[104:107], v[172:175], v[196:199], v[104:107]
	v_mfma_f32_16x16x32_bf16 v[100:103], v[164:167], v[204:207], v[100:103]
	v_mfma_f32_16x16x32_bf16 v[96:99], v[172:175], v[204:207], v[96:99]
	v_mfma_f32_16x16x32_bf16 v[124:127], v[168:171], v[184:187], v[124:127]
	v_mfma_f32_16x16x32_bf16 v[120:123], v[176:179], v[184:187], v[120:123]
	v_mfma_f32_16x16x32_bf16 v[116:119], v[168:171], v[192:195], v[116:119]
	v_mfma_f32_16x16x32_bf16 v[112:115], v[176:179], v[192:195], v[112:115]
	v_mfma_f32_16x16x32_bf16 v[108:111], v[168:171], v[200:203], v[108:111]
	v_mfma_f32_16x16x32_bf16 v[104:107], v[176:179], v[200:203], v[104:107]
	v_mfma_f32_16x16x32_bf16 v[100:103], v[168:171], v[208:211], v[100:103]
	s_setprio 2
	s_barrier
; #define PG8_STAGE(bufoff, gbase, voff) do { _Pragma("unroll") for (int _i = 0; _i < 2; ++_i) \
;         __builtin_amdgcn_global_load_lds((const unsigned*)((const char*)(gbase) + (voff)[_i]), (PG8_LAS unsigned*)(lds + (bufoff) + ldsw + _i * 8192), 16, 0, 0); } while (0)
; #define PG8_LDA(dst, b, h) do { _Pragma("unroll") for (int m = 0; m < 4; ++m) _Pragma("unroll") for (int k = 0; k < 2; ++k) dst[m][k] = *(const PG8_LAS bf16x8*)(lds + PG8_SA(b, h) + aoff + m * 2048 + k * 1024); } while (0)
; #define PG8_MMA(ai, bj, At, Bt) do { __builtin_amdgcn_s_setprio(1); _Pragma("unroll") for (int m = 0; m < 4; ++m) _Pragma("unroll") for (int n = 0; n < 2; ++n) _Pragma("unroll") for (int k = 0; k < 2; ++k) \
;         acc[ai][bj][m][n] = __builtin_amdgcn_mfma_f32_16x16x32_bf16(Bt[n][k], At[m][k], acc[ai][bj][m][n], 0, 0, 0); __builtin_amdgcn_s_setprio(0); } while (0)
; #define PG8_WAIT_V(n) asm volatile("s_waitcnt vmcnt(" #n ")" ::: "memory")
; #define PG8_WAIT_L(n) asm volatile("s_waitcnt lgkmcnt(" #n ")" ::: "memory")
; #define PG8_BAR __builtin_amdgcn_s_barrier()
; #define PG8_SCHED __builtin_amdgcn_sched_barrier(0)
; template <class Epi, class Sched, bool ALIGN_EPI = false, bool SP2 = false>
; __device__ __forceinline__ void gemm_phase(PG8_LAS unsigned char* lds, const Gemm g, const Sched& S, const Epi& E, const int wv  ) {
;     ...
;             PG8_WAIT_V(8); PG8_WAIT_L(0); PG8_BAR; PG8_MMA(0, 0, At, B0); PG8_MMA(0, 1, At, B1); PG8_BAR; PG8_SCHED;
;             PG8_LDA(At, 1, 1); PG8_STAGE(PG8_SB(1, 0), b3, voffB); PG8_STAGE(PG8_SB(1, 1), b3 + hstepB, voffB); PG8_STAGE(PG8_SA(1, 0), a3, voffA);
;             PG8_WAIT_V(8); PG8_WAIT_L(0); PG8_BAR; PG8_MMA(1, 0, At, B0); PG8_MMA(1, 1, At, B1); PG8_BAR; PG8_SCHED;
;     ...
;         if constexpr (ALIGN_EPI) { if (wr == 0) PG8_BAR; }
	v_mfma_f32_16x16x32_bf16 v[96:99], v[176:179], v[208:211], v[96:99]
	s_setprio 0
	s_add_i32 s62, s93, s69
	v_lshl_add_u64 v[212:213], v[212:213], 0, s[8:9]
	s_mov_b32 m0, s62
	ds_read_b128 v[180:183], v150 offset:49152
	ds_read_b128 v[184:187], v150 offset:50176
	ds_read_b128 v[188:191], v150 offset:51200
	ds_read_b128 v[192:195], v150 offset:52224
	ds_read_b128 v[196:199], v150 offset:53248
	ds_read_b128 v[200:203], v150 offset:54272
	ds_read_b128 v[204:207], v150 offset:55296
	ds_read_b128 v[208:211], v150 offset:56320
	global_load_lds_dwordx4 v[212:213], off
	s_add_i32 m0, s62, 0x2000
	s_add_u32 s60, s60, 0x100080
	v_lshl_add_u64 v[212:213], v[214:215], 0, s[8:9]
	s_addc_u32 s61, s61, 0
	s_add_i32 s62, s94, s69
	global_load_lds_dwordx4 v[212:213], off
	v_lshl_add_u64 v[212:213], s[60:61], 0, v[132:133]
	s_mov_b32 m0, s62
	s_nop 0
	global_load_lds_dwordx4 v[212:213], off
	v_lshl_add_u64 v[212:213], s[60:61], 0, v[128:129]
	s_add_i32 m0, s62, 0x2000
	s_nop 0
	global_load_lds_dwordx4 v[212:213], off
	v_lshl_add_u64 v[212:213], v[216:217], 0, s[8:9]
	s_mov_b32 m0, s81
	s_nop 0
	global_load_lds_dwordx4 v[212:213], off
	v_lshl_add_u64 v[212:213], v[218:219], 0, s[8:9]
	s_mov_b32 m0, s82
	s_nop 0
	global_load_lds_dwordx4 v[212:213], off
	s_waitcnt vmcnt(8)
	s_waitcnt lgkmcnt(0)
	s_barrier
	s_setprio 1
	s_waitcnt lgkmcnt(0)
	v_mfma_f32_16x16x32_bf16 v[28:31], v[142:145], v[180:183], v[28:31]
	v_mfma_f32_16x16x32_bf16 v[24:27], v[156:159], v[180:183], v[24:27]
	v_mfma_f32_16x16x32_bf16 v[20:23], v[142:145], v[188:191], v[20:23]
	v_mfma_f32_16x16x32_bf16 v[16:19], v[156:159], v[188:191], v[16:19]
	v_mfma_f32_16x16x32_bf16 v[12:15], v[142:145], v[196:199], v[12:15]
	v_mfma_f32_16x16x32_bf16 v[8:11], v[156:159], v[196:199], v[8:11]
	v_mfma_f32_16x16x32_bf16 v[4:7], v[142:145], v[204:207], v[4:7]
	v_mfma_f32_16x16x32_bf16 v[0:3], v[156:159], v[204:207], v[0:3]
	v_mfma_f32_16x16x32_bf16 v[28:31], v[152:155], v[184:187], v[28:31]
	v_mfma_f32_16x16x32_bf16 v[24:27], v[160:163], v[184:187], v[24:27]
	v_mfma_f32_16x16x32_bf16 v[20:23], v[152:155], v[192:195], v[20:23]
	v_mfma_f32_16x16x32_bf16 v[16:19], v[160:163], v[192:195], v[16:19]
	v_mfma_f32_16x16x32_bf16 v[12:15], v[152:155], v[200:203], v[12:15]
	v_mfma_f32_16x16x32_bf16 v[8:11], v[160:163], v[200:203], v[8:11]
	v_mfma_f32_16x16x32_bf16 v[4:7], v[152:155], v[208:211], v[4:7]
	v_mfma_f32_16x16x32_bf16 v[0:3], v[160:163], v[208:211], v[0:3]
	s_setprio 0
	s_setprio 1
	v_mfma_f32_16x16x32_bf16 v[92:95], v[164:167], v[180:183], v[92:95]
	v_mfma_f32_16x16x32_bf16 v[88:91], v[172:175], v[180:183], v[88:91]
	v_mfma_f32_16x16x32_bf16 v[84:87], v[164:167], v[188:191], v[84:87]
	v_mfma_f32_16x16x32_bf16 v[80:83], v[172:175], v[188:191], v[80:83]
	v_mfma_f32_16x16x32_bf16 v[60:63], v[164:167], v[196:199], v[60:63]
	v_mfma_f32_16x16x32_bf16 v[48:51], v[172:175], v[196:199], v[48:51]
	v_mfma_f32_16x16x32_bf16 v[36:39], v[164:167], v[204:207], v[36:39]
	v_mfma_f32_16x16x32_bf16 v[32:35], v[172:175], v[204:207], v[32:35]
	v_mfma_f32_16x16x32_bf16 v[92:95], v[168:171], v[184:187], v[92:95]
	v_mfma_f32_16x16x32_bf16 v[88:91], v[176:179], v[184:187], v[88:91]
	v_mfma_f32_16x16x32_bf16 v[84:87], v[168:171], v[192:195], v[84:87]
	v_mfma_f32_16x16x32_bf16 v[80:83], v[176:179], v[192:195], v[80:83]
	v_mfma_f32_16x16x32_bf16 v[60:63], v[168:171], v[200:203], v[60:63]
	v_mfma_f32_16x16x32_bf16 v[48:51], v[176:179], v[200:203], v[48:51]
	v_mfma_f32_16x16x32_bf16 v[36:39], v[168:171], v[208:211], v[36:39]
	s_setprio 2
	s_barrier
	v_mfma_f32_16x16x32_bf16 v[32:35], v[176:179], v[208:211], v[32:35]
	s_setprio 0
	s_add_i32 s92, s92, 2
	s_add_u32 s58, s58, 0x100
	s_addc_u32 s59, s59, 0
	s_add_u32 s90, s90, 0x100
	s_addc_u32 s91, s91, 0
	s_cmp_gt_u32 s92, 61
	s_cbranch_scc0 .LBB0_892
	s_and_b64 vcc, exec, s[10:11]
	s_cbranch_vccz .LBB0_895
	s_barrier

; #define PG8_STAGE(bufoff, gbase, voff) do { _Pragma("unroll") for (int _i = 0; _i < 2; ++_i) \
;         __builtin_amdgcn_global_load_lds((const unsigned*)((const char*)(gbase) + (voff)[_i]), (PG8_LAS unsigned*)(lds + (bufoff) + ldsw + _i * 8192), 16, 0, 0); } while (0)
; #define PG8_LDA(dst, b, h) do { _Pragma("unroll") for (int m = 0; m < 4; ++m) _Pragma("unroll") for (int k = 0; k < 2; ++k) dst[m][k] = *(const PG8_LAS bf16x8*)(lds + PG8_SA(b, h) + aoff + m * 2048 + k * 1024); } while (0)
; #define PG8_LDB(dst, b, h) do { _Pragma("unroll") for (int n = 0; n < 2; ++n) _Pragma("unroll") for (int k = 0; k < 2; ++k) dst[n][k] = *(const PG8_LAS bf16x8*)(lds + PG8_SB(b, h) + boff + n * 2048 + k * 1024); } while (0)
; #define PG8_MMA(ai, bj, At, Bt) do { __builtin_amdgcn_s_setprio(1); _Pragma("unroll") for (int m = 0; m < 4; ++m) _Pragma("unroll") for (int n = 0; n < 2; ++n) _Pragma("unroll") for (int k = 0; k < 2; ++k) \
;         acc[ai][bj][m][n] = __builtin_amdgcn_mfma_f32_16x16x32_bf16(Bt[n][k], At[m][k], acc[ai][bj][m][n], 0, 0, 0); __builtin_amdgcn_s_setprio(0); } while (0)
; #define PG8_WAIT_V(n) asm volatile("s_waitcnt vmcnt(" #n ")" ::: "memory")
; #define PG8_WAIT_L(n) asm volatile("s_waitcnt lgkmcnt(" #n ")" ::: "memory")
; #define PG8_BAR __builtin_amdgcn_s_barrier()
; template <class Epi, class Sched, bool ALIGN_EPI = false, bool SP2 = false>
; __device__ __forceinline__ void gemm_phase(PG8_LAS unsigned char* lds, const Gemm g, const Sched& S, const Epi& E, const int wv  ) {
;     ...
;         for (int t = 0; t < nt; t += 2) {
;             const bool last = (t == nt - 2);
;             const char* a1 = cA + (size_t)(t + 1) * kstep;
;             const char* a2 = last ? nA : cA + (size_t)(t + 2) * kstep; const char* b2 = last ? nB : cB + (size_t)(t + 2) * kstep;
;             const char* a3 = a2 + kstep; const char* b3 = b2 + kstep;
;             if (last && has_next) S.a_ready(nxt);
;             if constexpr (SP2) {
;             PG8_LDB(B0, 0, 0); PG8_LDB(B1, 0, 1); PG8_SCHED; PG8_LDA(At, 0, 0); PG8_STAGE(PG8_SA(1, 1), a1 + hstepA, voffA);
;             PG8_WAIT_V(8); PG8_WAIT_L(0); PG8_BAR; PG8_MMA(0, 0, At, B0); PG8_MMA(0, 1, At, B1); PG8_BAR; PG8_SCHED;
;             PG8_LDA(At, 0, 1); PG8_STAGE(PG8_SB(0, 0), b2, voffB); PG8_STAGE(PG8_SB(0, 1), b2 + hstepB, voffB); PG8_STAGE(PG8_SA(0, 0), a2, voffA);
.LBB0_1049:
	ds_read_b128 v[146:149], v152
	ds_read_b128 v[156:159], v152 offset:1024
	ds_read_b128 v[160:163], v152 offset:2048
	ds_read_b128 v[164:167], v152 offset:3072
	ds_read_b128 v[168:171], v153
	ds_read_b128 v[172:175], v153 offset:1024
	ds_read_b128 v[176:179], v153 offset:2048
	ds_read_b128 v[180:183], v153 offset:3072
	s_add_u32 s60, s58, 0xfffc0080
	s_addc_u32 s61, s59, -1
	s_cmp_eq_u32 s87, 12
	s_cselect_b32 s63, s51, s61
	s_cselect_b32 s62, s83, s60
	s_cselect_b32 s61, s49, s86
	s_cselect_b32 s60, s84, s85
	v_lshl_add_u64 v[216:217], s[58:59], 0, v[138:139]
	s_add_i32 m0, s68, 0xc000
	ds_read_b128 v[184:187], v154
	ds_read_b128 v[188:191], v154 offset:1024
	ds_read_b128 v[192:195], v154 offset:2048
	ds_read_b128 v[196:199], v154 offset:3072
	ds_read_b128 v[200:203], v154 offset:4096
	ds_read_b128 v[204:207], v154 offset:5120
	ds_read_b128 v[208:211], v154 offset:6144
	ds_read_b128 v[212:215], v154 offset:7168
	global_load_lds_dwordx4 v[216:217], off
	v_lshl_add_u64 v[216:217], s[58:59], 0, v[140:141]
	s_add_i32 m0, s68, 0xe000
	s_nop 0
	global_load_lds_dwordx4 v[216:217], off
	s_waitcnt vmcnt(8)
	s_waitcnt lgkmcnt(0)
	s_barrier
	s_setprio 1
	s_waitcnt lgkmcnt(0)
	v_mfma_f32_16x16x32_bf16 v[76:79], v[146:149], v[184:187], v[76:79]
	v_mfma_f32_16x16x32_bf16 v[72:75], v[160:163], v[184:187], v[72:75]
	v_mfma_f32_16x16x32_bf16 v[68:71], v[146:149], v[192:195], v[68:71]
	v_mfma_f32_16x16x32_bf16 v[64:67], v[160:163], v[192:195], v[64:67]
	v_mfma_f32_16x16x32_bf16 v[56:59], v[146:149], v[200:203], v[56:59]
	v_mfma_f32_16x16x32_bf16 v[52:55], v[160:163], v[200:203], v[52:55]
	v_mfma_f32_16x16x32_bf16 v[44:47], v[146:149], v[208:211], v[44:47]
	v_mfma_f32_16x16x32_bf16 v[40:43], v[160:163], v[208:211], v[40:43]
	v_mfma_f32_16x16x32_bf16 v[76:79], v[156:159], v[188:191], v[76:79]
	v_mfma_f32_16x16x32_bf16 v[72:75], v[164:167], v[188:191], v[72:75]
	v_mfma_f32_16x16x32_bf16 v[68:71], v[156:159], v[196:199], v[68:71]
	v_mfma_f32_16x16x32_bf16 v[64:67], v[164:167], v[196:199], v[64:67]
	v_mfma_f32_16x16x32_bf16 v[56:59], v[156:159], v[204:207], v[56:59]
	v_mfma_f32_16x16x32_bf16 v[52:55], v[164:167], v[204:207], v[52:55]
	v_mfma_f32_16x16x32_bf16 v[44:47], v[156:159], v[212:215], v[44:47]
	v_mfma_f32_16x16x32_bf16 v[40:43], v[164:167], v[212:215], v[40:43]
	s_setprio 0
	s_setprio 1
	v_mfma_f32_16x16x32_bf16 v[124:127], v[168:171], v[184:187], v[124:127]
	v_mfma_f32_16x16x32_bf16 v[120:123], v[176:179], v[184:187], v[120:123]
	v_mfma_f32_16x16x32_bf16 v[116:119], v[168:171], v[192:195], v[116:119]
	v_mfma_f32_16x16x32_bf16 v[112:115], v[176:179], v[192:195], v[112:115]
	v_mfma_f32_16x16x32_bf16 v[108:111], v[168:171], v[200:203], v[108:111]
	v_mfma_f32_16x16x32_bf16 v[104:107], v[176:179], v[200:203], v[104:107]
	v_mfma_f32_16x16x32_bf16 v[100:103], v[168:171], v[208:211], v[100:103]
	v_mfma_f32_16x16x32_bf16 v[96:99], v[176:179], v[208:211], v[96:99]
	v_mfma_f32_16x16x32_bf16 v[124:127], v[172:175], v[188:191], v[124:127]
	v_mfma_f32_16x16x32_bf16 v[120:123], v[180:183], v[188:191], v[120:123]
	v_mfma_f32_16x16x32_bf16 v[116:119], v[172:175], v[196:199], v[116:119]
	v_mfma_f32_16x16x32_bf16 v[112:115], v[180:183], v[196:199], v[112:115]
	v_mfma_f32_16x16x32_bf16 v[108:111], v[172:175], v[204:207], v[108:111]
	v_mfma_f32_16x16x32_bf16 v[104:107], v[180:183], v[204:207], v[104:107]
	v_mfma_f32_16x16x32_bf16 v[100:103], v[172:175], v[212:215], v[100:103]
	s_setprio 2
	s_barrier
	v_mfma_f32_16x16x32_bf16 v[96:99], v[180:183], v[212:215], v[96:99]
	s_setprio 0
	s_add_i32 s90, s77, s67
	v_lshl_add_u64 v[216:217], s[60:61], 0, v[130:131]
	s_mov_b32 m0, s90
	ds_read_b128 v[184:187], v154 offset:16384
	ds_read_b128 v[188:191], v154 offset:17408
	ds_read_b128 v[192:195], v154 offset:18432
	ds_read_b128 v[196:199], v154 offset:19456
	ds_read_b128 v[200:203], v154 offset:20480
	ds_read_b128 v[204:207], v154 offset:21504
	ds_read_b128 v[208:211], v154 offset:22528
	ds_read_b128 v[212:215], v154 offset:23552
	global_load_lds_dwordx4 v[216:217], off
	s_add_i32 m0, s90, 0x2000
	s_add_u32 s90, s60, 0x40000
	v_lshl_add_u64 v[218:219], s[60:61], 0, v[134:135]
	s_addc_u32 s91, s61, 0
	s_add_i32 s92, s78, s67
	global_load_lds_dwordx4 v[218:219], off
	v_lshl_add_u64 v[220:221], s[90:91], 0, v[130:131]
	s_mov_b32 m0, s92
	v_lshl_add_u64 v[222:223], s[62:63], 0, v[132:133]
	global_load_lds_dwordx4 v[220:221], off
	v_lshl_add_u64 v[220:221], s[90:91], 0, v[134:135]
	s_add_i32 m0, s92, 0x2000
	s_nop 0
	global_load_lds_dwordx4 v[220:221], off
	v_lshl_add_u64 v[220:221], s[62:63], 0, v[128:129]
	s_mov_b32 m0, s68
	s_nop 0
	global_load_lds_dwordx4 v[220:221], off
	s_mov_b32 m0, s69
	s_nop 0
	global_load_lds_dwordx4 v[222:223], off
	s_waitcnt vmcnt(8)
	s_waitcnt lgkmcnt(0)
	s_barrier
; #define PG8_STAGE(bufoff, gbase, voff) do { _Pragma("unroll") for (int _i = 0; _i < 2; ++_i) \
;         __builtin_amdgcn_global_load_lds((const unsigned*)((const char*)(gbase) + (voff)[_i]), (PG8_LAS unsigned*)(lds + (bufoff) + ldsw + _i * 8192), 16, 0, 0); } while (0)
; #define PG8_LDA(dst, b, h) do { _Pragma("unroll") for (int m = 0; m < 4; ++m) _Pragma("unroll") for (int k = 0; k < 2; ++k) dst[m][k] = *(const PG8_LAS bf16x8*)(lds + PG8_SA(b, h) + aoff + m * 2048 + k * 1024); } while (0)
; #define PG8_LDB(dst, b, h) do { _Pragma("unroll") for (int n = 0; n < 2; ++n) _Pragma("unroll") for (int k = 0; k < 2; ++k) dst[n][k] = *(const PG8_LAS bf16x8*)(lds + PG8_SB(b, h) + boff + n * 2048 + k * 1024); } while (0)
; #define PG8_MMA(ai, bj, At, Bt) do { __builtin_amdgcn_s_setprio(1); _Pragma("unroll") for (int m = 0; m < 4; ++m) _Pragma("unroll") for (int n = 0; n < 2; ++n) _Pragma("unroll") for (int k = 0; k < 2; ++k) \
;         acc[ai][bj][m][n] = __builtin_amdgcn_mfma_f32_16x16x32_bf16(Bt[n][k], At[m][k], acc[ai][bj][m][n], 0, 0, 0); __builtin_amdgcn_s_setprio(0); } while (0)
; #define PG8_WAIT_V(n) asm volatile("s_waitcnt vmcnt(" #n ")" ::: "memory")
; #define PG8_WAIT_L(n) asm volatile("s_waitcnt lgkmcnt(" #n ")" ::: "memory")
; #define PG8_BAR __builtin_amdgcn_s_barrier()
; #define PG8_SCHED __builtin_amdgcn_sched_barrier(0)
; template <class Epi, class Sched, bool ALIGN_EPI = false, bool SP2 = false>
; __device__ __forceinline__ void gemm_phase(PG8_LAS unsigned char* lds, const Gemm g, const Sched& S, const Epi& E, const int wv  ) {
;     ...
;             PG8_WAIT_V(8); PG8_WAIT_L(0); PG8_BAR; PG8_MMA(1, 0, At, B0); PG8_MMA(1, 1, At, B1); PG8_BAR; PG8_SCHED;
;             PG8_LDB(B0, 1, 0); PG8_LDB(B1, 1, 1); PG8_SCHED; PG8_LDA(At, 1, 0); PG8_STAGE(PG8_SA(0, 1), a2 + hstepA, voffA);
;             PG8_WAIT_V(8); PG8_WAIT_L(0); PG8_BAR; PG8_MMA(0, 0, At, B0); PG8_MMA(0, 1, At, B1); PG8_BAR; PG8_SCHED;
	s_setprio 1
	s_waitcnt lgkmcnt(0)
	v_mfma_f32_16x16x32_bf16 v[28:31], v[146:149], v[184:187], v[28:31]
	v_mfma_f32_16x16x32_bf16 v[24:27], v[160:163], v[184:187], v[24:27]
	v_mfma_f32_16x16x32_bf16 v[20:23], v[146:149], v[192:195], v[20:23]
	v_mfma_f32_16x16x32_bf16 v[16:19], v[160:163], v[192:195], v[16:19]
	v_mfma_f32_16x16x32_bf16 v[12:15], v[146:149], v[200:203], v[12:15]
	v_mfma_f32_16x16x32_bf16 v[8:11], v[160:163], v[200:203], v[8:11]
	v_mfma_f32_16x16x32_bf16 v[4:7], v[146:149], v[208:211], v[4:7]
	v_mfma_f32_16x16x32_bf16 v[0:3], v[160:163], v[208:211], v[0:3]
	v_mfma_f32_16x16x32_bf16 v[28:31], v[156:159], v[188:191], v[28:31]
	v_mfma_f32_16x16x32_bf16 v[24:27], v[164:167], v[188:191], v[24:27]
	v_mfma_f32_16x16x32_bf16 v[20:23], v[156:159], v[196:199], v[20:23]
	v_mfma_f32_16x16x32_bf16 v[16:19], v[164:167], v[196:199], v[16:19]
	v_mfma_f32_16x16x32_bf16 v[12:15], v[156:159], v[204:207], v[12:15]
	v_mfma_f32_16x16x32_bf16 v[8:11], v[164:167], v[204:207], v[8:11]
	v_mfma_f32_16x16x32_bf16 v[4:7], v[156:159], v[212:215], v[4:7]
	v_mfma_f32_16x16x32_bf16 v[0:3], v[164:167], v[212:215], v[0:3]
	s_setprio 0
	s_setprio 1
	v_mfma_f32_16x16x32_bf16 v[92:95], v[168:171], v[184:187], v[92:95]
	v_mfma_f32_16x16x32_bf16 v[88:91], v[176:179], v[184:187], v[88:91]
	v_mfma_f32_16x16x32_bf16 v[84:87], v[168:171], v[192:195], v[84:87]
	v_mfma_f32_16x16x32_bf16 v[80:83], v[176:179], v[192:195], v[80:83]
	v_mfma_f32_16x16x32_bf16 v[60:63], v[168:171], v[200:203], v[60:63]
	v_mfma_f32_16x16x32_bf16 v[48:51], v[176:179], v[200:203], v[48:51]
	v_mfma_f32_16x16x32_bf16 v[36:39], v[168:171], v[208:211], v[36:39]
	v_mfma_f32_16x16x32_bf16 v[32:35], v[176:179], v[208:211], v[32:35]
	v_mfma_f32_16x16x32_bf16 v[92:95], v[172:175], v[188:191], v[92:95]
	v_mfma_f32_16x16x32_bf16 v[88:91], v[180:183], v[188:191], v[88:91]
	v_mfma_f32_16x16x32_bf16 v[84:87], v[172:175], v[196:199], v[84:87]
	v_mfma_f32_16x16x32_bf16 v[80:83], v[180:183], v[196:199], v[80:83]
	v_mfma_f32_16x16x32_bf16 v[60:63], v[172:175], v[204:207], v[60:63]
	v_mfma_f32_16x16x32_bf16 v[48:51], v[180:183], v[204:207], v[48:51]
	v_mfma_f32_16x16x32_bf16 v[36:39], v[172:175], v[212:215], v[36:39]
	s_setprio 2
	s_barrier
	v_mfma_f32_16x16x32_bf16 v[32:35], v[180:183], v[212:215], v[32:35]
	s_setprio 0
	s_add_i32 s90, 0, 0x18000
	v_add_u32_e32 v155, s90, v150
	s_add_i32 s91, 0, 0x1c000
	ds_read_b128 v[146:149], v155
	ds_read_b128 v[156:159], v155 offset:1024
	ds_read_b128 v[160:163], v155 offset:2048
	ds_read_b128 v[164:167], v155 offset:3072
	v_add_u32_e32 v155, s91, v150
	ds_read_b128 v[168:171], v155
	ds_read_b128 v[172:175], v155 offset:1024
	ds_read_b128 v[176:179], v155 offset:2048
	ds_read_b128 v[180:183], v155 offset:3072
	s_add_u32 s62, s62, 0x40000
	s_addc_u32 s63, s63, 0
	s_mov_b32 m0, s70
	v_lshl_add_u64 v[224:225], s[62:63], 0, v[128:129]
	ds_read_b128 v[184:187], v154 offset:32768
	ds_read_b128 v[188:191], v154 offset:33792
	ds_read_b128 v[192:195], v154 offset:34816
	ds_read_b128 v[196:199], v154 offset:35840
	ds_read_b128 v[200:203], v154 offset:36864
	ds_read_b128 v[204:207], v154 offset:37888
	ds_read_b128 v[208:211], v154 offset:38912
	ds_read_b128 v[212:215], v154 offset:39936
	global_load_lds_dwordx4 v[224:225], off
	v_lshl_add_u64 v[224:225], s[62:63], 0, v[132:133]
	s_mov_b32 m0, s71
	s_nop 0
	global_load_lds_dwordx4 v[224:225], off
	s_waitcnt vmcnt(8)
	s_waitcnt lgkmcnt(0)
	s_barrier
	s_setprio 1
	s_waitcnt lgkmcnt(0)
	v_mfma_f32_16x16x32_bf16 v[76:79], v[146:149], v[184:187], v[76:79]
	v_mfma_f32_16x16x32_bf16 v[72:75], v[160:163], v[184:187], v[72:75]
	v_mfma_f32_16x16x32_bf16 v[68:71], v[146:149], v[192:195], v[68:71]
	v_mfma_f32_16x16x32_bf16 v[64:67], v[160:163], v[192:195], v[64:67]
	v_mfma_f32_16x16x32_bf16 v[56:59], v[146:149], v[200:203], v[56:59]
	v_mfma_f32_16x16x32_bf16 v[52:55], v[160:163], v[200:203], v[52:55]
	v_mfma_f32_16x16x32_bf16 v[44:47], v[146:149], v[208:211], v[44:47]
	v_mfma_f32_16x16x32_bf16 v[40:43], v[160:163], v[208:211], v[40:43]
	v_mfma_f32_16x16x32_bf16 v[76:79], v[156:159], v[188:191], v[76:79]
	v_mfma_f32_16x16x32_bf16 v[72:75], v[164:167], v[188:191], v[72:75]
	v_mfma_f32_16x16x32_bf16 v[68:71], v[156:159], v[196:199], v[68:71]
	v_mfma_f32_16x16x32_bf16 v[64:67], v[164:167], v[196:199], v[64:67]
	v_mfma_f32_16x16x32_bf16 v[56:59], v[156:159], v[204:207], v[56:59]
	v_mfma_f32_16x16x32_bf16 v[52:55], v[164:167], v[204:207], v[52:55]
	v_mfma_f32_16x16x32_bf16 v[44:47], v[156:159], v[212:215], v[44:47]
	v_mfma_f32_16x16x32_bf16 v[40:43], v[164:167], v[212:215], v[40:43]
	s_setprio 0
	s_setprio 1
	v_mfma_f32_16x16x32_bf16 v[124:127], v[168:171], v[184:187], v[124:127]
	v_mfma_f32_16x16x32_bf16 v[120:123], v[176:179], v[184:187], v[120:123]
	v_mfma_f32_16x16x32_bf16 v[116:119], v[168:171], v[192:195], v[116:119]
	v_mfma_f32_16x16x32_bf16 v[112:115], v[176:179], v[192:195], v[112:115]
	v_mfma_f32_16x16x32_bf16 v[108:111], v[168:171], v[200:203], v[108:111]
	v_mfma_f32_16x16x32_bf16 v[104:107], v[176:179], v[200:203], v[104:107]
	v_mfma_f32_16x16x32_bf16 v[100:103], v[168:171], v[208:211], v[100:103]
	v_mfma_f32_16x16x32_bf16 v[96:99], v[176:179], v[208:211], v[96:99]
	v_mfma_f32_16x16x32_bf16 v[124:127], v[172:175], v[188:191], v[124:127]
	v_mfma_f32_16x16x32_bf16 v[120:123], v[180:183], v[188:191], v[120:123]
	v_mfma_f32_16x16x32_bf16 v[116:119], v[172:175], v[196:199], v[116:119]
	v_mfma_f32_16x16x32_bf16 v[112:115], v[180:183], v[196:199], v[112:115]
	v_mfma_f32_16x16x32_bf16 v[108:111], v[172:175], v[204:207], v[108:111]
	v_mfma_f32_16x16x32_bf16 v[104:107], v[180:183], v[204:207], v[104:107]
	v_mfma_f32_16x16x32_bf16 v[100:103], v[172:175], v[212:215], v[100:103]
	s_setprio 2
	s_barrier
; #define PG8_STAGE(bufoff, gbase, voff) do { _Pragma("unroll") for (int _i = 0; _i < 2; ++_i) \
;         __builtin_amdgcn_global_load_lds((const unsigned*)((const char*)(gbase) + (voff)[_i]), (PG8_LAS unsigned*)(lds + (bufoff) + ldsw + _i * 8192), 16, 0, 0); } while (0)
; #define PG8_LDA(dst, b, h) do { _Pragma("unroll") for (int m = 0; m < 4; ++m) _Pragma("unroll") for (int k = 0; k < 2; ++k) dst[m][k] = *(const PG8_LAS bf16x8*)(lds + PG8_SA(b, h) + aoff + m * 2048 + k * 1024); } while (0)
; #define PG8_MMA(ai, bj, At, Bt) do { __builtin_amdgcn_s_setprio(1); _Pragma("unroll") for (int m = 0; m < 4; ++m) _Pragma("unroll") for (int n = 0; n < 2; ++n) _Pragma("unroll") for (int k = 0; k < 2; ++k) \
;         acc[ai][bj][m][n] = __builtin_amdgcn_mfma_f32_16x16x32_bf16(Bt[n][k], At[m][k], acc[ai][bj][m][n], 0, 0, 0); __builtin_amdgcn_s_setprio(0); } while (0)
; #define PG8_WAIT_V(n) asm volatile("s_waitcnt vmcnt(" #n ")" ::: "memory")
; #define PG8_WAIT_L(n) asm volatile("s_waitcnt lgkmcnt(" #n ")" ::: "memory")
; #define PG8_BAR __builtin_amdgcn_s_barrier()
; #define PG8_SCHED __builtin_amdgcn_sched_barrier(0)
; template <class Epi, class Sched, bool ALIGN_EPI = false, bool SP2 = false>
; __device__ __forceinline__ void gemm_phase(PG8_LAS unsigned char* lds, const Gemm g, const Sched& S, const Epi& E, const int wv  ) {
;     ...
;         for (int t = 0; t < nt; t += 2) {
;             const bool last = (t == nt - 2);
;     ...
;             PG8_WAIT_V(8); PG8_WAIT_L(0); PG8_BAR; PG8_MMA(0, 0, At, B0); PG8_MMA(0, 1, At, B1); PG8_BAR; PG8_SCHED;
;             PG8_LDA(At, 1, 1); PG8_STAGE(PG8_SB(1, 0), b3, voffB); PG8_STAGE(PG8_SB(1, 1), b3 + hstepB, voffB); PG8_STAGE(PG8_SA(1, 0), a3, voffA);
;             PG8_WAIT_V(8); PG8_WAIT_L(0); PG8_BAR; PG8_MMA(1, 0, At, B0); PG8_MMA(1, 1, At, B1); PG8_BAR; PG8_SCHED;
	v_mfma_f32_16x16x32_bf16 v[96:99], v[180:183], v[212:215], v[96:99]
	s_setprio 0
	s_add_i32 s62, s90, s67
	v_lshl_add_u64 v[216:217], v[216:217], 0, s[10:11]
	s_mov_b32 m0, s62
	ds_read_b128 v[184:187], v154 offset:49152
	ds_read_b128 v[188:191], v154 offset:50176
	ds_read_b128 v[192:195], v154 offset:51200
	ds_read_b128 v[196:199], v154 offset:52224
	ds_read_b128 v[200:203], v154 offset:53248
	ds_read_b128 v[204:207], v154 offset:54272
	ds_read_b128 v[208:211], v154 offset:55296
	ds_read_b128 v[212:215], v154 offset:56320
	global_load_lds_dwordx4 v[216:217], off
	s_add_i32 m0, s62, 0x2000
	s_add_u32 s60, s60, 0x40080
	v_lshl_add_u64 v[216:217], v[218:219], 0, s[10:11]
	s_addc_u32 s61, s61, 0
	s_add_i32 s62, s91, s67
	global_load_lds_dwordx4 v[216:217], off
	v_lshl_add_u64 v[216:217], s[60:61], 0, v[130:131]
	s_mov_b32 m0, s62
	s_nop 0
	global_load_lds_dwordx4 v[216:217], off
	v_lshl_add_u64 v[216:217], s[60:61], 0, v[134:135]
	s_add_i32 m0, s62, 0x2000
	s_nop 0
	global_load_lds_dwordx4 v[216:217], off
	v_lshl_add_u64 v[216:217], v[220:221], 0, s[10:11]
	s_mov_b32 m0, s74
	s_nop 0
	global_load_lds_dwordx4 v[216:217], off
	v_lshl_add_u64 v[216:217], v[222:223], 0, s[10:11]
	s_mov_b32 m0, s75
	s_nop 0
	global_load_lds_dwordx4 v[216:217], off
	s_waitcnt vmcnt(8)
	s_waitcnt lgkmcnt(0)
	s_barrier
	s_setprio 1
	s_waitcnt lgkmcnt(0)
	v_mfma_f32_16x16x32_bf16 v[28:31], v[146:149], v[184:187], v[28:31]
	v_mfma_f32_16x16x32_bf16 v[24:27], v[160:163], v[184:187], v[24:27]
	v_mfma_f32_16x16x32_bf16 v[20:23], v[146:149], v[192:195], v[20:23]
	v_mfma_f32_16x16x32_bf16 v[16:19], v[160:163], v[192:195], v[16:19]
	v_mfma_f32_16x16x32_bf16 v[12:15], v[146:149], v[200:203], v[12:15]
	v_mfma_f32_16x16x32_bf16 v[8:11], v[160:163], v[200:203], v[8:11]
	v_mfma_f32_16x16x32_bf16 v[4:7], v[146:149], v[208:211], v[4:7]
	v_mfma_f32_16x16x32_bf16 v[0:3], v[160:163], v[208:211], v[0:3]
	v_mfma_f32_16x16x32_bf16 v[28:31], v[156:159], v[188:191], v[28:31]
	v_mfma_f32_16x16x32_bf16 v[24:27], v[164:167], v[188:191], v[24:27]
	v_mfma_f32_16x16x32_bf16 v[20:23], v[156:159], v[196:199], v[20:23]
	v_mfma_f32_16x16x32_bf16 v[16:19], v[164:167], v[196:199], v[16:19]
	v_mfma_f32_16x16x32_bf16 v[12:15], v[156:159], v[204:207], v[12:15]
	v_mfma_f32_16x16x32_bf16 v[8:11], v[164:167], v[204:207], v[8:11]
	v_mfma_f32_16x16x32_bf16 v[4:7], v[156:159], v[212:215], v[4:7]
	v_mfma_f32_16x16x32_bf16 v[0:3], v[164:167], v[212:215], v[0:3]
	s_setprio 0
	s_setprio 1
	v_mfma_f32_16x16x32_bf16 v[92:95], v[168:171], v[184:187], v[92:95]
	v_mfma_f32_16x16x32_bf16 v[88:91], v[176:179], v[184:187], v[88:91]
	v_mfma_f32_16x16x32_bf16 v[84:87], v[168:171], v[192:195], v[84:87]
	v_mfma_f32_16x16x32_bf16 v[80:83], v[176:179], v[192:195], v[80:83]
	v_mfma_f32_16x16x32_bf16 v[60:63], v[168:171], v[200:203], v[60:63]
	v_mfma_f32_16x16x32_bf16 v[48:51], v[176:179], v[200:203], v[48:51]
	v_mfma_f32_16x16x32_bf16 v[36:39], v[168:171], v[208:211], v[36:39]
	v_mfma_f32_16x16x32_bf16 v[32:35], v[176:179], v[208:211], v[32:35]
	v_mfma_f32_16x16x32_bf16 v[92:95], v[172:175], v[188:191], v[92:95]
	v_mfma_f32_16x16x32_bf16 v[88:91], v[180:183], v[188:191], v[88:91]
	v_mfma_f32_16x16x32_bf16 v[84:87], v[172:175], v[196:199], v[84:87]
	v_mfma_f32_16x16x32_bf16 v[80:83], v[180:183], v[196:199], v[80:83]
	v_mfma_f32_16x16x32_bf16 v[60:63], v[172:175], v[204:207], v[60:63]
	v_mfma_f32_16x16x32_bf16 v[48:51], v[180:183], v[204:207], v[48:51]
	v_mfma_f32_16x16x32_bf16 v[36:39], v[172:175], v[212:215], v[36:39]
	s_setprio 2
	s_barrier
	v_mfma_f32_16x16x32_bf16 v[32:35], v[180:183], v[212:215], v[32:35]
	s_setprio 0
	s_add_i32 s87, s87, 2
	s_add_u32 s58, s58, 0x100
	s_addc_u32 s59, s59, 0
	s_add_u32 s85, s85, 0x100
	s_addc_u32 s86, s86, 0
	s_cmp_gt_u32 s87, 13
	s_cbranch_scc0 .LBB0_1049
	s_and_b64 vcc, exec, s[12:13]
	s_cbranch_vccz .LBB0_1052
	s_barrier

; #define PG8_STAGE(bufoff, gbase, voff) do { _Pragma("unroll") for (int _i = 0; _i < 2; ++_i) \
;         __builtin_amdgcn_global_load_lds((const unsigned*)((const char*)(gbase) + (voff)[_i]), (PG8_LAS unsigned*)(lds + (bufoff) + ldsw + _i * 8192), 16, 0, 0); } while (0)
; #define PG8_LDA(dst, b, h) do { _Pragma("unroll") for (int m = 0; m < 4; ++m) _Pragma("unroll") for (int k = 0; k < 2; ++k) dst[m][k] = *(const PG8_LAS bf16x8*)(lds + PG8_SA(b, h) + aoff + m * 2048 + k * 1024); } while (0)
; #define PG8_LDB(dst, b, h) do { _Pragma("unroll") for (int n = 0; n < 2; ++n) _Pragma("unroll") for (int k = 0; k < 2; ++k) dst[n][k] = *(const PG8_LAS bf16x8*)(lds + PG8_SB(b, h) + boff + n * 2048 + k * 1024); } while (0)
; #define PG8_MMA(ai, bj, At, Bt) do { __builtin_amdgcn_s_setprio(1); _Pragma("unroll") for (int m = 0; m < 4; ++m) _Pragma("unroll") for (int n = 0; n < 2; ++n) _Pragma("unroll") for (int k = 0; k < 2; ++k) \
;         acc[ai][bj][m][n] = __builtin_amdgcn_mfma_f32_16x16x32_bf16(Bt[n][k], At[m][k], acc[ai][bj][m][n], 0, 0, 0); __builtin_amdgcn_s_setprio(0); } while (0)
; #define PG8_WAIT_V(n) asm volatile("s_waitcnt vmcnt(" #n ")" ::: "memory")
; #define PG8_WAIT_L(n) asm volatile("s_waitcnt lgkmcnt(" #n ")" ::: "memory")
; template <class Epi, class Sched, bool ALIGN_EPI = false, bool SP2 = false>
; __device__ __forceinline__ void gemm_phase(PG8_LAS unsigned char* lds, const Gemm g, const Sched& S, const Epi& E, const int wv  ) {
;     ...
;             const bool last = (t == nt - 2);
;             const char* a1 = cA + (size_t)(t + 1) * kstep;
;             const char* a2 = last ? nA : cA + (size_t)(t + 2) * kstep; const char* b2 = last ? nB : cB + (size_t)(t + 2) * kstep;
;             const char* a3 = a2 + kstep; const char* b3 = b2 + kstep;
;             if (last && has_next) S.a_ready(nxt);
;             if constexpr (SP2) {
;             PG8_LDB(B0, 0, 0); PG8_LDB(B1, 0, 1); PG8_SCHED; PG8_LDA(At, 0, 0); PG8_STAGE(PG8_SA(1, 1), a1 + hstepA, voffA);
;             PG8_WAIT_V(8); PG8_WAIT_L(0); PG8_BAR; PG8_MMA(0, 0, At, B0); PG8_MMA(0, 1, At, B1); PG8_BAR; PG8_SCHED;
;             PG8_LDA(At, 0, 1); PG8_STAGE(PG8_SB(0, 0), b2, voffB); PG8_STAGE(PG8_SB(0, 1), b2 + hstepB, voffB); PG8_STAGE(PG8_SA(0, 0), a2, voffA);
;             PG8_WAIT_V(8); PG8_WAIT_L(0); PG8_BAR; PG8_MMA(1, 0, At, B0); PG8_MMA(1, 1, At, B1); PG8_BAR; PG8_SCHED;
.LBB0_1187:
	ds_read_b128 v[44:47], v196
	ds_read_b128 v[48:51], v196 offset:1024
	ds_read_b128 v[52:55], v196 offset:2048
	ds_read_b128 v[56:59], v196 offset:3072
	ds_read_b128 v[60:63], v197
	ds_read_b128 v[68:71], v197 offset:1024
	ds_read_b128 v[72:75], v197 offset:2048
	ds_read_b128 v[76:79], v197 offset:3072
	s_add_u32 s68, s66, 0xfff00080
	s_addc_u32 s69, s67, -1
	s_cmp_eq_u32 s94, 60
	s_cselect_b32 s71, s57, s69
	s_cselect_b32 s70, s63, s68
	s_cselect_b32 s69, s55, s93
	s_cselect_b32 s68, s65, s92
	v_lshl_add_u64 v[224:225], s[66:67], 0, v[172:173]
	s_add_i32 m0, s75, 0xc000
	ds_read_b128 v[180:183], v198
	ds_read_b128 v[184:187], v198 offset:1024
	ds_read_b128 v[200:203], v198 offset:2048
	ds_read_b128 v[204:207], v198 offset:3072
	ds_read_b128 v[208:211], v198 offset:4096
	ds_read_b128 v[212:215], v198 offset:5120
	ds_read_b128 v[216:219], v198 offset:6144
	ds_read_b128 v[220:223], v198 offset:7168
	global_load_lds_dwordx4 v[224:225], off
	v_lshl_add_u64 v[224:225], s[66:67], 0, v[174:175]
	s_add_i32 m0, s75, 0xe000
	s_nop 0
	global_load_lds_dwordx4 v[224:225], off
	s_waitcnt vmcnt(8)
	s_waitcnt lgkmcnt(0)
	s_barrier
	s_setprio 1
	s_waitcnt lgkmcnt(0)
	v_mfma_f32_16x16x32_bf16 v[104:107], v[44:47], v[180:183], v[104:107]
	v_mfma_f32_16x16x32_bf16 v[100:103], v[52:55], v[180:183], v[100:103]
	v_mfma_f32_16x16x32_bf16 v[156:159], v[44:47], v[200:203], v[156:159]
	v_mfma_f32_16x16x32_bf16 v[148:151], v[52:55], v[200:203], v[148:151]
	v_mfma_f32_16x16x32_bf16 v[140:143], v[44:47], v[208:211], v[140:143]
	v_mfma_f32_16x16x32_bf16 v[132:135], v[52:55], v[208:211], v[132:135]
	v_mfma_f32_16x16x32_bf16 v[124:127], v[44:47], v[216:219], v[124:127]
	v_mfma_f32_16x16x32_bf16 v[120:123], v[52:55], v[216:219], v[120:123]
	v_mfma_f32_16x16x32_bf16 v[104:107], v[48:51], v[184:187], v[104:107]
	v_mfma_f32_16x16x32_bf16 v[100:103], v[56:59], v[184:187], v[100:103]
	v_mfma_f32_16x16x32_bf16 v[156:159], v[48:51], v[204:207], v[156:159]
	v_mfma_f32_16x16x32_bf16 v[148:151], v[56:59], v[204:207], v[148:151]
	v_mfma_f32_16x16x32_bf16 v[140:143], v[48:51], v[212:215], v[140:143]
	v_mfma_f32_16x16x32_bf16 v[132:135], v[56:59], v[212:215], v[132:135]
	v_mfma_f32_16x16x32_bf16 v[124:127], v[48:51], v[220:223], v[124:127]
	v_mfma_f32_16x16x32_bf16 v[120:123], v[56:59], v[220:223], v[120:123]
	s_setprio 0
	s_setprio 1
	v_mfma_f32_16x16x32_bf16 v[92:95], v[60:63], v[180:183], v[92:95]
	v_mfma_f32_16x16x32_bf16 v[88:91], v[72:75], v[180:183], v[88:91]
	v_mfma_f32_16x16x32_bf16 v[152:155], v[60:63], v[200:203], v[152:155]
	v_mfma_f32_16x16x32_bf16 v[144:147], v[72:75], v[200:203], v[144:147]
	v_mfma_f32_16x16x32_bf16 v[136:139], v[60:63], v[208:211], v[136:139]
	v_mfma_f32_16x16x32_bf16 v[128:131], v[72:75], v[208:211], v[128:131]
	v_mfma_f32_16x16x32_bf16 v[116:119], v[60:63], v[216:219], v[116:119]
	v_mfma_f32_16x16x32_bf16 v[112:115], v[72:75], v[216:219], v[112:115]
	v_mfma_f32_16x16x32_bf16 v[92:95], v[68:71], v[184:187], v[92:95]
	v_mfma_f32_16x16x32_bf16 v[88:91], v[76:79], v[184:187], v[88:91]
	v_mfma_f32_16x16x32_bf16 v[152:155], v[68:71], v[204:207], v[152:155]
	v_mfma_f32_16x16x32_bf16 v[144:147], v[76:79], v[204:207], v[144:147]
	v_mfma_f32_16x16x32_bf16 v[136:139], v[68:71], v[212:215], v[136:139]
	v_mfma_f32_16x16x32_bf16 v[128:131], v[76:79], v[212:215], v[128:131]
	v_mfma_f32_16x16x32_bf16 v[116:119], v[68:71], v[220:223], v[116:119]
	s_setprio 2
	s_barrier
	v_mfma_f32_16x16x32_bf16 v[112:115], v[76:79], v[220:223], v[112:115]
	s_setprio 0
	s_add_i32 s95, s87, s74
	v_lshl_add_u64 v[228:229], s[68:69], 0, v[162:163]
	s_mov_b32 m0, s95
	ds_read_b128 v[180:183], v198 offset:16384
	ds_read_b128 v[184:187], v198 offset:17408
	ds_read_b128 v[200:203], v198 offset:18432
	ds_read_b128 v[204:207], v198 offset:19456
	ds_read_b128 v[208:211], v198 offset:20480
	ds_read_b128 v[212:215], v198 offset:21504
	ds_read_b128 v[216:219], v198 offset:22528
	ds_read_b128 v[220:223], v198 offset:23552
	global_load_lds_dwordx4 v[228:229], off
	s_add_i32 m0, s95, 0x2000
	s_add_u32 s96, s68, 0x100000
	v_lshl_add_u64 v[230:231], s[68:69], 0, v[166:167]
	s_addc_u32 s97, s69, 0
	s_add_i32 s95, s90, s74
	global_load_lds_dwordx4 v[230:231], off
	v_lshl_add_u64 v[224:225], s[96:97], 0, v[162:163]
	s_mov_b32 m0, s95
	v_lshl_add_u64 v[232:233], s[70:71], 0, v[160:161]
	global_load_lds_dwordx4 v[224:225], off
	v_lshl_add_u64 v[224:225], s[96:97], 0, v[166:167]
	s_add_i32 m0, s95, 0x2000
	v_lshl_add_u64 v[234:235], s[70:71], 0, v[164:165]
	global_load_lds_dwordx4 v[224:225], off
	s_mov_b32 m0, s75
	s_nop 0
	global_load_lds_dwordx4 v[232:233], off
	s_mov_b32 m0, s76
	s_nop 0
	global_load_lds_dwordx4 v[234:235], off
	s_waitcnt vmcnt(8)
	s_waitcnt lgkmcnt(0)
	s_barrier
; #define PG8_STAGE(bufoff, gbase, voff) do { _Pragma("unroll") for (int _i = 0; _i < 2; ++_i) \
;         __builtin_amdgcn_global_load_lds((const unsigned*)((const char*)(gbase) + (voff)[_i]), (PG8_LAS unsigned*)(lds + (bufoff) + ldsw + _i * 8192), 16, 0, 0); } while (0)
; #define PG8_LDA(dst, b, h) do { _Pragma("unroll") for (int m = 0; m < 4; ++m) _Pragma("unroll") for (int k = 0; k < 2; ++k) dst[m][k] = *(const PG8_LAS bf16x8*)(lds + PG8_SA(b, h) + aoff + m * 2048 + k * 1024); } while (0)
; #define PG8_LDB(dst, b, h) do { _Pragma("unroll") for (int n = 0; n < 2; ++n) _Pragma("unroll") for (int k = 0; k < 2; ++k) dst[n][k] = *(const PG8_LAS bf16x8*)(lds + PG8_SB(b, h) + boff + n * 2048 + k * 1024); } while (0)
; #define PG8_MMA(ai, bj, At, Bt) do { __builtin_amdgcn_s_setprio(1); _Pragma("unroll") for (int m = 0; m < 4; ++m) _Pragma("unroll") for (int n = 0; n < 2; ++n) _Pragma("unroll") for (int k = 0; k < 2; ++k) \
;         acc[ai][bj][m][n] = __builtin_amdgcn_mfma_f32_16x16x32_bf16(Bt[n][k], At[m][k], acc[ai][bj][m][n], 0, 0, 0); __builtin_amdgcn_s_setprio(0); } while (0)
; #define PG8_WAIT_V(n) asm volatile("s_waitcnt vmcnt(" #n ")" ::: "memory")
; #define PG8_WAIT_L(n) asm volatile("s_waitcnt lgkmcnt(" #n ")" ::: "memory")
; #define PG8_BAR __builtin_amdgcn_s_barrier()
; #define PG8_SCHED __builtin_amdgcn_sched_barrier(0)
; template <class Epi, class Sched, bool ALIGN_EPI = false, bool SP2 = false>
; __device__ __forceinline__ void gemm_phase(PG8_LAS unsigned char* lds, const Gemm g, const Sched& S, const Epi& E, const int wv  ) {
;     ...
;             PG8_WAIT_V(8); PG8_WAIT_L(0); PG8_BAR; PG8_MMA(1, 0, At, B0); PG8_MMA(1, 1, At, B1); PG8_BAR; PG8_SCHED;
;             PG8_LDB(B0, 1, 0); PG8_LDB(B1, 1, 1); PG8_SCHED; PG8_LDA(At, 1, 0); PG8_STAGE(PG8_SA(0, 1), a2 + hstepA, voffA);
;             PG8_WAIT_V(8); PG8_WAIT_L(0); PG8_BAR; PG8_MMA(0, 0, At, B0); PG8_MMA(0, 1, At, B1); PG8_BAR; PG8_SCHED;
	s_setprio 1
	s_waitcnt lgkmcnt(0)
	v_mfma_f32_16x16x32_bf16 v[108:111], v[44:47], v[180:183], v[108:111]
	v_mfma_f32_16x16x32_bf16 v[96:99], v[52:55], v[180:183], v[96:99]
	v_mfma_f32_16x16x32_bf16 v[64:67], v[44:47], v[200:203], v[64:67]
	v_mfma_f32_16x16x32_bf16 v[36:39], v[52:55], v[200:203], v[36:39]
	v_mfma_f32_16x16x32_bf16 v[28:31], v[44:47], v[208:211], v[28:31]
	v_mfma_f32_16x16x32_bf16 v[20:23], v[52:55], v[208:211], v[20:23]
	v_mfma_f32_16x16x32_bf16 v[12:15], v[44:47], v[216:219], v[12:15]
	v_mfma_f32_16x16x32_bf16 v[4:7], v[52:55], v[216:219], v[4:7]
	v_mfma_f32_16x16x32_bf16 v[108:111], v[48:51], v[184:187], v[108:111]
	v_mfma_f32_16x16x32_bf16 v[96:99], v[56:59], v[184:187], v[96:99]
	v_mfma_f32_16x16x32_bf16 v[64:67], v[48:51], v[204:207], v[64:67]
	v_mfma_f32_16x16x32_bf16 v[36:39], v[56:59], v[204:207], v[36:39]
	v_mfma_f32_16x16x32_bf16 v[28:31], v[48:51], v[212:215], v[28:31]
	v_mfma_f32_16x16x32_bf16 v[20:23], v[56:59], v[212:215], v[20:23]
	v_mfma_f32_16x16x32_bf16 v[12:15], v[48:51], v[220:223], v[12:15]
	v_mfma_f32_16x16x32_bf16 v[4:7], v[56:59], v[220:223], v[4:7]
	s_setprio 0
	s_setprio 1
	v_mfma_f32_16x16x32_bf16 v[40:43], v[60:63], v[200:203], v[40:43]
	v_mfma_f32_16x16x32_bf16 v[32:35], v[72:75], v[200:203], v[32:35]
	v_mfma_f32_16x16x32_bf16 v[24:27], v[60:63], v[208:211], v[24:27]
	v_mfma_f32_16x16x32_bf16 v[16:19], v[72:75], v[208:211], v[16:19]
	v_mfma_f32_16x16x32_bf16 v[8:11], v[60:63], v[216:219], v[8:11]
	v_mfma_f32_16x16x32_bf16 v[0:3], v[72:75], v[216:219], v[0:3]
	v_mfma_f32_16x16x32_bf16 v[44:47], v[60:63], v[180:183], v[84:87]
	v_mfma_f32_16x16x32_bf16 v[48:51], v[72:75], v[180:183], v[80:83]
	v_mfma_f32_16x16x32_bf16 v[40:43], v[68:71], v[204:207], v[40:43]
	v_mfma_f32_16x16x32_bf16 v[32:35], v[76:79], v[204:207], v[32:35]
	v_mfma_f32_16x16x32_bf16 v[24:27], v[68:71], v[212:215], v[24:27]
	v_mfma_f32_16x16x32_bf16 v[16:19], v[76:79], v[212:215], v[16:19]
	v_mfma_f32_16x16x32_bf16 v[8:11], v[68:71], v[220:223], v[8:11]
	v_mfma_f32_16x16x32_bf16 v[0:3], v[76:79], v[220:223], v[0:3]
	v_mfma_f32_16x16x32_bf16 v[44:47], v[68:71], v[184:187], v[44:47]
	s_setprio 2
	s_barrier
	v_mfma_f32_16x16x32_bf16 v[48:51], v[76:79], v[184:187], v[48:51]
	s_setprio 0
	s_add_i32 s95, 0, 0x18000
	s_add_i32 s96, 0, 0x1c000
	v_add_u32_e32 v68, s95, v190
	v_add_u32_e32 v80, s96, v190
	ds_read_b128 v[52:55], v68
	ds_read_b128 v[56:59], v68 offset:1024
	ds_read_b128 v[60:63], v68 offset:2048
	ds_read_b128 v[68:71], v68 offset:3072
	ds_read_b128 v[72:75], v80
	ds_read_b128 v[76:79], v80 offset:1024
	ds_read_b128 v[180:183], v80 offset:2048
	ds_read_b128 v[184:187], v80 offset:3072
	s_add_u32 s70, s70, 0x100000
	s_addc_u32 s71, s71, 0
	s_mov_b32 m0, s77
	v_lshl_add_u64 v[224:225], s[70:71], 0, v[160:161]
	ds_read_b128 v[80:83], v198 offset:32768
	ds_read_b128 v[84:87], v198 offset:33792
	ds_read_b128 v[200:203], v198 offset:34816
	ds_read_b128 v[204:207], v198 offset:35840
	ds_read_b128 v[208:211], v198 offset:36864
	ds_read_b128 v[212:215], v198 offset:37888
	ds_read_b128 v[216:219], v198 offset:38912
	ds_read_b128 v[220:223], v198 offset:39936
	global_load_lds_dwordx4 v[224:225], off
	v_lshl_add_u64 v[224:225], s[70:71], 0, v[164:165]
	s_mov_b32 m0, s78
	s_nop 0
	global_load_lds_dwordx4 v[224:225], off
	s_waitcnt vmcnt(8)
	s_waitcnt lgkmcnt(0)
	s_barrier
	s_setprio 1
	s_waitcnt lgkmcnt(0)
	v_mfma_f32_16x16x32_bf16 v[104:107], v[52:55], v[80:83], v[104:107]
	v_mfma_f32_16x16x32_bf16 v[100:103], v[60:63], v[80:83], v[100:103]
	v_mfma_f32_16x16x32_bf16 v[156:159], v[52:55], v[200:203], v[156:159]
	v_mfma_f32_16x16x32_bf16 v[148:151], v[60:63], v[200:203], v[148:151]
	v_mfma_f32_16x16x32_bf16 v[140:143], v[52:55], v[208:211], v[140:143]
	v_mfma_f32_16x16x32_bf16 v[132:135], v[60:63], v[208:211], v[132:135]
	v_mfma_f32_16x16x32_bf16 v[124:127], v[52:55], v[216:219], v[124:127]
	v_mfma_f32_16x16x32_bf16 v[120:123], v[60:63], v[216:219], v[120:123]
	v_mfma_f32_16x16x32_bf16 v[104:107], v[56:59], v[84:87], v[104:107]
	v_mfma_f32_16x16x32_bf16 v[100:103], v[68:71], v[84:87], v[100:103]
	v_mfma_f32_16x16x32_bf16 v[156:159], v[56:59], v[204:207], v[156:159]
	v_mfma_f32_16x16x32_bf16 v[148:151], v[68:71], v[204:207], v[148:151]
	v_mfma_f32_16x16x32_bf16 v[140:143], v[56:59], v[212:215], v[140:143]
	v_mfma_f32_16x16x32_bf16 v[132:135], v[68:71], v[212:215], v[132:135]
	v_mfma_f32_16x16x32_bf16 v[124:127], v[56:59], v[220:223], v[124:127]
	v_mfma_f32_16x16x32_bf16 v[120:123], v[68:71], v[220:223], v[120:123]
	s_setprio 0
	s_setprio 1
	v_mfma_f32_16x16x32_bf16 v[92:95], v[72:75], v[80:83], v[92:95]
	v_mfma_f32_16x16x32_bf16 v[80:83], v[180:183], v[80:83], v[88:91]
	v_mfma_f32_16x16x32_bf16 v[88:91], v[184:187], v[84:87], v[80:83]
	v_mfma_f32_16x16x32_bf16 v[80:83], v[72:75], v[200:203], v[152:155]
	v_mfma_f32_16x16x32_bf16 v[152:155], v[76:79], v[204:207], v[80:83]
	v_mfma_f32_16x16x32_bf16 v[80:83], v[180:183], v[200:203], v[144:147]
	v_mfma_f32_16x16x32_bf16 v[144:147], v[184:187], v[204:207], v[80:83]
	v_mfma_f32_16x16x32_bf16 v[80:83], v[72:75], v[208:211], v[136:139]
	v_mfma_f32_16x16x32_bf16 v[136:139], v[76:79], v[212:215], v[80:83]
	v_mfma_f32_16x16x32_bf16 v[80:83], v[180:183], v[208:211], v[128:131]
	v_mfma_f32_16x16x32_bf16 v[128:131], v[184:187], v[212:215], v[80:83]
	v_mfma_f32_16x16x32_bf16 v[80:83], v[72:75], v[216:219], v[116:119]
	v_mfma_f32_16x16x32_bf16 v[116:119], v[76:79], v[220:223], v[80:83]
	v_mfma_f32_16x16x32_bf16 v[80:83], v[180:183], v[216:219], v[112:115]
	v_mfma_f32_16x16x32_bf16 v[92:95], v[76:79], v[84:87], v[92:95]
	s_setprio 2
	s_barrier
; #define PG8_STAGE(bufoff, gbase, voff) do { _Pragma("unroll") for (int _i = 0; _i < 2; ++_i) \
;         __builtin_amdgcn_global_load_lds((const unsigned*)((const char*)(gbase) + (voff)[_i]), (PG8_LAS unsigned*)(lds + (bufoff) + ldsw + _i * 8192), 16, 0, 0); } while (0)
; #define PG8_LDA(dst, b, h) do { _Pragma("unroll") for (int m = 0; m < 4; ++m) _Pragma("unroll") for (int k = 0; k < 2; ++k) dst[m][k] = *(const PG8_LAS bf16x8*)(lds + PG8_SA(b, h) + aoff + m * 2048 + k * 1024); } while (0)
; #define PG8_MMA(ai, bj, At, Bt) do { __builtin_amdgcn_s_setprio(1); _Pragma("unroll") for (int m = 0; m < 4; ++m) _Pragma("unroll") for (int n = 0; n < 2; ++n) _Pragma("unroll") for (int k = 0; k < 2; ++k) \
;         acc[ai][bj][m][n] = __builtin_amdgcn_mfma_f32_16x16x32_bf16(Bt[n][k], At[m][k], acc[ai][bj][m][n], 0, 0, 0); __builtin_amdgcn_s_setprio(0); } while (0)
; #define PG8_WAIT_V(n) asm volatile("s_waitcnt vmcnt(" #n ")" ::: "memory")
; #define PG8_WAIT_L(n) asm volatile("s_waitcnt lgkmcnt(" #n ")" ::: "memory")
; #define PG8_BAR __builtin_amdgcn_s_barrier()
; #define PG8_SCHED __builtin_amdgcn_sched_barrier(0)
; template <class Epi, class Sched, bool ALIGN_EPI = false, bool SP2 = false>
; __device__ __forceinline__ void gemm_phase(PG8_LAS unsigned char* lds, const Gemm g, const Sched& S, const Epi& E, const int wv  ) {
;     ...
;         for (int t = 0; t < nt; t += 2) {
;             const bool last = (t == nt - 2);
;     ...
;             PG8_WAIT_V(8); PG8_WAIT_L(0); PG8_BAR; PG8_MMA(0, 0, At, B0); PG8_MMA(0, 1, At, B1); PG8_BAR; PG8_SCHED;
;             PG8_LDA(At, 1, 1); PG8_STAGE(PG8_SB(1, 0), b3, voffB); PG8_STAGE(PG8_SB(1, 1), b3 + hstepB, voffB); PG8_STAGE(PG8_SA(1, 0), a3, voffA);
;             PG8_WAIT_V(8); PG8_WAIT_L(0); PG8_BAR; PG8_MMA(1, 0, At, B0); PG8_MMA(1, 1, At, B1); PG8_BAR; PG8_SCHED;
	v_mfma_f32_16x16x32_bf16 v[112:115], v[184:187], v[220:223], v[80:83]
	s_setprio 0
	s_add_i32 s70, s95, s74
	v_lshl_add_u64 v[84:85], v[228:229], 0, s[18:19]
	s_mov_b32 m0, s70
	s_nop 0
	ds_read_b128 v[80:83], v198 offset:49152
	ds_read_b128 v[200:203], v198 offset:50176
	ds_read_b128 v[204:207], v198 offset:51200
	ds_read_b128 v[208:211], v198 offset:52224
	ds_read_b128 v[212:215], v198 offset:53248
	ds_read_b128 v[216:219], v198 offset:54272
	ds_read_b128 v[220:223], v198 offset:55296
	ds_read_b128 v[224:227], v198 offset:56320
	global_load_lds_dwordx4 v[84:85], off
	s_add_i32 m0, s70, 0x2000
	s_add_u32 s68, s68, 0x100080
	v_lshl_add_u64 v[84:85], v[230:231], 0, s[18:19]
	s_addc_u32 s69, s69, 0
	s_add_i32 s70, s96, s74
	global_load_lds_dwordx4 v[84:85], off
	v_lshl_add_u64 v[84:85], s[68:69], 0, v[162:163]
	s_mov_b32 m0, s70
	s_nop 0
	global_load_lds_dwordx4 v[84:85], off
	v_lshl_add_u64 v[84:85], s[68:69], 0, v[166:167]
	s_add_i32 m0, s70, 0x2000
	s_nop 0
	global_load_lds_dwordx4 v[84:85], off
	v_lshl_add_u64 v[84:85], v[232:233], 0, s[18:19]
	s_mov_b32 m0, s82
	s_nop 0
	global_load_lds_dwordx4 v[84:85], off
	v_lshl_add_u64 v[84:85], v[234:235], 0, s[18:19]
	s_mov_b32 m0, s83
	s_nop 0
	global_load_lds_dwordx4 v[84:85], off
	s_waitcnt vmcnt(8)
	s_waitcnt lgkmcnt(0)
	s_barrier
	s_setprio 1
	s_waitcnt lgkmcnt(0)
	v_mfma_f32_16x16x32_bf16 v[84:87], v[52:55], v[80:83], v[108:111]
	v_mfma_f32_16x16x32_bf16 v[108:111], v[56:59], v[200:203], v[84:87]
	v_mfma_f32_16x16x32_bf16 v[84:87], v[60:63], v[80:83], v[96:99]
	v_mfma_f32_16x16x32_bf16 v[64:67], v[52:55], v[204:207], v[64:67]
	v_mfma_f32_16x16x32_bf16 v[36:39], v[60:63], v[204:207], v[36:39]
	v_mfma_f32_16x16x32_bf16 v[28:31], v[52:55], v[212:215], v[28:31]
	v_mfma_f32_16x16x32_bf16 v[20:23], v[60:63], v[212:215], v[20:23]
	v_mfma_f32_16x16x32_bf16 v[12:15], v[52:55], v[220:223], v[12:15]
	v_mfma_f32_16x16x32_bf16 v[4:7], v[60:63], v[220:223], v[4:7]
	v_mfma_f32_16x16x32_bf16 v[96:99], v[68:71], v[200:203], v[84:87]
	v_mfma_f32_16x16x32_bf16 v[64:67], v[56:59], v[208:211], v[64:67]
	v_mfma_f32_16x16x32_bf16 v[36:39], v[68:71], v[208:211], v[36:39]
	v_mfma_f32_16x16x32_bf16 v[28:31], v[56:59], v[216:219], v[28:31]
	v_mfma_f32_16x16x32_bf16 v[20:23], v[68:71], v[216:219], v[20:23]
	v_mfma_f32_16x16x32_bf16 v[12:15], v[56:59], v[224:227], v[12:15]
	v_mfma_f32_16x16x32_bf16 v[4:7], v[68:71], v[224:227], v[4:7]
	s_setprio 0
	s_setprio 1
	v_mfma_f32_16x16x32_bf16 v[44:47], v[72:75], v[80:83], v[44:47]
	v_mfma_f32_16x16x32_bf16 v[84:87], v[76:79], v[200:203], v[44:47]
	v_mfma_f32_16x16x32_bf16 v[44:47], v[180:183], v[80:83], v[48:51]
	v_mfma_f32_16x16x32_bf16 v[40:43], v[72:75], v[204:207], v[40:43]
	v_mfma_f32_16x16x32_bf16 v[32:35], v[180:183], v[204:207], v[32:35]
	v_mfma_f32_16x16x32_bf16 v[24:27], v[72:75], v[212:215], v[24:27]
	v_mfma_f32_16x16x32_bf16 v[16:19], v[180:183], v[212:215], v[16:19]
	v_mfma_f32_16x16x32_bf16 v[8:11], v[72:75], v[220:223], v[8:11]
	v_mfma_f32_16x16x32_bf16 v[0:3], v[180:183], v[220:223], v[0:3]
	v_mfma_f32_16x16x32_bf16 v[80:83], v[184:187], v[200:203], v[44:47]
	v_mfma_f32_16x16x32_bf16 v[40:43], v[76:79], v[208:211], v[40:43]
	v_mfma_f32_16x16x32_bf16 v[32:35], v[184:187], v[208:211], v[32:35]
	v_mfma_f32_16x16x32_bf16 v[24:27], v[76:79], v[216:219], v[24:27]
	v_mfma_f32_16x16x32_bf16 v[16:19], v[184:187], v[216:219], v[16:19]
	v_mfma_f32_16x16x32_bf16 v[8:11], v[76:79], v[224:227], v[8:11]
	s_setprio 2
	s_barrier
	v_mfma_f32_16x16x32_bf16 v[0:3], v[184:187], v[224:227], v[0:3]
	s_setprio 0
	s_add_i32 s94, s94, 2
	s_add_u32 s66, s66, 0x100
	s_addc_u32 s67, s67, 0
	s_add_u32 s92, s92, 0x100
	s_addc_u32 s93, s93, 0
	s_cmp_gt_u32 s94, 61
	s_cbranch_scc0 .LBB0_1187
	s_and_b64 vcc, exec, s[20:21]
	s_cbranch_vccz .LBB0_1190
	s_barrier

; #define PG8_STAGE(bufoff, gbase, voff) do { _Pragma("unroll") for (int _i = 0; _i < 2; ++_i) \
;         __builtin_amdgcn_global_load_lds((const unsigned*)((const char*)(gbase) + (voff)[_i]), (PG8_LAS unsigned*)(lds + (bufoff) + ldsw + _i * 8192), 16, 0, 0); } while (0)
; #define PG8_LDA(dst, b, h) do { _Pragma("unroll") for (int m = 0; m < 4; ++m) _Pragma("unroll") for (int k = 0; k < 2; ++k) dst[m][k] = *(const PG8_LAS bf16x8*)(lds + PG8_SA(b, h) + aoff + m * 2048 + k * 1024); } while (0)
; #define PG8_LDB(dst, b, h) do { _Pragma("unroll") for (int n = 0; n < 2; ++n) _Pragma("unroll") for (int k = 0; k < 2; ++k) dst[n][k] = *(const PG8_LAS bf16x8*)(lds + PG8_SB(b, h) + boff + n * 2048 + k * 1024); } while (0)
; #define PG8_MMA(ai, bj, At, Bt) do { __builtin_amdgcn_s_setprio(1); _Pragma("unroll") for (int m = 0; m < 4; ++m) _Pragma("unroll") for (int n = 0; n < 2; ++n) _Pragma("unroll") for (int k = 0; k < 2; ++k) \
;         acc[ai][bj][m][n] = __builtin_amdgcn_mfma_f32_16x16x32_bf16(Bt[n][k], At[m][k], acc[ai][bj][m][n], 0, 0, 0); __builtin_amdgcn_s_setprio(0); } while (0)
; #define PG8_WAIT_V(n) asm volatile("s_waitcnt vmcnt(" #n ")" ::: "memory")
; #define PG8_WAIT_L(n) asm volatile("s_waitcnt lgkmcnt(" #n ")" ::: "memory")
; template <class Epi, class Sched, bool ALIGN_EPI = false, bool SP2 = false>
; __device__ __forceinline__ void gemm_phase(PG8_LAS unsigned char* lds, const Gemm g, const Sched& S, const Epi& E, const int wv  ) {
;     ...
;             const bool last = (t == nt - 2);
;             const char* a1 = cA + (size_t)(t + 1) * kstep;
;             const char* a2 = last ? nA : cA + (size_t)(t + 2) * kstep; const char* b2 = last ? nB : cB + (size_t)(t + 2) * kstep;
;             const char* a3 = a2 + kstep; const char* b3 = b2 + kstep;
;             if (last && has_next) S.a_ready(nxt);
;             if constexpr (SP2) {
;             PG8_LDB(B0, 0, 0); PG8_LDB(B1, 0, 1); PG8_SCHED; PG8_LDA(At, 0, 0); PG8_STAGE(PG8_SA(1, 1), a1 + hstepA, voffA);
;             PG8_WAIT_V(8); PG8_WAIT_L(0); PG8_BAR; PG8_MMA(0, 0, At, B0); PG8_MMA(0, 1, At, B1); PG8_BAR; PG8_SCHED;
;             PG8_LDA(At, 0, 1); PG8_STAGE(PG8_SB(0, 0), b2, voffB); PG8_STAGE(PG8_SB(0, 1), b2 + hstepB, voffB); PG8_STAGE(PG8_SA(0, 0), a2, voffA);
;             PG8_WAIT_V(8); PG8_WAIT_L(0); PG8_BAR; PG8_MMA(1, 0, At, B0); PG8_MMA(1, 1, At, B1); PG8_BAR; PG8_SCHED;
.LBB0_1544:
	ds_read_b128 v[146:149], v152
	ds_read_b128 v[156:159], v152 offset:1024
	ds_read_b128 v[160:163], v152 offset:2048
	ds_read_b128 v[164:167], v152 offset:3072
	ds_read_b128 v[168:171], v153
	ds_read_b128 v[172:175], v153 offset:1024
	ds_read_b128 v[176:179], v153 offset:2048
	ds_read_b128 v[180:183], v153 offset:3072
	s_add_u32 s54, s52, 0x100
	s_addc_u32 s55, s53, 0
	s_cmpk_eq_i32 s85, 0xa8
	s_cselect_b32 s59, s7, s55
	s_cselect_b32 s58, s6, s54
	s_cselect_b32 s57, s51, s84
	s_cselect_b32 s56, s50, s83
	v_lshl_add_u64 v[216:217], s[52:53], 0, v[138:139]
	s_add_i32 m0, s64, 0xc000
	ds_read_b128 v[184:187], v154
	ds_read_b128 v[188:191], v154 offset:1024
	ds_read_b128 v[192:195], v154 offset:2048
	ds_read_b128 v[196:199], v154 offset:3072
	ds_read_b128 v[200:203], v154 offset:4096
	ds_read_b128 v[204:207], v154 offset:5120
	ds_read_b128 v[208:211], v154 offset:6144
	ds_read_b128 v[212:215], v154 offset:7168
	global_load_lds_dwordx4 v[216:217], off
	v_lshl_add_u64 v[216:217], s[52:53], 0, v[140:141]
	s_add_i32 m0, s64, 0xe000
	s_nop 0
	global_load_lds_dwordx4 v[216:217], off
	s_waitcnt vmcnt(8)
	s_waitcnt lgkmcnt(0)
	s_barrier
	s_setprio 1
	s_waitcnt lgkmcnt(0)
	v_mfma_f32_16x16x32_bf16 v[76:79], v[146:149], v[184:187], v[76:79]
	v_mfma_f32_16x16x32_bf16 v[72:75], v[160:163], v[184:187], v[72:75]
	v_mfma_f32_16x16x32_bf16 v[68:71], v[146:149], v[192:195], v[68:71]
	v_mfma_f32_16x16x32_bf16 v[64:67], v[160:163], v[192:195], v[64:67]
	v_mfma_f32_16x16x32_bf16 v[56:59], v[146:149], v[200:203], v[56:59]
	v_mfma_f32_16x16x32_bf16 v[52:55], v[160:163], v[200:203], v[52:55]
	v_mfma_f32_16x16x32_bf16 v[44:47], v[146:149], v[208:211], v[44:47]
	v_mfma_f32_16x16x32_bf16 v[40:43], v[160:163], v[208:211], v[40:43]
	v_mfma_f32_16x16x32_bf16 v[76:79], v[156:159], v[188:191], v[76:79]
	v_mfma_f32_16x16x32_bf16 v[72:75], v[164:167], v[188:191], v[72:75]
	v_mfma_f32_16x16x32_bf16 v[68:71], v[156:159], v[196:199], v[68:71]
	v_mfma_f32_16x16x32_bf16 v[64:67], v[164:167], v[196:199], v[64:67]
	v_mfma_f32_16x16x32_bf16 v[56:59], v[156:159], v[204:207], v[56:59]
	v_mfma_f32_16x16x32_bf16 v[52:55], v[164:167], v[204:207], v[52:55]
	v_mfma_f32_16x16x32_bf16 v[44:47], v[156:159], v[212:215], v[44:47]
	v_mfma_f32_16x16x32_bf16 v[40:43], v[164:167], v[212:215], v[40:43]
	s_setprio 0
	s_setprio 1
	v_mfma_f32_16x16x32_bf16 v[124:127], v[168:171], v[184:187], v[124:127]
	v_mfma_f32_16x16x32_bf16 v[120:123], v[176:179], v[184:187], v[120:123]
	v_mfma_f32_16x16x32_bf16 v[116:119], v[168:171], v[192:195], v[116:119]
	v_mfma_f32_16x16x32_bf16 v[112:115], v[176:179], v[192:195], v[112:115]
	v_mfma_f32_16x16x32_bf16 v[108:111], v[168:171], v[200:203], v[108:111]
	v_mfma_f32_16x16x32_bf16 v[104:107], v[176:179], v[200:203], v[104:107]
	v_mfma_f32_16x16x32_bf16 v[100:103], v[168:171], v[208:211], v[100:103]
	v_mfma_f32_16x16x32_bf16 v[96:99], v[176:179], v[208:211], v[96:99]
	v_mfma_f32_16x16x32_bf16 v[124:127], v[172:175], v[188:191], v[124:127]
	v_mfma_f32_16x16x32_bf16 v[120:123], v[180:183], v[188:191], v[120:123]
	v_mfma_f32_16x16x32_bf16 v[116:119], v[172:175], v[196:199], v[116:119]
	v_mfma_f32_16x16x32_bf16 v[112:115], v[180:183], v[196:199], v[112:115]
	v_mfma_f32_16x16x32_bf16 v[108:111], v[172:175], v[204:207], v[108:111]
	v_mfma_f32_16x16x32_bf16 v[104:107], v[180:183], v[204:207], v[104:107]
	v_mfma_f32_16x16x32_bf16 v[100:103], v[172:175], v[212:215], v[100:103]
	s_setprio 2
	s_barrier
	v_mfma_f32_16x16x32_bf16 v[96:99], v[180:183], v[212:215], v[96:99]
	s_setprio 0
	s_add_i32 s52, s73, s63
	v_lshl_add_u64 v[216:217], s[56:57], 0, v[130:131]
	s_mov_b32 m0, s52
	ds_read_b128 v[184:187], v154 offset:16384
	ds_read_b128 v[188:191], v154 offset:17408
	ds_read_b128 v[192:195], v154 offset:18432
	ds_read_b128 v[196:199], v154 offset:19456
	ds_read_b128 v[200:203], v154 offset:20480
	ds_read_b128 v[204:207], v154 offset:21504
	ds_read_b128 v[208:211], v154 offset:22528
	ds_read_b128 v[212:215], v154 offset:23552
	global_load_lds_dwordx4 v[216:217], off
	s_add_i32 m0, s52, 0x2000
	s_add_u32 s52, s56, 0x2b0000
	v_lshl_add_u64 v[218:219], s[56:57], 0, v[134:135]
	s_addc_u32 s53, s57, 0
	s_add_i32 s86, s74, s63
	global_load_lds_dwordx4 v[218:219], off
	v_lshl_add_u64 v[220:221], s[52:53], 0, v[130:131]
	s_mov_b32 m0, s86
	v_lshl_add_u64 v[222:223], s[58:59], 0, v[132:133]
	global_load_lds_dwordx4 v[220:221], off
	v_lshl_add_u64 v[220:221], s[52:53], 0, v[134:135]
	s_add_i32 m0, s86, 0x2000
	s_nop 0
	global_load_lds_dwordx4 v[220:221], off
	v_lshl_add_u64 v[220:221], s[58:59], 0, v[128:129]
	s_mov_b32 m0, s64
	s_nop 0
	global_load_lds_dwordx4 v[220:221], off
	s_mov_b32 m0, s65
	s_nop 0
	global_load_lds_dwordx4 v[222:223], off
	s_waitcnt vmcnt(8)
	s_waitcnt lgkmcnt(0)
	s_barrier
; #define PG8_STAGE(bufoff, gbase, voff) do { _Pragma("unroll") for (int _i = 0; _i < 2; ++_i) \
;         __builtin_amdgcn_global_load_lds((const unsigned*)((const char*)(gbase) + (voff)[_i]), (PG8_LAS unsigned*)(lds + (bufoff) + ldsw + _i * 8192), 16, 0, 0); } while (0)
; #define PG8_LDA(dst, b, h) do { _Pragma("unroll") for (int m = 0; m < 4; ++m) _Pragma("unroll") for (int k = 0; k < 2; ++k) dst[m][k] = *(const PG8_LAS bf16x8*)(lds + PG8_SA(b, h) + aoff + m * 2048 + k * 1024); } while (0)
; #define PG8_LDB(dst, b, h) do { _Pragma("unroll") for (int n = 0; n < 2; ++n) _Pragma("unroll") for (int k = 0; k < 2; ++k) dst[n][k] = *(const PG8_LAS bf16x8*)(lds + PG8_SB(b, h) + boff + n * 2048 + k * 1024); } while (0)
; #define PG8_MMA(ai, bj, At, Bt) do { __builtin_amdgcn_s_setprio(1); _Pragma("unroll") for (int m = 0; m < 4; ++m) _Pragma("unroll") for (int n = 0; n < 2; ++n) _Pragma("unroll") for (int k = 0; k < 2; ++k) \
;         acc[ai][bj][m][n] = __builtin_amdgcn_mfma_f32_16x16x32_bf16(Bt[n][k], At[m][k], acc[ai][bj][m][n], 0, 0, 0); __builtin_amdgcn_s_setprio(0); } while (0)
; #define PG8_WAIT_V(n) asm volatile("s_waitcnt vmcnt(" #n ")" ::: "memory")
; #define PG8_WAIT_L(n) asm volatile("s_waitcnt lgkmcnt(" #n ")" ::: "memory")
; #define PG8_BAR __builtin_amdgcn_s_barrier()
; #define PG8_SCHED __builtin_amdgcn_sched_barrier(0)
; template <class Epi, class Sched, bool ALIGN_EPI = false, bool SP2 = false>
; __device__ __forceinline__ void gemm_phase(PG8_LAS unsigned char* lds, const Gemm g, const Sched& S, const Epi& E, const int wv  ) {
;     ...
;             PG8_WAIT_V(8); PG8_WAIT_L(0); PG8_BAR; PG8_MMA(1, 0, At, B0); PG8_MMA(1, 1, At, B1); PG8_BAR; PG8_SCHED;
;             PG8_LDB(B0, 1, 0); PG8_LDB(B1, 1, 1); PG8_SCHED; PG8_LDA(At, 1, 0); PG8_STAGE(PG8_SA(0, 1), a2 + hstepA, voffA);
;             PG8_WAIT_V(8); PG8_WAIT_L(0); PG8_BAR; PG8_MMA(0, 0, At, B0); PG8_MMA(0, 1, At, B1); PG8_BAR; PG8_SCHED;
	s_setprio 1
	s_waitcnt lgkmcnt(0)
	v_mfma_f32_16x16x32_bf16 v[28:31], v[146:149], v[184:187], v[28:31]
	v_mfma_f32_16x16x32_bf16 v[24:27], v[160:163], v[184:187], v[24:27]
	v_mfma_f32_16x16x32_bf16 v[20:23], v[146:149], v[192:195], v[20:23]
	v_mfma_f32_16x16x32_bf16 v[16:19], v[160:163], v[192:195], v[16:19]
	v_mfma_f32_16x16x32_bf16 v[12:15], v[146:149], v[200:203], v[12:15]
	v_mfma_f32_16x16x32_bf16 v[8:11], v[160:163], v[200:203], v[8:11]
	v_mfma_f32_16x16x32_bf16 v[4:7], v[146:149], v[208:211], v[4:7]
	v_mfma_f32_16x16x32_bf16 v[0:3], v[160:163], v[208:211], v[0:3]
	v_mfma_f32_16x16x32_bf16 v[28:31], v[156:159], v[188:191], v[28:31]
	v_mfma_f32_16x16x32_bf16 v[24:27], v[164:167], v[188:191], v[24:27]
	v_mfma_f32_16x16x32_bf16 v[20:23], v[156:159], v[196:199], v[20:23]
	v_mfma_f32_16x16x32_bf16 v[16:19], v[164:167], v[196:199], v[16:19]
	v_mfma_f32_16x16x32_bf16 v[12:15], v[156:159], v[204:207], v[12:15]
	v_mfma_f32_16x16x32_bf16 v[8:11], v[164:167], v[204:207], v[8:11]
	v_mfma_f32_16x16x32_bf16 v[4:7], v[156:159], v[212:215], v[4:7]
	v_mfma_f32_16x16x32_bf16 v[0:3], v[164:167], v[212:215], v[0:3]
	s_setprio 0
	s_setprio 1
	v_mfma_f32_16x16x32_bf16 v[92:95], v[168:171], v[184:187], v[92:95]
	v_mfma_f32_16x16x32_bf16 v[88:91], v[176:179], v[184:187], v[88:91]
	v_mfma_f32_16x16x32_bf16 v[84:87], v[168:171], v[192:195], v[84:87]
	v_mfma_f32_16x16x32_bf16 v[80:83], v[176:179], v[192:195], v[80:83]
	v_mfma_f32_16x16x32_bf16 v[60:63], v[168:171], v[200:203], v[60:63]
	v_mfma_f32_16x16x32_bf16 v[48:51], v[176:179], v[200:203], v[48:51]
	v_mfma_f32_16x16x32_bf16 v[36:39], v[168:171], v[208:211], v[36:39]
	v_mfma_f32_16x16x32_bf16 v[32:35], v[176:179], v[208:211], v[32:35]
	v_mfma_f32_16x16x32_bf16 v[92:95], v[172:175], v[188:191], v[92:95]
	v_mfma_f32_16x16x32_bf16 v[88:91], v[180:183], v[188:191], v[88:91]
	v_mfma_f32_16x16x32_bf16 v[84:87], v[172:175], v[196:199], v[84:87]
	v_mfma_f32_16x16x32_bf16 v[80:83], v[180:183], v[196:199], v[80:83]
	v_mfma_f32_16x16x32_bf16 v[60:63], v[172:175], v[204:207], v[60:63]
	v_mfma_f32_16x16x32_bf16 v[48:51], v[180:183], v[204:207], v[48:51]
	v_mfma_f32_16x16x32_bf16 v[36:39], v[172:175], v[212:215], v[36:39]
	s_setprio 2
	s_barrier
	v_mfma_f32_16x16x32_bf16 v[32:35], v[180:183], v[212:215], v[32:35]
	s_setprio 0
	s_add_i32 s86, 0, 0x18000
	v_add_u32_e32 v155, s86, v150
	s_add_i32 s87, 0, 0x1c000
	ds_read_b128 v[146:149], v155
	ds_read_b128 v[156:159], v155 offset:1024
	ds_read_b128 v[160:163], v155 offset:2048
	ds_read_b128 v[164:167], v155 offset:3072
	v_add_u32_e32 v155, s87, v150
	ds_read_b128 v[168:171], v155
	ds_read_b128 v[172:175], v155 offset:1024
	ds_read_b128 v[176:179], v155 offset:2048
	ds_read_b128 v[180:183], v155 offset:3072
	s_add_u32 s52, s58, 0x2b0000
	s_addc_u32 s53, s59, 0
	s_mov_b32 m0, s66
	v_lshl_add_u64 v[224:225], s[52:53], 0, v[128:129]
	ds_read_b128 v[184:187], v154 offset:32768
	ds_read_b128 v[188:191], v154 offset:33792
	ds_read_b128 v[192:195], v154 offset:34816
	ds_read_b128 v[196:199], v154 offset:35840
	ds_read_b128 v[200:203], v154 offset:36864
	ds_read_b128 v[204:207], v154 offset:37888
	ds_read_b128 v[208:211], v154 offset:38912
	ds_read_b128 v[212:215], v154 offset:39936
	global_load_lds_dwordx4 v[224:225], off
	v_lshl_add_u64 v[224:225], s[52:53], 0, v[132:133]
	s_mov_b32 m0, s67
	s_nop 0
	global_load_lds_dwordx4 v[224:225], off
	s_waitcnt vmcnt(8)
	s_waitcnt lgkmcnt(0)
	s_barrier
	s_setprio 1
	s_waitcnt lgkmcnt(0)
	v_mfma_f32_16x16x32_bf16 v[76:79], v[146:149], v[184:187], v[76:79]
	v_mfma_f32_16x16x32_bf16 v[72:75], v[160:163], v[184:187], v[72:75]
	v_mfma_f32_16x16x32_bf16 v[68:71], v[146:149], v[192:195], v[68:71]
	v_mfma_f32_16x16x32_bf16 v[64:67], v[160:163], v[192:195], v[64:67]
	v_mfma_f32_16x16x32_bf16 v[56:59], v[146:149], v[200:203], v[56:59]
	v_mfma_f32_16x16x32_bf16 v[52:55], v[160:163], v[200:203], v[52:55]
	v_mfma_f32_16x16x32_bf16 v[44:47], v[146:149], v[208:211], v[44:47]
	v_mfma_f32_16x16x32_bf16 v[40:43], v[160:163], v[208:211], v[40:43]
	v_mfma_f32_16x16x32_bf16 v[76:79], v[156:159], v[188:191], v[76:79]
	v_mfma_f32_16x16x32_bf16 v[72:75], v[164:167], v[188:191], v[72:75]
	v_mfma_f32_16x16x32_bf16 v[68:71], v[156:159], v[196:199], v[68:71]
	v_mfma_f32_16x16x32_bf16 v[64:67], v[164:167], v[196:199], v[64:67]
	v_mfma_f32_16x16x32_bf16 v[56:59], v[156:159], v[204:207], v[56:59]
	v_mfma_f32_16x16x32_bf16 v[52:55], v[164:167], v[204:207], v[52:55]
	v_mfma_f32_16x16x32_bf16 v[44:47], v[156:159], v[212:215], v[44:47]
	v_mfma_f32_16x16x32_bf16 v[40:43], v[164:167], v[212:215], v[40:43]
	s_setprio 0
	s_setprio 1
	v_mfma_f32_16x16x32_bf16 v[124:127], v[168:171], v[184:187], v[124:127]
	v_mfma_f32_16x16x32_bf16 v[120:123], v[176:179], v[184:187], v[120:123]
	v_mfma_f32_16x16x32_bf16 v[116:119], v[168:171], v[192:195], v[116:119]
	v_mfma_f32_16x16x32_bf16 v[112:115], v[176:179], v[192:195], v[112:115]
	v_mfma_f32_16x16x32_bf16 v[108:111], v[168:171], v[200:203], v[108:111]
	v_mfma_f32_16x16x32_bf16 v[104:107], v[176:179], v[200:203], v[104:107]
	v_mfma_f32_16x16x32_bf16 v[100:103], v[168:171], v[208:211], v[100:103]
	v_mfma_f32_16x16x32_bf16 v[96:99], v[176:179], v[208:211], v[96:99]
	v_mfma_f32_16x16x32_bf16 v[124:127], v[172:175], v[188:191], v[124:127]
	v_mfma_f32_16x16x32_bf16 v[120:123], v[180:183], v[188:191], v[120:123]
	v_mfma_f32_16x16x32_bf16 v[116:119], v[172:175], v[196:199], v[116:119]
	v_mfma_f32_16x16x32_bf16 v[112:115], v[180:183], v[196:199], v[112:115]
	v_mfma_f32_16x16x32_bf16 v[108:111], v[172:175], v[204:207], v[108:111]
	v_mfma_f32_16x16x32_bf16 v[104:107], v[180:183], v[204:207], v[104:107]
	v_mfma_f32_16x16x32_bf16 v[100:103], v[172:175], v[212:215], v[100:103]
	s_setprio 2
	s_barrier
; #define PG8_STAGE(bufoff, gbase, voff) do { _Pragma("unroll") for (int _i = 0; _i < 2; ++_i) \
;         __builtin_amdgcn_global_load_lds((const unsigned*)((const char*)(gbase) + (voff)[_i]), (PG8_LAS unsigned*)(lds + (bufoff) + ldsw + _i * 8192), 16, 0, 0); } while (0)
; #define PG8_LDA(dst, b, h) do { _Pragma("unroll") for (int m = 0; m < 4; ++m) _Pragma("unroll") for (int k = 0; k < 2; ++k) dst[m][k] = *(const PG8_LAS bf16x8*)(lds + PG8_SA(b, h) + aoff + m * 2048 + k * 1024); } while (0)
; #define PG8_MMA(ai, bj, At, Bt) do { __builtin_amdgcn_s_setprio(1); _Pragma("unroll") for (int m = 0; m < 4; ++m) _Pragma("unroll") for (int n = 0; n < 2; ++n) _Pragma("unroll") for (int k = 0; k < 2; ++k) \
;         acc[ai][bj][m][n] = __builtin_amdgcn_mfma_f32_16x16x32_bf16(Bt[n][k], At[m][k], acc[ai][bj][m][n], 0, 0, 0); __builtin_amdgcn_s_setprio(0); } while (0)
; #define PG8_WAIT_V(n) asm volatile("s_waitcnt vmcnt(" #n ")" ::: "memory")
; #define PG8_WAIT_L(n) asm volatile("s_waitcnt lgkmcnt(" #n ")" ::: "memory")
; #define PG8_BAR __builtin_amdgcn_s_barrier()
; #define PG8_SCHED __builtin_amdgcn_sched_barrier(0)
; template <class Epi, class Sched, bool ALIGN_EPI = false, bool SP2 = false>
; __device__ __forceinline__ void gemm_phase(PG8_LAS unsigned char* lds, const Gemm g, const Sched& S, const Epi& E, const int wv  ) {
;     ...
;         for (int t = 0; t < nt; t += 2) {
;             const bool last = (t == nt - 2);
;     ...
;             PG8_WAIT_V(8); PG8_WAIT_L(0); PG8_BAR; PG8_MMA(0, 0, At, B0); PG8_MMA(0, 1, At, B1); PG8_BAR; PG8_SCHED;
;             PG8_LDA(At, 1, 1); PG8_STAGE(PG8_SB(1, 0), b3, voffB); PG8_STAGE(PG8_SB(1, 1), b3 + hstepB, voffB); PG8_STAGE(PG8_SA(1, 0), a3, voffA);
;             PG8_WAIT_V(8); PG8_WAIT_L(0); PG8_BAR; PG8_MMA(1, 0, At, B0); PG8_MMA(1, 1, At, B1); PG8_BAR; PG8_SCHED;
	v_mfma_f32_16x16x32_bf16 v[96:99], v[180:183], v[212:215], v[96:99]
	s_setprio 0
	s_add_i32 s52, s86, s63
	v_lshl_add_u64 v[216:217], v[216:217], 0, s[12:13]
	s_mov_b32 m0, s52
	ds_read_b128 v[184:187], v154 offset:49152
	ds_read_b128 v[188:191], v154 offset:50176
	ds_read_b128 v[192:195], v154 offset:51200
	ds_read_b128 v[196:199], v154 offset:52224
	ds_read_b128 v[200:203], v154 offset:53248
	ds_read_b128 v[204:207], v154 offset:54272
	ds_read_b128 v[208:211], v154 offset:55296
	ds_read_b128 v[212:215], v154 offset:56320
	global_load_lds_dwordx4 v[216:217], off
	s_add_i32 m0, s52, 0x2000
	s_add_u32 s52, s56, 0x2b0080
	v_lshl_add_u64 v[216:217], v[218:219], 0, s[12:13]
	s_addc_u32 s53, s57, 0
	s_add_i32 s56, s87, s63
	global_load_lds_dwordx4 v[216:217], off
	v_lshl_add_u64 v[216:217], s[52:53], 0, v[130:131]
	s_mov_b32 m0, s56
	s_nop 0
	global_load_lds_dwordx4 v[216:217], off
	v_lshl_add_u64 v[216:217], s[52:53], 0, v[134:135]
	s_add_i32 m0, s56, 0x2000
	s_nop 0
	global_load_lds_dwordx4 v[216:217], off
	v_lshl_add_u64 v[216:217], v[220:221], 0, s[12:13]
	s_mov_b32 m0, s70
	s_nop 0
	global_load_lds_dwordx4 v[216:217], off
	v_lshl_add_u64 v[216:217], v[222:223], 0, s[12:13]
	s_mov_b32 m0, s71
	s_nop 0
	global_load_lds_dwordx4 v[216:217], off
	s_waitcnt vmcnt(8)
	s_waitcnt lgkmcnt(0)
	s_barrier
	s_setprio 1
	s_waitcnt lgkmcnt(0)
	v_mfma_f32_16x16x32_bf16 v[28:31], v[146:149], v[184:187], v[28:31]
	v_mfma_f32_16x16x32_bf16 v[24:27], v[160:163], v[184:187], v[24:27]
	v_mfma_f32_16x16x32_bf16 v[20:23], v[146:149], v[192:195], v[20:23]
	v_mfma_f32_16x16x32_bf16 v[16:19], v[160:163], v[192:195], v[16:19]
	v_mfma_f32_16x16x32_bf16 v[12:15], v[146:149], v[200:203], v[12:15]
	v_mfma_f32_16x16x32_bf16 v[8:11], v[160:163], v[200:203], v[8:11]
	v_mfma_f32_16x16x32_bf16 v[4:7], v[146:149], v[208:211], v[4:7]
	v_mfma_f32_16x16x32_bf16 v[0:3], v[160:163], v[208:211], v[0:3]
	v_mfma_f32_16x16x32_bf16 v[28:31], v[156:159], v[188:191], v[28:31]
	v_mfma_f32_16x16x32_bf16 v[24:27], v[164:167], v[188:191], v[24:27]
	v_mfma_f32_16x16x32_bf16 v[20:23], v[156:159], v[196:199], v[20:23]
	v_mfma_f32_16x16x32_bf16 v[16:19], v[164:167], v[196:199], v[16:19]
	v_mfma_f32_16x16x32_bf16 v[12:15], v[156:159], v[204:207], v[12:15]
	v_mfma_f32_16x16x32_bf16 v[8:11], v[164:167], v[204:207], v[8:11]
	v_mfma_f32_16x16x32_bf16 v[4:7], v[156:159], v[212:215], v[4:7]
	v_mfma_f32_16x16x32_bf16 v[0:3], v[164:167], v[212:215], v[0:3]
	s_setprio 0
	s_setprio 1
	v_mfma_f32_16x16x32_bf16 v[92:95], v[168:171], v[184:187], v[92:95]
	v_mfma_f32_16x16x32_bf16 v[88:91], v[176:179], v[184:187], v[88:91]
	v_mfma_f32_16x16x32_bf16 v[84:87], v[168:171], v[192:195], v[84:87]
	v_mfma_f32_16x16x32_bf16 v[80:83], v[176:179], v[192:195], v[80:83]
	v_mfma_f32_16x16x32_bf16 v[60:63], v[168:171], v[200:203], v[60:63]
	v_mfma_f32_16x16x32_bf16 v[48:51], v[176:179], v[200:203], v[48:51]
	v_mfma_f32_16x16x32_bf16 v[36:39], v[168:171], v[208:211], v[36:39]
	v_mfma_f32_16x16x32_bf16 v[32:35], v[176:179], v[208:211], v[32:35]
	v_mfma_f32_16x16x32_bf16 v[92:95], v[172:175], v[188:191], v[92:95]
	v_mfma_f32_16x16x32_bf16 v[88:91], v[180:183], v[188:191], v[88:91]
	v_mfma_f32_16x16x32_bf16 v[84:87], v[172:175], v[196:199], v[84:87]
	v_mfma_f32_16x16x32_bf16 v[80:83], v[180:183], v[196:199], v[80:83]
	v_mfma_f32_16x16x32_bf16 v[60:63], v[172:175], v[204:207], v[60:63]
	v_mfma_f32_16x16x32_bf16 v[48:51], v[180:183], v[204:207], v[48:51]
	v_mfma_f32_16x16x32_bf16 v[36:39], v[172:175], v[212:215], v[36:39]
	s_setprio 2
	s_barrier
	v_mfma_f32_16x16x32_bf16 v[32:35], v[180:183], v[212:215], v[32:35]
	s_setprio 0
	s_add_i32 s85, s85, 2
	s_add_u32 s83, s83, 0x100
	s_addc_u32 s84, s84, 0
	s_cmpk_gt_u32 s85, 0xa9
	s_mov_b64 s[52:53], s[54:55]
	s_cbranch_scc0 .LBB0_1544
	s_and_b64 vcc, exec, s[14:15]
	s_cbranch_vccz .LBB0_1547
	s_barrier

; #define PG8_STAGE(bufoff, gbase, voff) do { _Pragma("unroll") for (int _i = 0; _i < 2; ++_i) \
;         __builtin_amdgcn_global_load_lds((const unsigned*)((const char*)(gbase) + (voff)[_i]), (PG8_LAS unsigned*)(lds + (bufoff) + ldsw + _i * 8192), 16, 0, 0); } while (0)
; #define PG8_LDA(dst, b, h) do { _Pragma("unroll") for (int m = 0; m < 4; ++m) _Pragma("unroll") for (int k = 0; k < 2; ++k) dst[m][k] = *(const PG8_LAS bf16x8*)(lds + PG8_SA(b, h) + aoff + m * 2048 + k * 1024); } while (0)
; #define PG8_LDB(dst, b, h) do { _Pragma("unroll") for (int n = 0; n < 2; ++n) _Pragma("unroll") for (int k = 0; k < 2; ++k) dst[n][k] = *(const PG8_LAS bf16x8*)(lds + PG8_SB(b, h) + boff + n * 2048 + k * 1024); } while (0)
; #define PG8_MMA(ai, bj, At, Bt) do { __builtin_amdgcn_s_setprio(1); _Pragma("unroll") for (int m = 0; m < 4; ++m) _Pragma("unroll") for (int n = 0; n < 2; ++n) _Pragma("unroll") for (int k = 0; k < 2; ++k) \
;         acc[ai][bj][m][n] = __builtin_amdgcn_mfma_f32_16x16x32_bf16(Bt[n][k], At[m][k], acc[ai][bj][m][n], 0, 0, 0); __builtin_amdgcn_s_setprio(0); } while (0)
; #define PG8_WAIT_V(n) asm volatile("s_waitcnt vmcnt(" #n ")" ::: "memory")
; #define PG8_WAIT_L(n) asm volatile("s_waitcnt lgkmcnt(" #n ")" ::: "memory")
; template <class Epi, class Sched, bool ALIGN_EPI = false, bool SP2 = false>
; __device__ __forceinline__ void gemm_phase(PG8_LAS unsigned char* lds, const Gemm g, const Sched& S, const Epi& E, const int wv  ) {
;     ...
;             const bool last = (t == nt - 2);
;             const char* a1 = cA + (size_t)(t + 1) * kstep;
;             const char* a2 = last ? nA : cA + (size_t)(t + 2) * kstep; const char* b2 = last ? nB : cB + (size_t)(t + 2) * kstep;
;             const char* a3 = a2 + kstep; const char* b3 = b2 + kstep;
;             if (last && has_next) S.a_ready(nxt);
;             if constexpr (SP2) {
;             PG8_LDB(B0, 0, 0); PG8_LDB(B1, 0, 1); PG8_SCHED; PG8_LDA(At, 0, 0); PG8_STAGE(PG8_SA(1, 1), a1 + hstepA, voffA);
;             PG8_WAIT_V(8); PG8_WAIT_L(0); PG8_BAR; PG8_MMA(0, 0, At, B0); PG8_MMA(0, 1, At, B1); PG8_BAR; PG8_SCHED;
;             PG8_LDA(At, 0, 1); PG8_STAGE(PG8_SB(0, 0), b2, voffB); PG8_STAGE(PG8_SB(0, 1), b2 + hstepB, voffB); PG8_STAGE(PG8_SA(0, 0), a2, voffA);
;             PG8_WAIT_V(8); PG8_WAIT_L(0); PG8_BAR; PG8_MMA(1, 0, At, B0); PG8_MMA(1, 1, At, B1); PG8_BAR; PG8_SCHED;
.LBB0_1717:
	ds_read_b128 v[146:149], v152
	ds_read_b128 v[156:159], v152 offset:1024
	ds_read_b128 v[160:163], v152 offset:2048
	ds_read_b128 v[164:167], v152 offset:3072
	ds_read_b128 v[168:171], v153
	ds_read_b128 v[172:175], v153 offset:1024
	ds_read_b128 v[176:179], v153 offset:2048
	ds_read_b128 v[180:183], v153 offset:3072
	s_add_u32 s60, s58, 0xfff00080
	s_addc_u32 s61, s59, -1
	s_cmp_eq_u32 s87, 60
	s_cselect_b32 s63, s51, s61
	s_cselect_b32 s62, s83, s60
	s_cselect_b32 s61, s49, s86
	s_cselect_b32 s60, s84, s85
	v_lshl_add_u64 v[216:217], s[58:59], 0, v[138:139]
	s_add_i32 m0, s70, 0xc000
	ds_read_b128 v[184:187], v154
	ds_read_b128 v[188:191], v154 offset:1024
	ds_read_b128 v[192:195], v154 offset:2048
	ds_read_b128 v[196:199], v154 offset:3072
	ds_read_b128 v[200:203], v154 offset:4096
	ds_read_b128 v[204:207], v154 offset:5120
	ds_read_b128 v[208:211], v154 offset:6144
	ds_read_b128 v[212:215], v154 offset:7168
	global_load_lds_dwordx4 v[216:217], off
	v_lshl_add_u64 v[216:217], s[58:59], 0, v[140:141]
	s_add_i32 m0, s70, 0xe000
	s_nop 0
	global_load_lds_dwordx4 v[216:217], off
	s_waitcnt vmcnt(8)
	s_waitcnt lgkmcnt(0)
	s_barrier
	s_setprio 1
	s_waitcnt lgkmcnt(0)
	v_mfma_f32_16x16x32_bf16 v[76:79], v[146:149], v[184:187], v[76:79]
	v_mfma_f32_16x16x32_bf16 v[72:75], v[160:163], v[184:187], v[72:75]
	v_mfma_f32_16x16x32_bf16 v[68:71], v[146:149], v[192:195], v[68:71]
	v_mfma_f32_16x16x32_bf16 v[64:67], v[160:163], v[192:195], v[64:67]
	v_mfma_f32_16x16x32_bf16 v[56:59], v[146:149], v[200:203], v[56:59]
	v_mfma_f32_16x16x32_bf16 v[52:55], v[160:163], v[200:203], v[52:55]
	v_mfma_f32_16x16x32_bf16 v[44:47], v[146:149], v[208:211], v[44:47]
	v_mfma_f32_16x16x32_bf16 v[40:43], v[160:163], v[208:211], v[40:43]
	v_mfma_f32_16x16x32_bf16 v[76:79], v[156:159], v[188:191], v[76:79]
	v_mfma_f32_16x16x32_bf16 v[72:75], v[164:167], v[188:191], v[72:75]
	v_mfma_f32_16x16x32_bf16 v[68:71], v[156:159], v[196:199], v[68:71]
	v_mfma_f32_16x16x32_bf16 v[64:67], v[164:167], v[196:199], v[64:67]
	v_mfma_f32_16x16x32_bf16 v[56:59], v[156:159], v[204:207], v[56:59]
	v_mfma_f32_16x16x32_bf16 v[52:55], v[164:167], v[204:207], v[52:55]
	v_mfma_f32_16x16x32_bf16 v[44:47], v[156:159], v[212:215], v[44:47]
	v_mfma_f32_16x16x32_bf16 v[40:43], v[164:167], v[212:215], v[40:43]
	s_setprio 0
	s_setprio 1
	v_mfma_f32_16x16x32_bf16 v[124:127], v[168:171], v[184:187], v[124:127]
	v_mfma_f32_16x16x32_bf16 v[120:123], v[176:179], v[184:187], v[120:123]
	v_mfma_f32_16x16x32_bf16 v[116:119], v[168:171], v[192:195], v[116:119]
	v_mfma_f32_16x16x32_bf16 v[112:115], v[176:179], v[192:195], v[112:115]
	v_mfma_f32_16x16x32_bf16 v[108:111], v[168:171], v[200:203], v[108:111]
	v_mfma_f32_16x16x32_bf16 v[104:107], v[176:179], v[200:203], v[104:107]
	v_mfma_f32_16x16x32_bf16 v[100:103], v[168:171], v[208:211], v[100:103]
	v_mfma_f32_16x16x32_bf16 v[96:99], v[176:179], v[208:211], v[96:99]
	v_mfma_f32_16x16x32_bf16 v[124:127], v[172:175], v[188:191], v[124:127]
	v_mfma_f32_16x16x32_bf16 v[120:123], v[180:183], v[188:191], v[120:123]
	v_mfma_f32_16x16x32_bf16 v[116:119], v[172:175], v[196:199], v[116:119]
	v_mfma_f32_16x16x32_bf16 v[112:115], v[180:183], v[196:199], v[112:115]
	v_mfma_f32_16x16x32_bf16 v[108:111], v[172:175], v[204:207], v[108:111]
	v_mfma_f32_16x16x32_bf16 v[104:107], v[180:183], v[204:207], v[104:107]
	v_mfma_f32_16x16x32_bf16 v[100:103], v[172:175], v[212:215], v[100:103]
	s_setprio 2
	s_barrier
	v_mfma_f32_16x16x32_bf16 v[96:99], v[180:183], v[212:215], v[96:99]
	s_setprio 0
	s_add_i32 s90, s77, s69
	v_lshl_add_u64 v[216:217], s[60:61], 0, v[130:131]
	s_mov_b32 m0, s90
	ds_read_b128 v[184:187], v154 offset:16384
	ds_read_b128 v[188:191], v154 offset:17408
	ds_read_b128 v[192:195], v154 offset:18432
	ds_read_b128 v[196:199], v154 offset:19456
	ds_read_b128 v[200:203], v154 offset:20480
	ds_read_b128 v[204:207], v154 offset:21504
	ds_read_b128 v[208:211], v154 offset:22528
	ds_read_b128 v[212:215], v154 offset:23552
	global_load_lds_dwordx4 v[216:217], off
	s_add_i32 m0, s90, 0x2000
	s_add_u32 s90, s60, 0x100000
	v_lshl_add_u64 v[218:219], s[60:61], 0, v[134:135]
	s_addc_u32 s91, s61, 0
	s_add_i32 s92, s78, s69
	global_load_lds_dwordx4 v[218:219], off
	v_lshl_add_u64 v[220:221], s[90:91], 0, v[130:131]
	s_mov_b32 m0, s92
	v_lshl_add_u64 v[222:223], s[62:63], 0, v[132:133]
	global_load_lds_dwordx4 v[220:221], off
	v_lshl_add_u64 v[220:221], s[90:91], 0, v[134:135]
	s_add_i32 m0, s92, 0x2000
	s_nop 0
	global_load_lds_dwordx4 v[220:221], off
	v_lshl_add_u64 v[220:221], s[62:63], 0, v[128:129]
	s_mov_b32 m0, s70
	s_nop 0
	global_load_lds_dwordx4 v[220:221], off
	s_mov_b32 m0, s71
	s_nop 0
	global_load_lds_dwordx4 v[222:223], off
	s_waitcnt vmcnt(8)
	s_waitcnt lgkmcnt(0)
	s_barrier
; #define PG8_STAGE(bufoff, gbase, voff) do { _Pragma("unroll") for (int _i = 0; _i < 2; ++_i) \
;         __builtin_amdgcn_global_load_lds((const unsigned*)((const char*)(gbase) + (voff)[_i]), (PG8_LAS unsigned*)(lds + (bufoff) + ldsw + _i * 8192), 16, 0, 0); } while (0)
; #define PG8_LDA(dst, b, h) do { _Pragma("unroll") for (int m = 0; m < 4; ++m) _Pragma("unroll") for (int k = 0; k < 2; ++k) dst[m][k] = *(const PG8_LAS bf16x8*)(lds + PG8_SA(b, h) + aoff + m * 2048 + k * 1024); } while (0)
; #define PG8_LDB(dst, b, h) do { _Pragma("unroll") for (int n = 0; n < 2; ++n) _Pragma("unroll") for (int k = 0; k < 2; ++k) dst[n][k] = *(const PG8_LAS bf16x8*)(lds + PG8_SB(b, h) + boff + n * 2048 + k * 1024); } while (0)
; #define PG8_MMA(ai, bj, At, Bt) do { __builtin_amdgcn_s_setprio(1); _Pragma("unroll") for (int m = 0; m < 4; ++m) _Pragma("unroll") for (int n = 0; n < 2; ++n) _Pragma("unroll") for (int k = 0; k < 2; ++k) \
;         acc[ai][bj][m][n] = __builtin_amdgcn_mfma_f32_16x16x32_bf16(Bt[n][k], At[m][k], acc[ai][bj][m][n], 0, 0, 0); __builtin_amdgcn_s_setprio(0); } while (0)
; #define PG8_WAIT_V(n) asm volatile("s_waitcnt vmcnt(" #n ")" ::: "memory")
; #define PG8_WAIT_L(n) asm volatile("s_waitcnt lgkmcnt(" #n ")" ::: "memory")
; #define PG8_BAR __builtin_amdgcn_s_barrier()
; #define PG8_SCHED __builtin_amdgcn_sched_barrier(0)
; template <class Epi, class Sched, bool ALIGN_EPI = false, bool SP2 = false>
; __device__ __forceinline__ void gemm_phase(PG8_LAS unsigned char* lds, const Gemm g, const Sched& S, const Epi& E, const int wv  ) {
;     ...
;             PG8_WAIT_V(8); PG8_WAIT_L(0); PG8_BAR; PG8_MMA(1, 0, At, B0); PG8_MMA(1, 1, At, B1); PG8_BAR; PG8_SCHED;
;             PG8_LDB(B0, 1, 0); PG8_LDB(B1, 1, 1); PG8_SCHED; PG8_LDA(At, 1, 0); PG8_STAGE(PG8_SA(0, 1), a2 + hstepA, voffA);
;             PG8_WAIT_V(8); PG8_WAIT_L(0); PG8_BAR; PG8_MMA(0, 0, At, B0); PG8_MMA(0, 1, At, B1); PG8_BAR; PG8_SCHED;
	s_setprio 1
	s_waitcnt lgkmcnt(0)
	v_mfma_f32_16x16x32_bf16 v[28:31], v[146:149], v[184:187], v[28:31]
	v_mfma_f32_16x16x32_bf16 v[24:27], v[160:163], v[184:187], v[24:27]
	v_mfma_f32_16x16x32_bf16 v[20:23], v[146:149], v[192:195], v[20:23]
	v_mfma_f32_16x16x32_bf16 v[16:19], v[160:163], v[192:195], v[16:19]
	v_mfma_f32_16x16x32_bf16 v[12:15], v[146:149], v[200:203], v[12:15]
	v_mfma_f32_16x16x32_bf16 v[8:11], v[160:163], v[200:203], v[8:11]
	v_mfma_f32_16x16x32_bf16 v[4:7], v[146:149], v[208:211], v[4:7]
	v_mfma_f32_16x16x32_bf16 v[0:3], v[160:163], v[208:211], v[0:3]
	v_mfma_f32_16x16x32_bf16 v[28:31], v[156:159], v[188:191], v[28:31]
	v_mfma_f32_16x16x32_bf16 v[24:27], v[164:167], v[188:191], v[24:27]
	v_mfma_f32_16x16x32_bf16 v[20:23], v[156:159], v[196:199], v[20:23]
	v_mfma_f32_16x16x32_bf16 v[16:19], v[164:167], v[196:199], v[16:19]
	v_mfma_f32_16x16x32_bf16 v[12:15], v[156:159], v[204:207], v[12:15]
	v_mfma_f32_16x16x32_bf16 v[8:11], v[164:167], v[204:207], v[8:11]
	v_mfma_f32_16x16x32_bf16 v[4:7], v[156:159], v[212:215], v[4:7]
	v_mfma_f32_16x16x32_bf16 v[0:3], v[164:167], v[212:215], v[0:3]
	s_setprio 0
	s_setprio 1
	v_mfma_f32_16x16x32_bf16 v[92:95], v[168:171], v[184:187], v[92:95]
	v_mfma_f32_16x16x32_bf16 v[88:91], v[176:179], v[184:187], v[88:91]
	v_mfma_f32_16x16x32_bf16 v[84:87], v[168:171], v[192:195], v[84:87]
	v_mfma_f32_16x16x32_bf16 v[80:83], v[176:179], v[192:195], v[80:83]
	v_mfma_f32_16x16x32_bf16 v[60:63], v[168:171], v[200:203], v[60:63]
	v_mfma_f32_16x16x32_bf16 v[48:51], v[176:179], v[200:203], v[48:51]
	v_mfma_f32_16x16x32_bf16 v[36:39], v[168:171], v[208:211], v[36:39]
	v_mfma_f32_16x16x32_bf16 v[32:35], v[176:179], v[208:211], v[32:35]
	v_mfma_f32_16x16x32_bf16 v[92:95], v[172:175], v[188:191], v[92:95]
	v_mfma_f32_16x16x32_bf16 v[88:91], v[180:183], v[188:191], v[88:91]
	v_mfma_f32_16x16x32_bf16 v[84:87], v[172:175], v[196:199], v[84:87]
	v_mfma_f32_16x16x32_bf16 v[80:83], v[180:183], v[196:199], v[80:83]
	v_mfma_f32_16x16x32_bf16 v[60:63], v[172:175], v[204:207], v[60:63]
	v_mfma_f32_16x16x32_bf16 v[48:51], v[180:183], v[204:207], v[48:51]
	v_mfma_f32_16x16x32_bf16 v[36:39], v[172:175], v[212:215], v[36:39]
	s_setprio 2
	s_barrier
	v_mfma_f32_16x16x32_bf16 v[32:35], v[180:183], v[212:215], v[32:35]
	s_setprio 0
	s_add_i32 s90, 0, 0x18000
	v_add_u32_e32 v155, s90, v150
	s_add_i32 s91, 0, 0x1c000
	ds_read_b128 v[146:149], v155
	ds_read_b128 v[156:159], v155 offset:1024
	ds_read_b128 v[160:163], v155 offset:2048
	ds_read_b128 v[164:167], v155 offset:3072
	v_add_u32_e32 v155, s91, v150
	ds_read_b128 v[168:171], v155
	ds_read_b128 v[172:175], v155 offset:1024
	ds_read_b128 v[176:179], v155 offset:2048
	ds_read_b128 v[180:183], v155 offset:3072
	s_add_u32 s62, s62, 0x100000
	s_addc_u32 s63, s63, 0
	s_mov_b32 m0, s72
	v_lshl_add_u64 v[224:225], s[62:63], 0, v[128:129]
	ds_read_b128 v[184:187], v154 offset:32768
	ds_read_b128 v[188:191], v154 offset:33792
	ds_read_b128 v[192:195], v154 offset:34816
	ds_read_b128 v[196:199], v154 offset:35840
	ds_read_b128 v[200:203], v154 offset:36864
	ds_read_b128 v[204:207], v154 offset:37888
	ds_read_b128 v[208:211], v154 offset:38912
	ds_read_b128 v[212:215], v154 offset:39936
	global_load_lds_dwordx4 v[224:225], off
	v_lshl_add_u64 v[224:225], s[62:63], 0, v[132:133]
	s_mov_b32 m0, s73
	s_nop 0
	global_load_lds_dwordx4 v[224:225], off
	s_waitcnt vmcnt(8)
	s_waitcnt lgkmcnt(0)
	s_barrier
	s_setprio 1
	s_waitcnt lgkmcnt(0)
	v_mfma_f32_16x16x32_bf16 v[76:79], v[146:149], v[184:187], v[76:79]
	v_mfma_f32_16x16x32_bf16 v[72:75], v[160:163], v[184:187], v[72:75]
	v_mfma_f32_16x16x32_bf16 v[68:71], v[146:149], v[192:195], v[68:71]
	v_mfma_f32_16x16x32_bf16 v[64:67], v[160:163], v[192:195], v[64:67]
	v_mfma_f32_16x16x32_bf16 v[56:59], v[146:149], v[200:203], v[56:59]
	v_mfma_f32_16x16x32_bf16 v[52:55], v[160:163], v[200:203], v[52:55]
	v_mfma_f32_16x16x32_bf16 v[44:47], v[146:149], v[208:211], v[44:47]
	v_mfma_f32_16x16x32_bf16 v[40:43], v[160:163], v[208:211], v[40:43]
	v_mfma_f32_16x16x32_bf16 v[76:79], v[156:159], v[188:191], v[76:79]
	v_mfma_f32_16x16x32_bf16 v[72:75], v[164:167], v[188:191], v[72:75]
	v_mfma_f32_16x16x32_bf16 v[68:71], v[156:159], v[196:199], v[68:71]
	v_mfma_f32_16x16x32_bf16 v[64:67], v[164:167], v[196:199], v[64:67]
	v_mfma_f32_16x16x32_bf16 v[56:59], v[156:159], v[204:207], v[56:59]
	v_mfma_f32_16x16x32_bf16 v[52:55], v[164:167], v[204:207], v[52:55]
	v_mfma_f32_16x16x32_bf16 v[44:47], v[156:159], v[212:215], v[44:47]
	v_mfma_f32_16x16x32_bf16 v[40:43], v[164:167], v[212:215], v[40:43]
	s_setprio 0
	s_setprio 1
	v_mfma_f32_16x16x32_bf16 v[124:127], v[168:171], v[184:187], v[124:127]
	v_mfma_f32_16x16x32_bf16 v[120:123], v[176:179], v[184:187], v[120:123]
	v_mfma_f32_16x16x32_bf16 v[116:119], v[168:171], v[192:195], v[116:119]
	v_mfma_f32_16x16x32_bf16 v[112:115], v[176:179], v[192:195], v[112:115]
	v_mfma_f32_16x16x32_bf16 v[108:111], v[168:171], v[200:203], v[108:111]
	v_mfma_f32_16x16x32_bf16 v[104:107], v[176:179], v[200:203], v[104:107]
	v_mfma_f32_16x16x32_bf16 v[100:103], v[168:171], v[208:211], v[100:103]
	v_mfma_f32_16x16x32_bf16 v[96:99], v[176:179], v[208:211], v[96:99]
	v_mfma_f32_16x16x32_bf16 v[124:127], v[172:175], v[188:191], v[124:127]
	v_mfma_f32_16x16x32_bf16 v[120:123], v[180:183], v[188:191], v[120:123]
	v_mfma_f32_16x16x32_bf16 v[116:119], v[172:175], v[196:199], v[116:119]
	v_mfma_f32_16x16x32_bf16 v[112:115], v[180:183], v[196:199], v[112:115]
	v_mfma_f32_16x16x32_bf16 v[108:111], v[172:175], v[204:207], v[108:111]
	v_mfma_f32_16x16x32_bf16 v[104:107], v[180:183], v[204:207], v[104:107]
	v_mfma_f32_16x16x32_bf16 v[100:103], v[172:175], v[212:215], v[100:103]
	s_setprio 2
	s_barrier
; #define PG8_STAGE(bufoff, gbase, voff) do { _Pragma("unroll") for (int _i = 0; _i < 2; ++_i) \
;         __builtin_amdgcn_global_load_lds((const unsigned*)((const char*)(gbase) + (voff)[_i]), (PG8_LAS unsigned*)(lds + (bufoff) + ldsw + _i * 8192), 16, 0, 0); } while (0)
; #define PG8_LDA(dst, b, h) do { _Pragma("unroll") for (int m = 0; m < 4; ++m) _Pragma("unroll") for (int k = 0; k < 2; ++k) dst[m][k] = *(const PG8_LAS bf16x8*)(lds + PG8_SA(b, h) + aoff + m * 2048 + k * 1024); } while (0)
; #define PG8_MMA(ai, bj, At, Bt) do { __builtin_amdgcn_s_setprio(1); _Pragma("unroll") for (int m = 0; m < 4; ++m) _Pragma("unroll") for (int n = 0; n < 2; ++n) _Pragma("unroll") for (int k = 0; k < 2; ++k) \
;         acc[ai][bj][m][n] = __builtin_amdgcn_mfma_f32_16x16x32_bf16(Bt[n][k], At[m][k], acc[ai][bj][m][n], 0, 0, 0); __builtin_amdgcn_s_setprio(0); } while (0)
; #define PG8_WAIT_V(n) asm volatile("s_waitcnt vmcnt(" #n ")" ::: "memory")
; #define PG8_WAIT_L(n) asm volatile("s_waitcnt lgkmcnt(" #n ")" ::: "memory")
; #define PG8_BAR __builtin_amdgcn_s_barrier()
; #define PG8_SCHED __builtin_amdgcn_sched_barrier(0)
; template <class Epi, class Sched, bool ALIGN_EPI = false, bool SP2 = false>
; __device__ __forceinline__ void gemm_phase(PG8_LAS unsigned char* lds, const Gemm g, const Sched& S, const Epi& E, const int wv  ) {
;     ...
;         for (int t = 0; t < nt; t += 2) {
;             const bool last = (t == nt - 2);
;     ...
;             PG8_WAIT_V(8); PG8_WAIT_L(0); PG8_BAR; PG8_MMA(0, 0, At, B0); PG8_MMA(0, 1, At, B1); PG8_BAR; PG8_SCHED;
;             PG8_LDA(At, 1, 1); PG8_STAGE(PG8_SB(1, 0), b3, voffB); PG8_STAGE(PG8_SB(1, 1), b3 + hstepB, voffB); PG8_STAGE(PG8_SA(1, 0), a3, voffA);
;             PG8_WAIT_V(8); PG8_WAIT_L(0); PG8_BAR; PG8_MMA(1, 0, At, B0); PG8_MMA(1, 1, At, B1); PG8_BAR; PG8_SCHED;
	v_mfma_f32_16x16x32_bf16 v[96:99], v[180:183], v[212:215], v[96:99]
	s_setprio 0
	s_add_i32 s62, s90, s69
	v_lshl_add_u64 v[216:217], v[216:217], 0, s[10:11]
	s_mov_b32 m0, s62
	ds_read_b128 v[184:187], v154 offset:49152
	ds_read_b128 v[188:191], v154 offset:50176
	ds_read_b128 v[192:195], v154 offset:51200
	ds_read_b128 v[196:199], v154 offset:52224
	ds_read_b128 v[200:203], v154 offset:53248
	ds_read_b128 v[204:207], v154 offset:54272
	ds_read_b128 v[208:211], v154 offset:55296
	ds_read_b128 v[212:215], v154 offset:56320
	global_load_lds_dwordx4 v[216:217], off
	s_add_i32 m0, s62, 0x2000
	s_add_u32 s60, s60, 0x100080
	v_lshl_add_u64 v[216:217], v[218:219], 0, s[10:11]
	s_addc_u32 s61, s61, 0
	s_add_i32 s62, s91, s69
	global_load_lds_dwordx4 v[216:217], off
	v_lshl_add_u64 v[216:217], s[60:61], 0, v[130:131]
	s_mov_b32 m0, s62
	s_nop 0
	global_load_lds_dwordx4 v[216:217], off
	v_lshl_add_u64 v[216:217], s[60:61], 0, v[134:135]
	s_add_i32 m0, s62, 0x2000
	s_nop 0
	global_load_lds_dwordx4 v[216:217], off
	v_lshl_add_u64 v[216:217], v[220:221], 0, s[10:11]
	s_mov_b32 m0, s64
	s_nop 0
	global_load_lds_dwordx4 v[216:217], off
	v_lshl_add_u64 v[216:217], v[222:223], 0, s[10:11]
	s_mov_b32 m0, s65
	s_nop 0
	global_load_lds_dwordx4 v[216:217], off
	s_waitcnt vmcnt(8)
	s_waitcnt lgkmcnt(0)
	s_barrier
	s_setprio 1
	s_waitcnt lgkmcnt(0)
	v_mfma_f32_16x16x32_bf16 v[28:31], v[146:149], v[184:187], v[28:31]
	v_mfma_f32_16x16x32_bf16 v[24:27], v[160:163], v[184:187], v[24:27]
	v_mfma_f32_16x16x32_bf16 v[20:23], v[146:149], v[192:195], v[20:23]
	v_mfma_f32_16x16x32_bf16 v[16:19], v[160:163], v[192:195], v[16:19]
	v_mfma_f32_16x16x32_bf16 v[12:15], v[146:149], v[200:203], v[12:15]
	v_mfma_f32_16x16x32_bf16 v[8:11], v[160:163], v[200:203], v[8:11]
	v_mfma_f32_16x16x32_bf16 v[4:7], v[146:149], v[208:211], v[4:7]
	v_mfma_f32_16x16x32_bf16 v[0:3], v[160:163], v[208:211], v[0:3]
	v_mfma_f32_16x16x32_bf16 v[28:31], v[156:159], v[188:191], v[28:31]
	v_mfma_f32_16x16x32_bf16 v[24:27], v[164:167], v[188:191], v[24:27]
	v_mfma_f32_16x16x32_bf16 v[20:23], v[156:159], v[196:199], v[20:23]
	v_mfma_f32_16x16x32_bf16 v[16:19], v[164:167], v[196:199], v[16:19]
	v_mfma_f32_16x16x32_bf16 v[12:15], v[156:159], v[204:207], v[12:15]
	v_mfma_f32_16x16x32_bf16 v[8:11], v[164:167], v[204:207], v[8:11]
	v_mfma_f32_16x16x32_bf16 v[4:7], v[156:159], v[212:215], v[4:7]
	v_mfma_f32_16x16x32_bf16 v[0:3], v[164:167], v[212:215], v[0:3]
	s_setprio 0
	s_setprio 1
	v_mfma_f32_16x16x32_bf16 v[92:95], v[168:171], v[184:187], v[92:95]
	v_mfma_f32_16x16x32_bf16 v[88:91], v[176:179], v[184:187], v[88:91]
	v_mfma_f32_16x16x32_bf16 v[84:87], v[168:171], v[192:195], v[84:87]
	v_mfma_f32_16x16x32_bf16 v[80:83], v[176:179], v[192:195], v[80:83]
	v_mfma_f32_16x16x32_bf16 v[60:63], v[168:171], v[200:203], v[60:63]
	v_mfma_f32_16x16x32_bf16 v[48:51], v[176:179], v[200:203], v[48:51]
	v_mfma_f32_16x16x32_bf16 v[36:39], v[168:171], v[208:211], v[36:39]
	v_mfma_f32_16x16x32_bf16 v[32:35], v[176:179], v[208:211], v[32:35]
	v_mfma_f32_16x16x32_bf16 v[92:95], v[172:175], v[188:191], v[92:95]
	v_mfma_f32_16x16x32_bf16 v[88:91], v[180:183], v[188:191], v[88:91]
	v_mfma_f32_16x16x32_bf16 v[84:87], v[172:175], v[196:199], v[84:87]
	v_mfma_f32_16x16x32_bf16 v[80:83], v[180:183], v[196:199], v[80:83]
	v_mfma_f32_16x16x32_bf16 v[60:63], v[172:175], v[204:207], v[60:63]
	v_mfma_f32_16x16x32_bf16 v[48:51], v[180:183], v[204:207], v[48:51]
	v_mfma_f32_16x16x32_bf16 v[36:39], v[172:175], v[212:215], v[36:39]
	s_setprio 2
	s_barrier
	v_mfma_f32_16x16x32_bf16 v[32:35], v[180:183], v[212:215], v[32:35]
	s_setprio 0
	s_add_i32 s87, s87, 2
	s_add_u32 s58, s58, 0x100
	s_addc_u32 s59, s59, 0
	s_add_u32 s85, s85, 0x100
	s_addc_u32 s86, s86, 0
	s_cmp_gt_u32 s87, 61
	s_cbranch_scc0 .LBB0_1717
	s_and_b64 vcc, exec, s[12:13]
	s_cbranch_vccz .LBB0_1720
	s_barrier

; #define PG8_STAGE(bufoff, gbase, voff) do { _Pragma("unroll") for (int _i = 0; _i < 2; ++_i) \
;         __builtin_amdgcn_global_load_lds((const unsigned*)((const char*)(gbase) + (voff)[_i]), (PG8_LAS unsigned*)(lds + (bufoff) + ldsw + _i * 8192), 16, 0, 0); } while (0)
; #define PG8_LDA(dst, b, h) do { _Pragma("unroll") for (int m = 0; m < 4; ++m) _Pragma("unroll") for (int k = 0; k < 2; ++k) dst[m][k] = *(const PG8_LAS bf16x8*)(lds + PG8_SA(b, h) + aoff + m * 2048 + k * 1024); } while (0)
; #define PG8_LDB(dst, b, h) do { _Pragma("unroll") for (int n = 0; n < 2; ++n) _Pragma("unroll") for (int k = 0; k < 2; ++k) dst[n][k] = *(const PG8_LAS bf16x8*)(lds + PG8_SB(b, h) + boff + n * 2048 + k * 1024); } while (0)
; #define PG8_MMA(ai, bj, At, Bt) do { __builtin_amdgcn_s_setprio(1); _Pragma("unroll") for (int m = 0; m < 4; ++m) _Pragma("unroll") for (int n = 0; n < 2; ++n) _Pragma("unroll") for (int k = 0; k < 2; ++k) \
;         acc[ai][bj][m][n] = __builtin_amdgcn_mfma_f32_16x16x32_bf16(Bt[n][k], At[m][k], acc[ai][bj][m][n], 0, 0, 0); __builtin_amdgcn_s_setprio(0); } while (0)
; #define PG8_WAIT_V(n) asm volatile("s_waitcnt vmcnt(" #n ")" ::: "memory")
; #define PG8_WAIT_L(n) asm volatile("s_waitcnt lgkmcnt(" #n ")" ::: "memory")
; template <class Epi, class Sched, bool ALIGN_EPI = false, bool SP2 = false>
; __device__ __forceinline__ void gemm_phase(PG8_LAS unsigned char* lds, const Gemm g, const Sched& S, const Epi& E, const int wv  ) {
;     ...
;             const bool last = (t == nt - 2);
;             const char* a1 = cA + (size_t)(t + 1) * kstep;
;             const char* a2 = last ? nA : cA + (size_t)(t + 2) * kstep; const char* b2 = last ? nB : cB + (size_t)(t + 2) * kstep;
;             const char* a3 = a2 + kstep; const char* b3 = b2 + kstep;
;             if (last && has_next) S.a_ready(nxt);
;             if constexpr (SP2) {
;             PG8_LDB(B0, 0, 0); PG8_LDB(B1, 0, 1); PG8_SCHED; PG8_LDA(At, 0, 0); PG8_STAGE(PG8_SA(1, 1), a1 + hstepA, voffA);
;             PG8_WAIT_V(8); PG8_WAIT_L(0); PG8_BAR; PG8_MMA(0, 0, At, B0); PG8_MMA(0, 1, At, B1); PG8_BAR; PG8_SCHED;
;             PG8_LDA(At, 0, 1); PG8_STAGE(PG8_SB(0, 0), b2, voffB); PG8_STAGE(PG8_SB(0, 1), b2 + hstepB, voffB); PG8_STAGE(PG8_SA(0, 0), a2, voffA);
;             PG8_WAIT_V(8); PG8_WAIT_L(0); PG8_BAR; PG8_MMA(1, 0, At, B0); PG8_MMA(1, 1, At, B1); PG8_BAR; PG8_SCHED;
.LBB0_2399:
	ds_read_b128 v[44:47], v196
	ds_read_b128 v[48:51], v196 offset:1024
	ds_read_b128 v[52:55], v196 offset:2048
	ds_read_b128 v[56:59], v196 offset:3072
	ds_read_b128 v[60:63], v197
	ds_read_b128 v[68:71], v197 offset:1024
	ds_read_b128 v[72:75], v197 offset:2048
	ds_read_b128 v[76:79], v197 offset:3072
	s_add_u32 s68, s66, 0xfff00080
	s_addc_u32 s69, s67, -1
	s_cmp_eq_u32 s94, 60
	s_cselect_b32 s71, s57, s69
	s_cselect_b32 s70, s63, s68
	s_cselect_b32 s69, s55, s93
	s_cselect_b32 s68, s65, s92
	v_lshl_add_u64 v[224:225], s[66:67], 0, v[172:173]
	s_add_i32 m0, s75, 0xc000
	ds_read_b128 v[180:183], v198
	ds_read_b128 v[184:187], v198 offset:1024
	ds_read_b128 v[200:203], v198 offset:2048
	ds_read_b128 v[204:207], v198 offset:3072
	ds_read_b128 v[208:211], v198 offset:4096
	ds_read_b128 v[212:215], v198 offset:5120
	ds_read_b128 v[216:219], v198 offset:6144
	ds_read_b128 v[220:223], v198 offset:7168
	global_load_lds_dwordx4 v[224:225], off
	v_lshl_add_u64 v[224:225], s[66:67], 0, v[174:175]
	s_add_i32 m0, s75, 0xe000
	s_nop 0
	global_load_lds_dwordx4 v[224:225], off
	s_waitcnt vmcnt(8)
	s_waitcnt lgkmcnt(0)
	s_barrier
	s_setprio 1
	s_waitcnt lgkmcnt(0)
	v_mfma_f32_16x16x32_bf16 v[104:107], v[44:47], v[180:183], v[104:107]
	v_mfma_f32_16x16x32_bf16 v[100:103], v[52:55], v[180:183], v[100:103]
	v_mfma_f32_16x16x32_bf16 v[156:159], v[44:47], v[200:203], v[156:159]
	v_mfma_f32_16x16x32_bf16 v[148:151], v[52:55], v[200:203], v[148:151]
	v_mfma_f32_16x16x32_bf16 v[140:143], v[44:47], v[208:211], v[140:143]
	v_mfma_f32_16x16x32_bf16 v[132:135], v[52:55], v[208:211], v[132:135]
	v_mfma_f32_16x16x32_bf16 v[124:127], v[44:47], v[216:219], v[124:127]
	v_mfma_f32_16x16x32_bf16 v[120:123], v[52:55], v[216:219], v[120:123]
	v_mfma_f32_16x16x32_bf16 v[104:107], v[48:51], v[184:187], v[104:107]
	v_mfma_f32_16x16x32_bf16 v[100:103], v[56:59], v[184:187], v[100:103]
	v_mfma_f32_16x16x32_bf16 v[156:159], v[48:51], v[204:207], v[156:159]
	v_mfma_f32_16x16x32_bf16 v[148:151], v[56:59], v[204:207], v[148:151]
	v_mfma_f32_16x16x32_bf16 v[140:143], v[48:51], v[212:215], v[140:143]
	v_mfma_f32_16x16x32_bf16 v[132:135], v[56:59], v[212:215], v[132:135]
	v_mfma_f32_16x16x32_bf16 v[124:127], v[48:51], v[220:223], v[124:127]
	v_mfma_f32_16x16x32_bf16 v[120:123], v[56:59], v[220:223], v[120:123]
	s_setprio 0
	s_setprio 1
	v_mfma_f32_16x16x32_bf16 v[92:95], v[60:63], v[180:183], v[92:95]
	v_mfma_f32_16x16x32_bf16 v[88:91], v[72:75], v[180:183], v[88:91]
	v_mfma_f32_16x16x32_bf16 v[152:155], v[60:63], v[200:203], v[152:155]
	v_mfma_f32_16x16x32_bf16 v[144:147], v[72:75], v[200:203], v[144:147]
	v_mfma_f32_16x16x32_bf16 v[136:139], v[60:63], v[208:211], v[136:139]
	v_mfma_f32_16x16x32_bf16 v[128:131], v[72:75], v[208:211], v[128:131]
	v_mfma_f32_16x16x32_bf16 v[116:119], v[60:63], v[216:219], v[116:119]
	v_mfma_f32_16x16x32_bf16 v[112:115], v[72:75], v[216:219], v[112:115]
	v_mfma_f32_16x16x32_bf16 v[92:95], v[68:71], v[184:187], v[92:95]
	v_mfma_f32_16x16x32_bf16 v[88:91], v[76:79], v[184:187], v[88:91]
	v_mfma_f32_16x16x32_bf16 v[152:155], v[68:71], v[204:207], v[152:155]
	v_mfma_f32_16x16x32_bf16 v[144:147], v[76:79], v[204:207], v[144:147]
	v_mfma_f32_16x16x32_bf16 v[136:139], v[68:71], v[212:215], v[136:139]
	v_mfma_f32_16x16x32_bf16 v[128:131], v[76:79], v[212:215], v[128:131]
	v_mfma_f32_16x16x32_bf16 v[116:119], v[68:71], v[220:223], v[116:119]
	s_setprio 2
	s_barrier
	v_mfma_f32_16x16x32_bf16 v[112:115], v[76:79], v[220:223], v[112:115]
	s_setprio 0
	s_add_i32 s95, s87, s74
	v_lshl_add_u64 v[228:229], s[68:69], 0, v[162:163]
	s_mov_b32 m0, s95
	ds_read_b128 v[180:183], v198 offset:16384
	ds_read_b128 v[184:187], v198 offset:17408
	ds_read_b128 v[200:203], v198 offset:18432
	ds_read_b128 v[204:207], v198 offset:19456
	ds_read_b128 v[208:211], v198 offset:20480
	ds_read_b128 v[212:215], v198 offset:21504
	ds_read_b128 v[216:219], v198 offset:22528
	ds_read_b128 v[220:223], v198 offset:23552
	global_load_lds_dwordx4 v[228:229], off
	s_add_i32 m0, s95, 0x2000
	s_add_u32 s96, s68, 0x100000
	v_lshl_add_u64 v[230:231], s[68:69], 0, v[166:167]
	s_addc_u32 s97, s69, 0
	s_add_i32 s95, s90, s74
	global_load_lds_dwordx4 v[230:231], off
	v_lshl_add_u64 v[224:225], s[96:97], 0, v[162:163]
	s_mov_b32 m0, s95
	v_lshl_add_u64 v[232:233], s[70:71], 0, v[160:161]
	global_load_lds_dwordx4 v[224:225], off
	v_lshl_add_u64 v[224:225], s[96:97], 0, v[166:167]
	s_add_i32 m0, s95, 0x2000
	v_lshl_add_u64 v[234:235], s[70:71], 0, v[164:165]
	global_load_lds_dwordx4 v[224:225], off
	s_mov_b32 m0, s75
	s_nop 0
	global_load_lds_dwordx4 v[232:233], off
	s_mov_b32 m0, s76
	s_nop 0
	global_load_lds_dwordx4 v[234:235], off
	s_waitcnt vmcnt(8)
	s_waitcnt lgkmcnt(0)
	s_barrier
; #define PG8_STAGE(bufoff, gbase, voff) do { _Pragma("unroll") for (int _i = 0; _i < 2; ++_i) \
;         __builtin_amdgcn_global_load_lds((const unsigned*)((const char*)(gbase) + (voff)[_i]), (PG8_LAS unsigned*)(lds + (bufoff) + ldsw + _i * 8192), 16, 0, 0); } while (0)
; #define PG8_LDA(dst, b, h) do { _Pragma("unroll") for (int m = 0; m < 4; ++m) _Pragma("unroll") for (int k = 0; k < 2; ++k) dst[m][k] = *(const PG8_LAS bf16x8*)(lds + PG8_SA(b, h) + aoff + m * 2048 + k * 1024); } while (0)
; #define PG8_LDB(dst, b, h) do { _Pragma("unroll") for (int n = 0; n < 2; ++n) _Pragma("unroll") for (int k = 0; k < 2; ++k) dst[n][k] = *(const PG8_LAS bf16x8*)(lds + PG8_SB(b, h) + boff + n * 2048 + k * 1024); } while (0)
; #define PG8_MMA(ai, bj, At, Bt) do { __builtin_amdgcn_s_setprio(1); _Pragma("unroll") for (int m = 0; m < 4; ++m) _Pragma("unroll") for (int n = 0; n < 2; ++n) _Pragma("unroll") for (int k = 0; k < 2; ++k) \
;         acc[ai][bj][m][n] = __builtin_amdgcn_mfma_f32_16x16x32_bf16(Bt[n][k], At[m][k], acc[ai][bj][m][n], 0, 0, 0); __builtin_amdgcn_s_setprio(0); } while (0)
; #define PG8_WAIT_V(n) asm volatile("s_waitcnt vmcnt(" #n ")" ::: "memory")
; #define PG8_WAIT_L(n) asm volatile("s_waitcnt lgkmcnt(" #n ")" ::: "memory")
; #define PG8_BAR __builtin_amdgcn_s_barrier()
; #define PG8_SCHED __builtin_amdgcn_sched_barrier(0)
; template <class Epi, class Sched, bool ALIGN_EPI = false, bool SP2 = false>
; __device__ __forceinline__ void gemm_phase(PG8_LAS unsigned char* lds, const Gemm g, const Sched& S, const Epi& E, const int wv  ) {
;     ...
;             PG8_WAIT_V(8); PG8_WAIT_L(0); PG8_BAR; PG8_MMA(1, 0, At, B0); PG8_MMA(1, 1, At, B1); PG8_BAR; PG8_SCHED;
;             PG8_LDB(B0, 1, 0); PG8_LDB(B1, 1, 1); PG8_SCHED; PG8_LDA(At, 1, 0); PG8_STAGE(PG8_SA(0, 1), a2 + hstepA, voffA);
;             PG8_WAIT_V(8); PG8_WAIT_L(0); PG8_BAR; PG8_MMA(0, 0, At, B0); PG8_MMA(0, 1, At, B1); PG8_BAR; PG8_SCHED;
	s_setprio 1
	s_waitcnt lgkmcnt(0)
	v_mfma_f32_16x16x32_bf16 v[108:111], v[44:47], v[180:183], v[108:111]
	v_mfma_f32_16x16x32_bf16 v[96:99], v[52:55], v[180:183], v[96:99]
	v_mfma_f32_16x16x32_bf16 v[64:67], v[44:47], v[200:203], v[64:67]
	v_mfma_f32_16x16x32_bf16 v[36:39], v[52:55], v[200:203], v[36:39]
	v_mfma_f32_16x16x32_bf16 v[28:31], v[44:47], v[208:211], v[28:31]
	v_mfma_f32_16x16x32_bf16 v[20:23], v[52:55], v[208:211], v[20:23]
	v_mfma_f32_16x16x32_bf16 v[12:15], v[44:47], v[216:219], v[12:15]
	v_mfma_f32_16x16x32_bf16 v[4:7], v[52:55], v[216:219], v[4:7]
	v_mfma_f32_16x16x32_bf16 v[108:111], v[48:51], v[184:187], v[108:111]
	v_mfma_f32_16x16x32_bf16 v[96:99], v[56:59], v[184:187], v[96:99]
	v_mfma_f32_16x16x32_bf16 v[64:67], v[48:51], v[204:207], v[64:67]
	v_mfma_f32_16x16x32_bf16 v[36:39], v[56:59], v[204:207], v[36:39]
	v_mfma_f32_16x16x32_bf16 v[28:31], v[48:51], v[212:215], v[28:31]
	v_mfma_f32_16x16x32_bf16 v[20:23], v[56:59], v[212:215], v[20:23]
	v_mfma_f32_16x16x32_bf16 v[12:15], v[48:51], v[220:223], v[12:15]
	v_mfma_f32_16x16x32_bf16 v[4:7], v[56:59], v[220:223], v[4:7]
	s_setprio 0
	s_setprio 1
	v_mfma_f32_16x16x32_bf16 v[40:43], v[60:63], v[200:203], v[40:43]
	v_mfma_f32_16x16x32_bf16 v[32:35], v[72:75], v[200:203], v[32:35]
	v_mfma_f32_16x16x32_bf16 v[24:27], v[60:63], v[208:211], v[24:27]
	v_mfma_f32_16x16x32_bf16 v[16:19], v[72:75], v[208:211], v[16:19]
	v_mfma_f32_16x16x32_bf16 v[8:11], v[60:63], v[216:219], v[8:11]
	v_mfma_f32_16x16x32_bf16 v[0:3], v[72:75], v[216:219], v[0:3]
	v_mfma_f32_16x16x32_bf16 v[44:47], v[60:63], v[180:183], v[84:87]
	v_mfma_f32_16x16x32_bf16 v[48:51], v[72:75], v[180:183], v[80:83]
	v_mfma_f32_16x16x32_bf16 v[40:43], v[68:71], v[204:207], v[40:43]
	v_mfma_f32_16x16x32_bf16 v[32:35], v[76:79], v[204:207], v[32:35]
	v_mfma_f32_16x16x32_bf16 v[24:27], v[68:71], v[212:215], v[24:27]
	v_mfma_f32_16x16x32_bf16 v[16:19], v[76:79], v[212:215], v[16:19]
	v_mfma_f32_16x16x32_bf16 v[8:11], v[68:71], v[220:223], v[8:11]
	v_mfma_f32_16x16x32_bf16 v[0:3], v[76:79], v[220:223], v[0:3]
	v_mfma_f32_16x16x32_bf16 v[44:47], v[68:71], v[184:187], v[44:47]
	s_setprio 2
	s_barrier
	v_mfma_f32_16x16x32_bf16 v[48:51], v[76:79], v[184:187], v[48:51]
	s_setprio 0
	s_add_i32 s95, 0, 0x18000
	s_add_i32 s96, 0, 0x1c000
	v_add_u32_e32 v68, s95, v190
	v_add_u32_e32 v80, s96, v190
	ds_read_b128 v[52:55], v68
	ds_read_b128 v[56:59], v68 offset:1024
	ds_read_b128 v[60:63], v68 offset:2048
	ds_read_b128 v[68:71], v68 offset:3072
	ds_read_b128 v[72:75], v80
	ds_read_b128 v[76:79], v80 offset:1024
	ds_read_b128 v[180:183], v80 offset:2048
	ds_read_b128 v[184:187], v80 offset:3072
	s_add_u32 s70, s70, 0x100000
	s_addc_u32 s71, s71, 0
	s_mov_b32 m0, s77
	v_lshl_add_u64 v[224:225], s[70:71], 0, v[160:161]
	ds_read_b128 v[80:83], v198 offset:32768
	ds_read_b128 v[84:87], v198 offset:33792
	ds_read_b128 v[200:203], v198 offset:34816
	ds_read_b128 v[204:207], v198 offset:35840
	ds_read_b128 v[208:211], v198 offset:36864
	ds_read_b128 v[212:215], v198 offset:37888
	ds_read_b128 v[216:219], v198 offset:38912
	ds_read_b128 v[220:223], v198 offset:39936
	global_load_lds_dwordx4 v[224:225], off
	v_lshl_add_u64 v[224:225], s[70:71], 0, v[164:165]
	s_mov_b32 m0, s78
	s_nop 0
	global_load_lds_dwordx4 v[224:225], off
	s_waitcnt vmcnt(8)
	s_waitcnt lgkmcnt(0)
	s_barrier
	s_setprio 1
	s_waitcnt lgkmcnt(0)
	v_mfma_f32_16x16x32_bf16 v[104:107], v[52:55], v[80:83], v[104:107]
	v_mfma_f32_16x16x32_bf16 v[100:103], v[60:63], v[80:83], v[100:103]
	v_mfma_f32_16x16x32_bf16 v[156:159], v[52:55], v[200:203], v[156:159]
	v_mfma_f32_16x16x32_bf16 v[148:151], v[60:63], v[200:203], v[148:151]
	v_mfma_f32_16x16x32_bf16 v[140:143], v[52:55], v[208:211], v[140:143]
	v_mfma_f32_16x16x32_bf16 v[132:135], v[60:63], v[208:211], v[132:135]
	v_mfma_f32_16x16x32_bf16 v[124:127], v[52:55], v[216:219], v[124:127]
	v_mfma_f32_16x16x32_bf16 v[120:123], v[60:63], v[216:219], v[120:123]
	v_mfma_f32_16x16x32_bf16 v[104:107], v[56:59], v[84:87], v[104:107]
	v_mfma_f32_16x16x32_bf16 v[100:103], v[68:71], v[84:87], v[100:103]
	v_mfma_f32_16x16x32_bf16 v[156:159], v[56:59], v[204:207], v[156:159]
	v_mfma_f32_16x16x32_bf16 v[148:151], v[68:71], v[204:207], v[148:151]
	v_mfma_f32_16x16x32_bf16 v[140:143], v[56:59], v[212:215], v[140:143]
	v_mfma_f32_16x16x32_bf16 v[132:135], v[68:71], v[212:215], v[132:135]
	v_mfma_f32_16x16x32_bf16 v[124:127], v[56:59], v[220:223], v[124:127]
	v_mfma_f32_16x16x32_bf16 v[120:123], v[68:71], v[220:223], v[120:123]
	s_setprio 0
	s_setprio 1
	v_mfma_f32_16x16x32_bf16 v[92:95], v[72:75], v[80:83], v[92:95]
	v_mfma_f32_16x16x32_bf16 v[80:83], v[180:183], v[80:83], v[88:91]
	v_mfma_f32_16x16x32_bf16 v[88:91], v[184:187], v[84:87], v[80:83]
	v_mfma_f32_16x16x32_bf16 v[80:83], v[72:75], v[200:203], v[152:155]
	v_mfma_f32_16x16x32_bf16 v[152:155], v[76:79], v[204:207], v[80:83]
	v_mfma_f32_16x16x32_bf16 v[80:83], v[180:183], v[200:203], v[144:147]
	v_mfma_f32_16x16x32_bf16 v[144:147], v[184:187], v[204:207], v[80:83]
	v_mfma_f32_16x16x32_bf16 v[80:83], v[72:75], v[208:211], v[136:139]
	v_mfma_f32_16x16x32_bf16 v[136:139], v[76:79], v[212:215], v[80:83]
	v_mfma_f32_16x16x32_bf16 v[80:83], v[180:183], v[208:211], v[128:131]
	v_mfma_f32_16x16x32_bf16 v[128:131], v[184:187], v[212:215], v[80:83]
	v_mfma_f32_16x16x32_bf16 v[80:83], v[72:75], v[216:219], v[116:119]
	v_mfma_f32_16x16x32_bf16 v[116:119], v[76:79], v[220:223], v[80:83]
	v_mfma_f32_16x16x32_bf16 v[80:83], v[180:183], v[216:219], v[112:115]
	v_mfma_f32_16x16x32_bf16 v[92:95], v[76:79], v[84:87], v[92:95]
	s_setprio 2
	s_barrier
; #define PG8_STAGE(bufoff, gbase, voff) do { _Pragma("unroll") for (int _i = 0; _i < 2; ++_i) \
;         __builtin_amdgcn_global_load_lds((const unsigned*)((const char*)(gbase) + (voff)[_i]), (PG8_LAS unsigned*)(lds + (bufoff) + ldsw + _i * 8192), 16, 0, 0); } while (0)
; #define PG8_LDA(dst, b, h) do { _Pragma("unroll") for (int m = 0; m < 4; ++m) _Pragma("unroll") for (int k = 0; k < 2; ++k) dst[m][k] = *(const PG8_LAS bf16x8*)(lds + PG8_SA(b, h) + aoff + m * 2048 + k * 1024); } while (0)
; #define PG8_MMA(ai, bj, At, Bt) do { __builtin_amdgcn_s_setprio(1); _Pragma("unroll") for (int m = 0; m < 4; ++m) _Pragma("unroll") for (int n = 0; n < 2; ++n) _Pragma("unroll") for (int k = 0; k < 2; ++k) \
;         acc[ai][bj][m][n] = __builtin_amdgcn_mfma_f32_16x16x32_bf16(Bt[n][k], At[m][k], acc[ai][bj][m][n], 0, 0, 0); __builtin_amdgcn_s_setprio(0); } while (0)
; #define PG8_WAIT_V(n) asm volatile("s_waitcnt vmcnt(" #n ")" ::: "memory")
; #define PG8_WAIT_L(n) asm volatile("s_waitcnt lgkmcnt(" #n ")" ::: "memory")
; #define PG8_BAR __builtin_amdgcn_s_barrier()
; #define PG8_SCHED __builtin_amdgcn_sched_barrier(0)
; template <class Epi, class Sched, bool ALIGN_EPI = false, bool SP2 = false>
; __device__ __forceinline__ void gemm_phase(PG8_LAS unsigned char* lds, const Gemm g, const Sched& S, const Epi& E, const int wv  ) {
;     ...
;         for (int t = 0; t < nt; t += 2) {
;             const bool last = (t == nt - 2);
;     ...
;             PG8_WAIT_V(8); PG8_WAIT_L(0); PG8_BAR; PG8_MMA(0, 0, At, B0); PG8_MMA(0, 1, At, B1); PG8_BAR; PG8_SCHED;
;             PG8_LDA(At, 1, 1); PG8_STAGE(PG8_SB(1, 0), b3, voffB); PG8_STAGE(PG8_SB(1, 1), b3 + hstepB, voffB); PG8_STAGE(PG8_SA(1, 0), a3, voffA);
;             PG8_WAIT_V(8); PG8_WAIT_L(0); PG8_BAR; PG8_MMA(1, 0, At, B0); PG8_MMA(1, 1, At, B1); PG8_BAR; PG8_SCHED;
	v_mfma_f32_16x16x32_bf16 v[112:115], v[184:187], v[220:223], v[80:83]
	s_setprio 0
	s_add_i32 s70, s95, s74
	v_lshl_add_u64 v[84:85], v[228:229], 0, s[20:21]
	s_mov_b32 m0, s70
	s_nop 0
	ds_read_b128 v[80:83], v198 offset:49152
	ds_read_b128 v[200:203], v198 offset:50176
	ds_read_b128 v[204:207], v198 offset:51200
	ds_read_b128 v[208:211], v198 offset:52224
	ds_read_b128 v[212:215], v198 offset:53248
	ds_read_b128 v[216:219], v198 offset:54272
	ds_read_b128 v[220:223], v198 offset:55296
	ds_read_b128 v[224:227], v198 offset:56320
	global_load_lds_dwordx4 v[84:85], off
	s_add_i32 m0, s70, 0x2000
	s_add_u32 s68, s68, 0x100080
	v_lshl_add_u64 v[84:85], v[230:231], 0, s[20:21]
	s_addc_u32 s69, s69, 0
	s_add_i32 s70, s96, s74
	global_load_lds_dwordx4 v[84:85], off
	v_lshl_add_u64 v[84:85], s[68:69], 0, v[162:163]
	s_mov_b32 m0, s70
	s_nop 0
	global_load_lds_dwordx4 v[84:85], off
	v_lshl_add_u64 v[84:85], s[68:69], 0, v[166:167]
	s_add_i32 m0, s70, 0x2000
	s_nop 0
	global_load_lds_dwordx4 v[84:85], off
	v_lshl_add_u64 v[84:85], v[232:233], 0, s[20:21]
	s_mov_b32 m0, s82
	s_nop 0
	global_load_lds_dwordx4 v[84:85], off
	v_lshl_add_u64 v[84:85], v[234:235], 0, s[20:21]
	s_mov_b32 m0, s83
	s_nop 0
	global_load_lds_dwordx4 v[84:85], off
	s_waitcnt vmcnt(8)
	s_waitcnt lgkmcnt(0)
	s_barrier
	s_setprio 1
	s_waitcnt lgkmcnt(0)
	v_mfma_f32_16x16x32_bf16 v[84:87], v[52:55], v[80:83], v[108:111]
	v_mfma_f32_16x16x32_bf16 v[108:111], v[56:59], v[200:203], v[84:87]
	v_mfma_f32_16x16x32_bf16 v[84:87], v[60:63], v[80:83], v[96:99]
	v_mfma_f32_16x16x32_bf16 v[64:67], v[52:55], v[204:207], v[64:67]
	v_mfma_f32_16x16x32_bf16 v[36:39], v[60:63], v[204:207], v[36:39]
	v_mfma_f32_16x16x32_bf16 v[28:31], v[52:55], v[212:215], v[28:31]
	v_mfma_f32_16x16x32_bf16 v[20:23], v[60:63], v[212:215], v[20:23]
	v_mfma_f32_16x16x32_bf16 v[12:15], v[52:55], v[220:223], v[12:15]
	v_mfma_f32_16x16x32_bf16 v[4:7], v[60:63], v[220:223], v[4:7]
	v_mfma_f32_16x16x32_bf16 v[96:99], v[68:71], v[200:203], v[84:87]
	v_mfma_f32_16x16x32_bf16 v[64:67], v[56:59], v[208:211], v[64:67]
	v_mfma_f32_16x16x32_bf16 v[36:39], v[68:71], v[208:211], v[36:39]
	v_mfma_f32_16x16x32_bf16 v[28:31], v[56:59], v[216:219], v[28:31]
	v_mfma_f32_16x16x32_bf16 v[20:23], v[68:71], v[216:219], v[20:23]
	v_mfma_f32_16x16x32_bf16 v[12:15], v[56:59], v[224:227], v[12:15]
	v_mfma_f32_16x16x32_bf16 v[4:7], v[68:71], v[224:227], v[4:7]
	s_setprio 0
	s_setprio 1
	v_mfma_f32_16x16x32_bf16 v[44:47], v[72:75], v[80:83], v[44:47]
	v_mfma_f32_16x16x32_bf16 v[84:87], v[76:79], v[200:203], v[44:47]
	v_mfma_f32_16x16x32_bf16 v[44:47], v[180:183], v[80:83], v[48:51]
	v_mfma_f32_16x16x32_bf16 v[40:43], v[72:75], v[204:207], v[40:43]
	v_mfma_f32_16x16x32_bf16 v[32:35], v[180:183], v[204:207], v[32:35]
	v_mfma_f32_16x16x32_bf16 v[24:27], v[72:75], v[212:215], v[24:27]
	v_mfma_f32_16x16x32_bf16 v[16:19], v[180:183], v[212:215], v[16:19]
	v_mfma_f32_16x16x32_bf16 v[8:11], v[72:75], v[220:223], v[8:11]
	v_mfma_f32_16x16x32_bf16 v[0:3], v[180:183], v[220:223], v[0:3]
	v_mfma_f32_16x16x32_bf16 v[80:83], v[184:187], v[200:203], v[44:47]
	v_mfma_f32_16x16x32_bf16 v[40:43], v[76:79], v[208:211], v[40:43]
	v_mfma_f32_16x16x32_bf16 v[32:35], v[184:187], v[208:211], v[32:35]
	v_mfma_f32_16x16x32_bf16 v[24:27], v[76:79], v[216:219], v[24:27]
	v_mfma_f32_16x16x32_bf16 v[16:19], v[184:187], v[216:219], v[16:19]
	v_mfma_f32_16x16x32_bf16 v[8:11], v[76:79], v[224:227], v[8:11]
	s_setprio 2
	s_barrier
	v_mfma_f32_16x16x32_bf16 v[0:3], v[184:187], v[224:227], v[0:3]
	s_setprio 0
	s_add_i32 s94, s94, 2
	s_add_u32 s66, s66, 0x100
	s_addc_u32 s67, s67, 0
	s_add_u32 s92, s92, 0x100
	s_addc_u32 s93, s93, 0
	s_cmp_gt_u32 s94, 61
	s_cbranch_scc0 .LBB0_2399
	s_and_b64 vcc, exec, s[22:23]
	s_cbranch_vccz .LBB0_2402
	s_barrier

; #define PG8_STAGE(bufoff, gbase, voff) do { _Pragma("unroll") for (int _i = 0; _i < 2; ++_i) \
;         __builtin_amdgcn_global_load_lds((const unsigned*)((const char*)(gbase) + (voff)[_i]), (PG8_LAS unsigned*)(lds + (bufoff) + ldsw + _i * 8192), 16, 0, 0); } while (0)
; #define PG8_LDA(dst, b, h) do { _Pragma("unroll") for (int m = 0; m < 4; ++m) _Pragma("unroll") for (int k = 0; k < 2; ++k) dst[m][k] = *(const PG8_LAS bf16x8*)(lds + PG8_SA(b, h) + aoff + m * 2048 + k * 1024); } while (0)
; #define PG8_LDB(dst, b, h) do { _Pragma("unroll") for (int n = 0; n < 2; ++n) _Pragma("unroll") for (int k = 0; k < 2; ++k) dst[n][k] = *(const PG8_LAS bf16x8*)(lds + PG8_SB(b, h) + boff + n * 2048 + k * 1024); } while (0)
; #define PG8_MMA(ai, bj, At, Bt) do { __builtin_amdgcn_s_setprio(1); _Pragma("unroll") for (int m = 0; m < 4; ++m) _Pragma("unroll") for (int n = 0; n < 2; ++n) _Pragma("unroll") for (int k = 0; k < 2; ++k) \
;         acc[ai][bj][m][n] = __builtin_amdgcn_mfma_f32_16x16x32_bf16(Bt[n][k], At[m][k], acc[ai][bj][m][n], 0, 0, 0); __builtin_amdgcn_s_setprio(0); } while (0)
; #define PG8_WAIT_V(n) asm volatile("s_waitcnt vmcnt(" #n ")" ::: "memory")
; #define PG8_WAIT_L(n) asm volatile("s_waitcnt lgkmcnt(" #n ")" ::: "memory")
; template <class Epi, class Sched, bool ALIGN_EPI = false, bool SP2 = false>
; __device__ __forceinline__ void gemm_phase(PG8_LAS unsigned char* lds, const Gemm g, const Sched& S, const Epi& E, const int wv  ) {
;     ...
;             const bool last = (t == nt - 2);
;             const char* a1 = cA + (size_t)(t + 1) * kstep;
;             const char* a2 = last ? nA : cA + (size_t)(t + 2) * kstep; const char* b2 = last ? nB : cB + (size_t)(t + 2) * kstep;
;             const char* a3 = a2 + kstep; const char* b3 = b2 + kstep;
;             if (last && has_next) S.a_ready(nxt);
;             if constexpr (SP2) {
;             PG8_LDB(B0, 0, 0); PG8_LDB(B1, 0, 1); PG8_SCHED; PG8_LDA(At, 0, 0); PG8_STAGE(PG8_SA(1, 1), a1 + hstepA, voffA);
;             PG8_WAIT_V(8); PG8_WAIT_L(0); PG8_BAR; PG8_MMA(0, 0, At, B0); PG8_MMA(0, 1, At, B1); PG8_BAR; PG8_SCHED;
;             PG8_LDA(At, 0, 1); PG8_STAGE(PG8_SB(0, 0), b2, voffB); PG8_STAGE(PG8_SB(0, 1), b2 + hstepB, voffB); PG8_STAGE(PG8_SA(0, 0), a2, voffA);
;             PG8_WAIT_V(8); PG8_WAIT_L(0); PG8_BAR; PG8_MMA(1, 0, At, B0); PG8_MMA(1, 1, At, B1); PG8_BAR; PG8_SCHED;
.LBB0_2756:
	ds_read_b128 v[146:149], v152
	ds_read_b128 v[156:159], v152 offset:1024
	ds_read_b128 v[160:163], v152 offset:2048
	ds_read_b128 v[164:167], v152 offset:3072
	ds_read_b128 v[168:171], v153
	ds_read_b128 v[172:175], v153 offset:1024
	ds_read_b128 v[176:179], v153 offset:2048
	ds_read_b128 v[180:183], v153 offset:3072
	s_add_u32 s54, s52, 0x100
	s_addc_u32 s55, s53, 0
	s_cmpk_eq_i32 s84, 0xa8
	s_cselect_b32 s59, s7, s55
	s_cselect_b32 s58, s6, s54
	s_cselect_b32 s57, s51, s83
	s_cselect_b32 s56, s50, s82
	v_lshl_add_u64 v[216:217], s[52:53], 0, v[138:139]
	s_add_i32 m0, s63, 0xc000
	ds_read_b128 v[184:187], v154
	ds_read_b128 v[188:191], v154 offset:1024
	ds_read_b128 v[192:195], v154 offset:2048
	ds_read_b128 v[196:199], v154 offset:3072
	ds_read_b128 v[200:203], v154 offset:4096
	ds_read_b128 v[204:207], v154 offset:5120
	ds_read_b128 v[208:211], v154 offset:6144
	ds_read_b128 v[212:215], v154 offset:7168
	global_load_lds_dwordx4 v[216:217], off
	v_lshl_add_u64 v[216:217], s[52:53], 0, v[140:141]
	s_add_i32 m0, s63, 0xe000
	s_nop 0
	global_load_lds_dwordx4 v[216:217], off
	s_waitcnt vmcnt(8)
	s_waitcnt lgkmcnt(0)
	s_barrier
	s_setprio 1
	s_waitcnt lgkmcnt(0)
	v_mfma_f32_16x16x32_bf16 v[76:79], v[146:149], v[184:187], v[76:79]
	v_mfma_f32_16x16x32_bf16 v[72:75], v[160:163], v[184:187], v[72:75]
	v_mfma_f32_16x16x32_bf16 v[68:71], v[146:149], v[192:195], v[68:71]
	v_mfma_f32_16x16x32_bf16 v[64:67], v[160:163], v[192:195], v[64:67]
	v_mfma_f32_16x16x32_bf16 v[56:59], v[146:149], v[200:203], v[56:59]
	v_mfma_f32_16x16x32_bf16 v[52:55], v[160:163], v[200:203], v[52:55]
	v_mfma_f32_16x16x32_bf16 v[44:47], v[146:149], v[208:211], v[44:47]
	v_mfma_f32_16x16x32_bf16 v[40:43], v[160:163], v[208:211], v[40:43]
	v_mfma_f32_16x16x32_bf16 v[76:79], v[156:159], v[188:191], v[76:79]
	v_mfma_f32_16x16x32_bf16 v[72:75], v[164:167], v[188:191], v[72:75]
	v_mfma_f32_16x16x32_bf16 v[68:71], v[156:159], v[196:199], v[68:71]
	v_mfma_f32_16x16x32_bf16 v[64:67], v[164:167], v[196:199], v[64:67]
	v_mfma_f32_16x16x32_bf16 v[56:59], v[156:159], v[204:207], v[56:59]
	v_mfma_f32_16x16x32_bf16 v[52:55], v[164:167], v[204:207], v[52:55]
	v_mfma_f32_16x16x32_bf16 v[44:47], v[156:159], v[212:215], v[44:47]
	v_mfma_f32_16x16x32_bf16 v[40:43], v[164:167], v[212:215], v[40:43]
	s_setprio 0
	s_setprio 1
	v_mfma_f32_16x16x32_bf16 v[124:127], v[168:171], v[184:187], v[124:127]
	v_mfma_f32_16x16x32_bf16 v[120:123], v[176:179], v[184:187], v[120:123]
	v_mfma_f32_16x16x32_bf16 v[116:119], v[168:171], v[192:195], v[116:119]
	v_mfma_f32_16x16x32_bf16 v[112:115], v[176:179], v[192:195], v[112:115]
	v_mfma_f32_16x16x32_bf16 v[108:111], v[168:171], v[200:203], v[108:111]
	v_mfma_f32_16x16x32_bf16 v[104:107], v[176:179], v[200:203], v[104:107]
	v_mfma_f32_16x16x32_bf16 v[100:103], v[168:171], v[208:211], v[100:103]
	v_mfma_f32_16x16x32_bf16 v[96:99], v[176:179], v[208:211], v[96:99]
	v_mfma_f32_16x16x32_bf16 v[124:127], v[172:175], v[188:191], v[124:127]
	v_mfma_f32_16x16x32_bf16 v[120:123], v[180:183], v[188:191], v[120:123]
	v_mfma_f32_16x16x32_bf16 v[116:119], v[172:175], v[196:199], v[116:119]
	v_mfma_f32_16x16x32_bf16 v[112:115], v[180:183], v[196:199], v[112:115]
	v_mfma_f32_16x16x32_bf16 v[108:111], v[172:175], v[204:207], v[108:111]
	v_mfma_f32_16x16x32_bf16 v[104:107], v[180:183], v[204:207], v[104:107]
	v_mfma_f32_16x16x32_bf16 v[100:103], v[172:175], v[212:215], v[100:103]
	s_setprio 2
	s_barrier
	v_mfma_f32_16x16x32_bf16 v[96:99], v[180:183], v[212:215], v[96:99]
	s_setprio 0
	s_add_i32 s52, s72, s62
	v_lshl_add_u64 v[216:217], s[56:57], 0, v[130:131]
	s_mov_b32 m0, s52
	ds_read_b128 v[184:187], v154 offset:16384
	ds_read_b128 v[188:191], v154 offset:17408
	ds_read_b128 v[192:195], v154 offset:18432
	ds_read_b128 v[196:199], v154 offset:19456
	ds_read_b128 v[200:203], v154 offset:20480
	ds_read_b128 v[204:207], v154 offset:21504
	ds_read_b128 v[208:211], v154 offset:22528
	ds_read_b128 v[212:215], v154 offset:23552
	global_load_lds_dwordx4 v[216:217], off
	s_add_i32 m0, s52, 0x2000
	s_add_u32 s52, s56, 0x2b0000
	v_lshl_add_u64 v[218:219], s[56:57], 0, v[134:135]
	s_addc_u32 s53, s57, 0
	s_add_i32 s85, s73, s62
	global_load_lds_dwordx4 v[218:219], off
	v_lshl_add_u64 v[220:221], s[52:53], 0, v[130:131]
	s_mov_b32 m0, s85
	v_lshl_add_u64 v[222:223], s[58:59], 0, v[132:133]
	global_load_lds_dwordx4 v[220:221], off
	v_lshl_add_u64 v[220:221], s[52:53], 0, v[134:135]
	s_add_i32 m0, s85, 0x2000
	s_nop 0
	global_load_lds_dwordx4 v[220:221], off
	v_lshl_add_u64 v[220:221], s[58:59], 0, v[128:129]
	s_mov_b32 m0, s63
	s_nop 0
	global_load_lds_dwordx4 v[220:221], off
	s_mov_b32 m0, s64
	s_nop 0
	global_load_lds_dwordx4 v[222:223], off
	s_waitcnt vmcnt(8)
	s_waitcnt lgkmcnt(0)
	s_barrier
; #define PG8_STAGE(bufoff, gbase, voff) do { _Pragma("unroll") for (int _i = 0; _i < 2; ++_i) \
;         __builtin_amdgcn_global_load_lds((const unsigned*)((const char*)(gbase) + (voff)[_i]), (PG8_LAS unsigned*)(lds + (bufoff) + ldsw + _i * 8192), 16, 0, 0); } while (0)
; #define PG8_LDA(dst, b, h) do { _Pragma("unroll") for (int m = 0; m < 4; ++m) _Pragma("unroll") for (int k = 0; k < 2; ++k) dst[m][k] = *(const PG8_LAS bf16x8*)(lds + PG8_SA(b, h) + aoff + m * 2048 + k * 1024); } while (0)
; #define PG8_LDB(dst, b, h) do { _Pragma("unroll") for (int n = 0; n < 2; ++n) _Pragma("unroll") for (int k = 0; k < 2; ++k) dst[n][k] = *(const PG8_LAS bf16x8*)(lds + PG8_SB(b, h) + boff + n * 2048 + k * 1024); } while (0)
; #define PG8_MMA(ai, bj, At, Bt) do { __builtin_amdgcn_s_setprio(1); _Pragma("unroll") for (int m = 0; m < 4; ++m) _Pragma("unroll") for (int n = 0; n < 2; ++n) _Pragma("unroll") for (int k = 0; k < 2; ++k) \
;         acc[ai][bj][m][n] = __builtin_amdgcn_mfma_f32_16x16x32_bf16(Bt[n][k], At[m][k], acc[ai][bj][m][n], 0, 0, 0); __builtin_amdgcn_s_setprio(0); } while (0)
; #define PG8_WAIT_V(n) asm volatile("s_waitcnt vmcnt(" #n ")" ::: "memory")
; #define PG8_WAIT_L(n) asm volatile("s_waitcnt lgkmcnt(" #n ")" ::: "memory")
; #define PG8_BAR __builtin_amdgcn_s_barrier()
; #define PG8_SCHED __builtin_amdgcn_sched_barrier(0)
; template <class Epi, class Sched, bool ALIGN_EPI = false, bool SP2 = false>
; __device__ __forceinline__ void gemm_phase(PG8_LAS unsigned char* lds, const Gemm g, const Sched& S, const Epi& E, const int wv  ) {
;     ...
;             PG8_WAIT_V(8); PG8_WAIT_L(0); PG8_BAR; PG8_MMA(1, 0, At, B0); PG8_MMA(1, 1, At, B1); PG8_BAR; PG8_SCHED;
;             PG8_LDB(B0, 1, 0); PG8_LDB(B1, 1, 1); PG8_SCHED; PG8_LDA(At, 1, 0); PG8_STAGE(PG8_SA(0, 1), a2 + hstepA, voffA);
;             PG8_WAIT_V(8); PG8_WAIT_L(0); PG8_BAR; PG8_MMA(0, 0, At, B0); PG8_MMA(0, 1, At, B1); PG8_BAR; PG8_SCHED;
	s_setprio 1
	s_waitcnt lgkmcnt(0)
	v_mfma_f32_16x16x32_bf16 v[28:31], v[146:149], v[184:187], v[28:31]
	v_mfma_f32_16x16x32_bf16 v[24:27], v[160:163], v[184:187], v[24:27]
	v_mfma_f32_16x16x32_bf16 v[20:23], v[146:149], v[192:195], v[20:23]
	v_mfma_f32_16x16x32_bf16 v[16:19], v[160:163], v[192:195], v[16:19]
	v_mfma_f32_16x16x32_bf16 v[12:15], v[146:149], v[200:203], v[12:15]
	v_mfma_f32_16x16x32_bf16 v[8:11], v[160:163], v[200:203], v[8:11]
	v_mfma_f32_16x16x32_bf16 v[4:7], v[146:149], v[208:211], v[4:7]
	v_mfma_f32_16x16x32_bf16 v[0:3], v[160:163], v[208:211], v[0:3]
	v_mfma_f32_16x16x32_bf16 v[28:31], v[156:159], v[188:191], v[28:31]
	v_mfma_f32_16x16x32_bf16 v[24:27], v[164:167], v[188:191], v[24:27]
	v_mfma_f32_16x16x32_bf16 v[20:23], v[156:159], v[196:199], v[20:23]
	v_mfma_f32_16x16x32_bf16 v[16:19], v[164:167], v[196:199], v[16:19]
	v_mfma_f32_16x16x32_bf16 v[12:15], v[156:159], v[204:207], v[12:15]
	v_mfma_f32_16x16x32_bf16 v[8:11], v[164:167], v[204:207], v[8:11]
	v_mfma_f32_16x16x32_bf16 v[4:7], v[156:159], v[212:215], v[4:7]
	v_mfma_f32_16x16x32_bf16 v[0:3], v[164:167], v[212:215], v[0:3]
	s_setprio 0
	s_setprio 1
	v_mfma_f32_16x16x32_bf16 v[92:95], v[168:171], v[184:187], v[92:95]
	v_mfma_f32_16x16x32_bf16 v[88:91], v[176:179], v[184:187], v[88:91]
	v_mfma_f32_16x16x32_bf16 v[84:87], v[168:171], v[192:195], v[84:87]
	v_mfma_f32_16x16x32_bf16 v[80:83], v[176:179], v[192:195], v[80:83]
	v_mfma_f32_16x16x32_bf16 v[60:63], v[168:171], v[200:203], v[60:63]
	v_mfma_f32_16x16x32_bf16 v[48:51], v[176:179], v[200:203], v[48:51]
	v_mfma_f32_16x16x32_bf16 v[36:39], v[168:171], v[208:211], v[36:39]
	v_mfma_f32_16x16x32_bf16 v[32:35], v[176:179], v[208:211], v[32:35]
	v_mfma_f32_16x16x32_bf16 v[92:95], v[172:175], v[188:191], v[92:95]
	v_mfma_f32_16x16x32_bf16 v[88:91], v[180:183], v[188:191], v[88:91]
	v_mfma_f32_16x16x32_bf16 v[84:87], v[172:175], v[196:199], v[84:87]
	v_mfma_f32_16x16x32_bf16 v[80:83], v[180:183], v[196:199], v[80:83]
	v_mfma_f32_16x16x32_bf16 v[60:63], v[172:175], v[204:207], v[60:63]
	v_mfma_f32_16x16x32_bf16 v[48:51], v[180:183], v[204:207], v[48:51]
	v_mfma_f32_16x16x32_bf16 v[36:39], v[172:175], v[212:215], v[36:39]
	s_setprio 2
	s_barrier
	v_mfma_f32_16x16x32_bf16 v[32:35], v[180:183], v[212:215], v[32:35]
	s_setprio 0
	s_add_i32 s85, 0, 0x18000
	v_add_u32_e32 v155, s85, v150
	s_add_i32 s86, 0, 0x1c000
	ds_read_b128 v[146:149], v155
	ds_read_b128 v[156:159], v155 offset:1024
	ds_read_b128 v[160:163], v155 offset:2048
	ds_read_b128 v[164:167], v155 offset:3072
	v_add_u32_e32 v155, s86, v150
	ds_read_b128 v[168:171], v155
	ds_read_b128 v[172:175], v155 offset:1024
	ds_read_b128 v[176:179], v155 offset:2048
	ds_read_b128 v[180:183], v155 offset:3072
	s_add_u32 s52, s58, 0x2b0000
	s_addc_u32 s53, s59, 0
	s_mov_b32 m0, s65
	v_lshl_add_u64 v[224:225], s[52:53], 0, v[128:129]
	ds_read_b128 v[184:187], v154 offset:32768
	ds_read_b128 v[188:191], v154 offset:33792
	ds_read_b128 v[192:195], v154 offset:34816
	ds_read_b128 v[196:199], v154 offset:35840
	ds_read_b128 v[200:203], v154 offset:36864
	ds_read_b128 v[204:207], v154 offset:37888
	ds_read_b128 v[208:211], v154 offset:38912
	ds_read_b128 v[212:215], v154 offset:39936
	global_load_lds_dwordx4 v[224:225], off
	v_lshl_add_u64 v[224:225], s[52:53], 0, v[132:133]
	s_mov_b32 m0, s66
	s_nop 0
	global_load_lds_dwordx4 v[224:225], off
	s_waitcnt vmcnt(8)
	s_waitcnt lgkmcnt(0)
	s_barrier
	s_setprio 1
	s_waitcnt lgkmcnt(0)
	v_mfma_f32_16x16x32_bf16 v[76:79], v[146:149], v[184:187], v[76:79]
	v_mfma_f32_16x16x32_bf16 v[72:75], v[160:163], v[184:187], v[72:75]
	v_mfma_f32_16x16x32_bf16 v[68:71], v[146:149], v[192:195], v[68:71]
	v_mfma_f32_16x16x32_bf16 v[64:67], v[160:163], v[192:195], v[64:67]
	v_mfma_f32_16x16x32_bf16 v[56:59], v[146:149], v[200:203], v[56:59]
	v_mfma_f32_16x16x32_bf16 v[52:55], v[160:163], v[200:203], v[52:55]
	v_mfma_f32_16x16x32_bf16 v[44:47], v[146:149], v[208:211], v[44:47]
	v_mfma_f32_16x16x32_bf16 v[40:43], v[160:163], v[208:211], v[40:43]
	v_mfma_f32_16x16x32_bf16 v[76:79], v[156:159], v[188:191], v[76:79]
	v_mfma_f32_16x16x32_bf16 v[72:75], v[164:167], v[188:191], v[72:75]
	v_mfma_f32_16x16x32_bf16 v[68:71], v[156:159], v[196:199], v[68:71]
	v_mfma_f32_16x16x32_bf16 v[64:67], v[164:167], v[196:199], v[64:67]
	v_mfma_f32_16x16x32_bf16 v[56:59], v[156:159], v[204:207], v[56:59]
	v_mfma_f32_16x16x32_bf16 v[52:55], v[164:167], v[204:207], v[52:55]
	v_mfma_f32_16x16x32_bf16 v[44:47], v[156:159], v[212:215], v[44:47]
	v_mfma_f32_16x16x32_bf16 v[40:43], v[164:167], v[212:215], v[40:43]
	s_setprio 0
	s_setprio 1
	v_mfma_f32_16x16x32_bf16 v[124:127], v[168:171], v[184:187], v[124:127]
	v_mfma_f32_16x16x32_bf16 v[120:123], v[176:179], v[184:187], v[120:123]
	v_mfma_f32_16x16x32_bf16 v[116:119], v[168:171], v[192:195], v[116:119]
	v_mfma_f32_16x16x32_bf16 v[112:115], v[176:179], v[192:195], v[112:115]
	v_mfma_f32_16x16x32_bf16 v[108:111], v[168:171], v[200:203], v[108:111]
	v_mfma_f32_16x16x32_bf16 v[104:107], v[176:179], v[200:203], v[104:107]
	v_mfma_f32_16x16x32_bf16 v[100:103], v[168:171], v[208:211], v[100:103]
	v_mfma_f32_16x16x32_bf16 v[96:99], v[176:179], v[208:211], v[96:99]
	v_mfma_f32_16x16x32_bf16 v[124:127], v[172:175], v[188:191], v[124:127]
	v_mfma_f32_16x16x32_bf16 v[120:123], v[180:183], v[188:191], v[120:123]
	v_mfma_f32_16x16x32_bf16 v[116:119], v[172:175], v[196:199], v[116:119]
	v_mfma_f32_16x16x32_bf16 v[112:115], v[180:183], v[196:199], v[112:115]
	v_mfma_f32_16x16x32_bf16 v[108:111], v[172:175], v[204:207], v[108:111]
	v_mfma_f32_16x16x32_bf16 v[104:107], v[180:183], v[204:207], v[104:107]
	v_mfma_f32_16x16x32_bf16 v[100:103], v[172:175], v[212:215], v[100:103]
	s_setprio 2
	s_barrier
; #define PG8_STAGE(bufoff, gbase, voff) do { _Pragma("unroll") for (int _i = 0; _i < 2; ++_i) \
;         __builtin_amdgcn_global_load_lds((const unsigned*)((const char*)(gbase) + (voff)[_i]), (PG8_LAS unsigned*)(lds + (bufoff) + ldsw + _i * 8192), 16, 0, 0); } while (0)
; #define PG8_LDA(dst, b, h) do { _Pragma("unroll") for (int m = 0; m < 4; ++m) _Pragma("unroll") for (int k = 0; k < 2; ++k) dst[m][k] = *(const PG8_LAS bf16x8*)(lds + PG8_SA(b, h) + aoff + m * 2048 + k * 1024); } while (0)
; #define PG8_MMA(ai, bj, At, Bt) do { __builtin_amdgcn_s_setprio(1); _Pragma("unroll") for (int m = 0; m < 4; ++m) _Pragma("unroll") for (int n = 0; n < 2; ++n) _Pragma("unroll") for (int k = 0; k < 2; ++k) \
;         acc[ai][bj][m][n] = __builtin_amdgcn_mfma_f32_16x16x32_bf16(Bt[n][k], At[m][k], acc[ai][bj][m][n], 0, 0, 0); __builtin_amdgcn_s_setprio(0); } while (0)
; #define PG8_WAIT_V(n) asm volatile("s_waitcnt vmcnt(" #n ")" ::: "memory")
; #define PG8_WAIT_L(n) asm volatile("s_waitcnt lgkmcnt(" #n ")" ::: "memory")
; #define PG8_BAR __builtin_amdgcn_s_barrier()
; #define PG8_SCHED __builtin_amdgcn_sched_barrier(0)
; template <class Epi, class Sched, bool ALIGN_EPI = false, bool SP2 = false>
; __device__ __forceinline__ void gemm_phase(PG8_LAS unsigned char* lds, const Gemm g, const Sched& S, const Epi& E, const int wv  ) {
;     ...
;         for (int t = 0; t < nt; t += 2) {
;             const bool last = (t == nt - 2);
;     ...
;             PG8_WAIT_V(8); PG8_WAIT_L(0); PG8_BAR; PG8_MMA(0, 0, At, B0); PG8_MMA(0, 1, At, B1); PG8_BAR; PG8_SCHED;
;             PG8_LDA(At, 1, 1); PG8_STAGE(PG8_SB(1, 0), b3, voffB); PG8_STAGE(PG8_SB(1, 1), b3 + hstepB, voffB); PG8_STAGE(PG8_SA(1, 0), a3, voffA);
;             PG8_WAIT_V(8); PG8_WAIT_L(0); PG8_BAR; PG8_MMA(1, 0, At, B0); PG8_MMA(1, 1, At, B1); PG8_BAR; PG8_SCHED;
	v_mfma_f32_16x16x32_bf16 v[96:99], v[180:183], v[212:215], v[96:99]
	s_setprio 0
	s_add_i32 s52, s85, s62
	v_lshl_add_u64 v[216:217], v[216:217], 0, s[12:13]
	s_mov_b32 m0, s52
	ds_read_b128 v[184:187], v154 offset:49152
	ds_read_b128 v[188:191], v154 offset:50176
	ds_read_b128 v[192:195], v154 offset:51200
	ds_read_b128 v[196:199], v154 offset:52224
	ds_read_b128 v[200:203], v154 offset:53248
	ds_read_b128 v[204:207], v154 offset:54272
	ds_read_b128 v[208:211], v154 offset:55296
	ds_read_b128 v[212:215], v154 offset:56320
	global_load_lds_dwordx4 v[216:217], off
	s_add_i32 m0, s52, 0x2000
	s_add_u32 s52, s56, 0x2b0080
	v_lshl_add_u64 v[216:217], v[218:219], 0, s[12:13]
	s_addc_u32 s53, s57, 0
	s_add_i32 s56, s86, s62
	global_load_lds_dwordx4 v[216:217], off
	v_lshl_add_u64 v[216:217], s[52:53], 0, v[130:131]
	s_mov_b32 m0, s56
	s_nop 0
	global_load_lds_dwordx4 v[216:217], off
	v_lshl_add_u64 v[216:217], s[52:53], 0, v[134:135]
	s_add_i32 m0, s56, 0x2000
	s_nop 0
	global_load_lds_dwordx4 v[216:217], off
	v_lshl_add_u64 v[216:217], v[220:221], 0, s[12:13]
	s_mov_b32 m0, s69
	s_nop 0
	global_load_lds_dwordx4 v[216:217], off
	v_lshl_add_u64 v[216:217], v[222:223], 0, s[12:13]
	s_mov_b32 m0, s70
	s_nop 0
	global_load_lds_dwordx4 v[216:217], off
	s_waitcnt vmcnt(8)
	s_waitcnt lgkmcnt(0)
	s_barrier
	s_setprio 1
	s_waitcnt lgkmcnt(0)
	v_mfma_f32_16x16x32_bf16 v[28:31], v[146:149], v[184:187], v[28:31]
	v_mfma_f32_16x16x32_bf16 v[24:27], v[160:163], v[184:187], v[24:27]
	v_mfma_f32_16x16x32_bf16 v[20:23], v[146:149], v[192:195], v[20:23]
	v_mfma_f32_16x16x32_bf16 v[16:19], v[160:163], v[192:195], v[16:19]
	v_mfma_f32_16x16x32_bf16 v[12:15], v[146:149], v[200:203], v[12:15]
	v_mfma_f32_16x16x32_bf16 v[8:11], v[160:163], v[200:203], v[8:11]
	v_mfma_f32_16x16x32_bf16 v[4:7], v[146:149], v[208:211], v[4:7]
	v_mfma_f32_16x16x32_bf16 v[0:3], v[160:163], v[208:211], v[0:3]
	v_mfma_f32_16x16x32_bf16 v[28:31], v[156:159], v[188:191], v[28:31]
	v_mfma_f32_16x16x32_bf16 v[24:27], v[164:167], v[188:191], v[24:27]
	v_mfma_f32_16x16x32_bf16 v[20:23], v[156:159], v[196:199], v[20:23]
	v_mfma_f32_16x16x32_bf16 v[16:19], v[164:167], v[196:199], v[16:19]
	v_mfma_f32_16x16x32_bf16 v[12:15], v[156:159], v[204:207], v[12:15]
	v_mfma_f32_16x16x32_bf16 v[8:11], v[164:167], v[204:207], v[8:11]
	v_mfma_f32_16x16x32_bf16 v[4:7], v[156:159], v[212:215], v[4:7]
	v_mfma_f32_16x16x32_bf16 v[0:3], v[164:167], v[212:215], v[0:3]
	s_setprio 0
	s_setprio 1
	v_mfma_f32_16x16x32_bf16 v[92:95], v[168:171], v[184:187], v[92:95]
	v_mfma_f32_16x16x32_bf16 v[88:91], v[176:179], v[184:187], v[88:91]
	v_mfma_f32_16x16x32_bf16 v[84:87], v[168:171], v[192:195], v[84:87]
	v_mfma_f32_16x16x32_bf16 v[80:83], v[176:179], v[192:195], v[80:83]
	v_mfma_f32_16x16x32_bf16 v[60:63], v[168:171], v[200:203], v[60:63]
	v_mfma_f32_16x16x32_bf16 v[48:51], v[176:179], v[200:203], v[48:51]
	v_mfma_f32_16x16x32_bf16 v[36:39], v[168:171], v[208:211], v[36:39]
	v_mfma_f32_16x16x32_bf16 v[32:35], v[176:179], v[208:211], v[32:35]
	v_mfma_f32_16x16x32_bf16 v[92:95], v[172:175], v[188:191], v[92:95]
	v_mfma_f32_16x16x32_bf16 v[88:91], v[180:183], v[188:191], v[88:91]
	v_mfma_f32_16x16x32_bf16 v[84:87], v[172:175], v[196:199], v[84:87]
	v_mfma_f32_16x16x32_bf16 v[80:83], v[180:183], v[196:199], v[80:83]
	v_mfma_f32_16x16x32_bf16 v[60:63], v[172:175], v[204:207], v[60:63]
	v_mfma_f32_16x16x32_bf16 v[48:51], v[180:183], v[204:207], v[48:51]
	v_mfma_f32_16x16x32_bf16 v[36:39], v[172:175], v[212:215], v[36:39]
	s_setprio 2
	s_barrier
	v_mfma_f32_16x16x32_bf16 v[32:35], v[180:183], v[212:215], v[32:35]
	s_setprio 0
	s_add_i32 s84, s84, 2
	s_add_u32 s82, s82, 0x100
	s_addc_u32 s83, s83, 0
	s_cmpk_gt_u32 s84, 0xa9
	s_mov_b64 s[52:53], s[54:55]
	s_cbranch_scc0 .LBB0_2756
	s_and_b64 vcc, exec, s[14:15]
	s_cbranch_vccz .LBB0_2759
	s_barrier
